# v69 + write-through (sc1) on all remaining plain wide output stores (scan-independent GEMMs, sample tail, phase 5a/5b)
# baseline (speedup 1.0000x reference)
.LBB0_592:
	v_readlane_b32 s96, v255, 33
	s_cmpk_gt_u32 s96, 0xff
	s_cbranch_scc1 .LBB0_594
	v_readlane_b32 s4, v255, 0
	v_readlane_b32 s5, v255, 1
	v_readlane_b32 s6, v255, 2
	v_readlane_b32 s7, v255, 3
	v_readlane_b32 s8, v255, 4
	v_readlane_b32 s9, v255, 5
	s_mov_b32 s3, 0x82b1000
	s_and_b64 s[0:1], s[36:37], exec
	v_readlane_b32 s10, v255, 6
	v_readlane_b32 s11, v255, 7
	s_mov_b64 s[4:5], s[8:9]
	s_cselect_b32 s0, s3, 0x8080000
	s_mov_b64 s[6:7], s[10:11]
	s_add_u32 s0, s6, s0
	s_addc_u32 s1, s7, 0
	s_waitcnt lgkmcnt(0)
	v_lshl_add_u64 v[8:9], s[0:1], 0, v[46:47]
	v_lshlrev_b32_e32 v10, 2, v90
	v_mov_b32_e32 v11, 0
	v_lshl_add_u64 v[8:9], v[8:9], 0, v[10:11]
	global_store_dwordx4 v[8:9], v[0:3], off sc1
	global_store_dwordx4 v[8:9], v[4:7], off offset:64 sc1
	global_store_dwordx4 v[8:9], v[12:15], off offset:128 sc1
	global_store_dwordx4 v[8:9], v[16:19], off offset:192 sc1

.LBB0_653:
	s_or_b64 exec, exec, s[0:1]
	global_load_dword v4, v[6:7], off offset:28
	global_load_dword v10, v[8:9], off offset:28
	v_lshlrev_b32_e32 v11, 10, v18
	v_lshlrev_b64 v[2:3], 19, v[2:3]
	v_fma_mixlo_f16 v6, v17, v19, v0
	v_lshl_add_u64 v[2:3], s[8:9], 0, v[2:3]
	v_lshlrev_b32_e32 v0, 1, v11
	v_fma_mixlo_f16 v7, v23, v27, v26
	v_fma_mixlo_f16 v8, v31, v33, v32
	s_waitcnt vmcnt(3)
	v_fma_mixlo_f16 v9, v37, v39, v38
	v_lshl_add_u64 v[2:3], v[2:3], 0, v[0:1]
	v_lshlrev_b32_e32 v0, 1, v16
	v_fma_mixhi_f16 v8, v34, v36, v35
	v_fma_mixhi_f16 v7, v28, v30, v29
	v_fma_mixhi_f16 v6, v20, v22, v21
	v_lshl_add_u64 v[2:3], v[2:3], 0, v[0:1]
	s_waitcnt vmcnt(0)
	v_fma_mixhi_f16 v9, v5, v10, v4
	global_store_dwordx4 v[2:3], v[6:9], off sc1

.LBB0_690:
	s_or_b64 exec, exec, s[16:17]
	v_readlane_b32 s80, v255, 14
	v_readlane_b32 s86, v255, 20
	v_readlane_b32 s87, v255, 21
	v_mov_b32_e32 v31, v27
	s_mov_b64 s[42:43], s[86:87]
	v_lshl_add_u64 v[62:63], s[42:43], 0, v[30:31]
	v_add_co_u32_e32 v58, vcc, s20, v62
	v_lshl_add_u64 v[46:47], v[62:63], 0, s[12:13]
	s_nop 0
	v_addc_co_u32_e32 v59, vcc, 0, v63, vcc
	global_load_dwordx4 v[42:45], v[58:59], off offset:-4096
	s_nop 0
	global_load_dwordx4 v[46:49], v[46:47], off offset:16
	s_nop 0
	global_load_dwordx4 v[50:53], v30, s[86:87]
	global_load_dwordx4 v[54:57], v30, s[86:87] offset:16
	s_nop 0
	global_load_dwordx4 v[58:61], v[58:59], off
	v_lshl_add_u64 v[30:31], v[62:63], 0, s[14:15]
	global_load_dwordx4 v[62:65], v[30:31], off offset:16
	s_waitcnt vmcnt(7)
	v_cvt_f32_f16_sdwa v31, v0 dst_sel:DWORD dst_unused:UNUSED_PAD src0_sel:WORD_1
	v_cvt_f32_f16_e32 v30, v0
	s_waitcnt vmcnt(6)
	v_cvt_f32_f16_sdwa v67, v4 dst_sel:DWORD dst_unused:UNUSED_PAD src0_sel:WORD_1
	v_cvt_f32_f16_e32 v66, v4
	v_cvt_f32_f16_sdwa v69, v1 dst_sel:DWORD dst_unused:UNUSED_PAD src0_sel:WORD_1
	v_cvt_f32_f16_e32 v68, v1
	v_cvt_f32_f16_sdwa v1, v5 dst_sel:DWORD dst_unused:UNUSED_PAD src0_sel:WORD_1
	v_cvt_f32_f16_e32 v0, v5
	v_cvt_f32_f16_sdwa v5, v2 dst_sel:DWORD dst_unused:UNUSED_PAD src0_sel:WORD_1
	v_cvt_f32_f16_e32 v4, v2
	v_cvt_f32_f16_sdwa v73, v3 dst_sel:DWORD dst_unused:UNUSED_PAD src0_sel:WORD_1
	v_cvt_f32_f16_e32 v72, v3
	v_cvt_f32_f16_sdwa v71, v6 dst_sel:DWORD dst_unused:UNUSED_PAD src0_sel:WORD_1
	v_cvt_f32_f16_e32 v70, v6
	v_cvt_f32_f16_sdwa v3, v7 dst_sel:DWORD dst_unused:UNUSED_PAD src0_sel:WORD_1
	v_cvt_f32_f16_e32 v2, v7
	v_lshlrev_b64 v[6:7], 11, v[28:29]
	v_add_u32_e32 v40, s6, v40
	v_lshl_add_u64 v[6:7], s[8:9], 0, v[6:7]
	v_cmp_lt_i32_e32 vcc, s21, v40
	v_lshl_add_u64 v[6:7], v[6:7], 0, v[26:27]
	s_or_b64 s[10:11], vcc, s[10:11]
	v_add_u32_e32 v25, s19, v25
	v_readlane_b32 s81, v255, 15
	v_readlane_b32 s82, v255, 16
	v_readlane_b32 s83, v255, 17
	v_readlane_b32 s84, v255, 18
	v_readlane_b32 s85, v255, 19
	v_readlane_b32 s88, v255, 22
	v_readlane_b32 s89, v255, 23
	v_readlane_b32 s90, v255, 24
	v_readlane_b32 s91, v255, 25
	v_readlane_b32 s92, v255, 26
	v_readlane_b32 s93, v255, 27
	v_readlane_b32 s94, v255, 28
	v_readlane_b32 s95, v255, 29
	s_waitcnt vmcnt(4)
	v_pk_mul_f32 v[12:13], v[12:13], v[46:47]
	v_pk_mul_f32 v[14:15], v[14:15], v[48:49]
	v_pk_mul_f32 v[8:9], v[8:9], v[42:43]
	v_pk_mul_f32 v[10:11], v[10:11], v[44:45]
	s_waitcnt vmcnt(3)
	v_pk_fma_f32 v[8:9], v[16:17], v[50:51], v[8:9]
	v_pk_fma_f32 v[10:11], v[18:19], v[52:53], v[10:11]
	s_waitcnt vmcnt(2)
	v_pk_fma_f32 v[12:13], v[20:21], v[54:55], v[12:13]
	v_pk_fma_f32 v[14:15], v[22:23], v[56:57], v[14:15]
	s_waitcnt vmcnt(1)
	v_pk_fma_f32 v[8:9], v[58:59], v[30:31], v[8:9]
	v_pk_fma_f32 v[10:11], v[60:61], v[68:69], v[10:11]
	s_waitcnt vmcnt(0)
	v_pk_fma_f32 v[4:5], v[62:63], v[4:5], v[12:13]
	v_pk_fma_f32 v[12:13], v[64:65], v[72:73], v[14:15]
	v_pk_mul_f32 v[8:9], v[8:9], v[66:67]
	v_pk_mul_f32 v[10:11], v[10:11], v[0:1]
	v_pk_mul_f32 v[4:5], v[4:5], v[70:71]
	v_pk_mul_f32 v[12:13], v[12:13], v[2:3]
	v_cvt_pk_f16_f32 v0, v8, v9
	v_cvt_pk_f16_f32 v1, v10, v11
	v_cvt_pk_f16_f32 v2, v4, v5
	v_cvt_pk_f16_f32 v3, v12, v13
	global_store_dwordx4 v[6:7], v[0:3], off sc1
	s_andn2_b64 exec, exec, s[10:11]
	s_cbranch_execz .LBB0_699

.LBB0_700:
	v_add_u32_e32 v24, s6, v24
	v_cmp_lt_i32_e32 vcc, s7, v24
	global_store_dwordx4 v[4:5], v[0:3], off sc1
	s_or_b64 s[10:11], vcc, s[10:11]
	v_lshl_add_u64 v[4:5], v[4:5], 0, s[8:9]
	s_andn2_b64 exec, exec, s[10:11]
	s_cbranch_execnz .LBB0_700

.LBB0_738:
	s_andn2_b64 vcc, exec, s[4:5]
	s_cbranch_vccnz .LBB0_740
	global_load_dwordx4 v[158:161], v[142:143], off
	s_waitcnt vmcnt(0)
	v_cvt_f32_f16_e32 v162, v159
	v_cvt_f32_f16_sdwa v163, v159 dst_sel:DWORD dst_unused:UNUSED_PAD src0_sel:WORD_1
	v_cvt_f32_f16_e32 v164, v158
	v_cvt_f32_f16_sdwa v165, v158 dst_sel:DWORD dst_unused:UNUSED_PAD src0_sel:WORD_1
	v_cvt_f32_f16_e32 v158, v161
	v_cvt_f32_f16_e32 v166, v160
	v_cvt_f32_f16_sdwa v167, v160 dst_sel:DWORD dst_unused:UNUSED_PAD src0_sel:WORD_1
	v_cvt_f32_f16_sdwa v159, v161 dst_sel:DWORD dst_unused:UNUSED_PAD src0_sel:WORD_1
	v_pk_mul_f32 v[164:165], v[124:125], v[164:165]
	v_pk_mul_f32 v[162:163], v[126:127], v[162:163]
	v_pk_mul_f32 v[166:167], v[120:121], v[166:167]
	v_pk_mul_f32 v[158:159], v[122:123], v[158:159]
	v_cvt_pk_f16_f32 v160, v166, v167
	v_cvt_pk_f16_f32 v161, v158, v159
	v_cvt_pk_f16_f32 v159, v162, v163
	v_cvt_pk_f16_f32 v158, v164, v165
	global_store_dwordx4 v[142:143], v[158:161], off sc1

.LBB0_741:
	s_andn2_b64 vcc, exec, s[4:5]
	s_cbranch_vccnz .LBB0_743
	v_mul_f32_e32 v124, 0xbfb8aa3b, v124
	v_mul_f32_e32 v120, 0xbfb8aa3b, v120
	v_mul_f32_e32 v125, 0xbfb8aa3b, v125
	v_mul_f32_e32 v121, 0xbfb8aa3b, v121
	v_mul_f32_e32 v126, 0xbfb8aa3b, v126
	v_mul_f32_e32 v122, 0xbfb8aa3b, v122
	v_mul_f32_e32 v123, 0xbfb8aa3b, v123
	v_mul_f32_e32 v127, 0xbfb8aa3b, v127
	v_exp_f32_e32 v124, v124
	v_exp_f32_e32 v120, v120
	v_exp_f32_e32 v125, v125
	v_exp_f32_e32 v121, v121
	v_exp_f32_e32 v126, v126
	v_exp_f32_e32 v122, v122
	v_exp_f32_e32 v123, v123
	v_exp_f32_e32 v127, v127
	v_add_f32_e32 v124, 1.0, v124
	v_add_f32_e32 v120, 1.0, v120
	v_add_f32_e32 v125, 1.0, v125
	v_add_f32_e32 v121, 1.0, v121
	v_add_f32_e32 v126, 1.0, v126
	v_add_f32_e32 v122, 1.0, v122
	v_add_f32_e32 v123, 1.0, v123
	v_add_f32_e32 v127, 1.0, v127
	v_rcp_f32_e32 v124, v124
	v_rcp_f32_e32 v120, v120
	v_rcp_f32_e32 v121, v121
	v_rcp_f32_e32 v126, v126
	v_rcp_f32_e32 v122, v122
	v_rcp_f32_e32 v123, v123
	v_rcp_f32_e32 v127, v127
	v_rcp_f32_e32 v125, v125
	s_cmp_eq_u32 s41, 0
	v_cvt_pk_f16_f32 v123, v122, v123
	v_cvt_pk_f16_f32 v122, v120, v121
	v_cvt_pk_f16_f32 v121, v126, v127
	v_cvt_pk_f16_f32 v120, v124, v125
	s_cselect_b32 s5, s37, s39
	s_cselect_b32 s4, s36, s38
	global_store_dwordx4 v136, v[120:123], s[4:5] sc1

.LBB0_746:
	s_andn2_b64 vcc, exec, s[18:19]
	s_cbranch_vccnz .LBB0_748
	global_load_dwordx4 v[122:125], v[120:121], off
	s_waitcnt vmcnt(0)
	v_cvt_f32_f16_e32 v126, v123
	v_cvt_f32_f16_sdwa v127, v123 dst_sel:DWORD dst_unused:UNUSED_PAD src0_sel:WORD_1
	v_cvt_f32_f16_e32 v142, v122
	v_cvt_f32_f16_sdwa v143, v122 dst_sel:DWORD dst_unused:UNUSED_PAD src0_sel:WORD_1
	v_cvt_f32_f16_e32 v122, v125
	v_cvt_f32_f16_e32 v158, v124
	v_cvt_f32_f16_sdwa v159, v124 dst_sel:DWORD dst_unused:UNUSED_PAD src0_sel:WORD_1
	v_cvt_f32_f16_sdwa v123, v125 dst_sel:DWORD dst_unused:UNUSED_PAD src0_sel:WORD_1
	v_pk_mul_f32 v[142:143], v[116:117], v[142:143]
	v_pk_mul_f32 v[126:127], v[118:119], v[126:127]
	v_pk_mul_f32 v[158:159], v[112:113], v[158:159]
	v_pk_mul_f32 v[122:123], v[114:115], v[122:123]
	v_cvt_pk_f16_f32 v124, v158, v159
	v_cvt_pk_f16_f32 v125, v122, v123
	v_cvt_pk_f16_f32 v123, v126, v127
	v_cvt_pk_f16_f32 v122, v142, v143
	global_store_dwordx4 v[120:121], v[122:125], off sc1

.LBB0_752:
	s_andn2_b64 vcc, exec, s[18:19]
	s_cbranch_vccnz .LBB0_754
	global_load_dwordx4 v[114:117], v[112:113], off
	s_waitcnt vmcnt(0)
	v_cvt_f32_f16_e32 v118, v115
	v_cvt_f32_f16_sdwa v119, v115 dst_sel:DWORD dst_unused:UNUSED_PAD src0_sel:WORD_1
	v_cvt_f32_f16_e32 v120, v114
	v_cvt_f32_f16_sdwa v121, v114 dst_sel:DWORD dst_unused:UNUSED_PAD src0_sel:WORD_1
	v_cvt_f32_f16_e32 v114, v117
	v_cvt_f32_f16_e32 v122, v116
	v_cvt_f32_f16_sdwa v123, v116 dst_sel:DWORD dst_unused:UNUSED_PAD src0_sel:WORD_1
	v_cvt_f32_f16_sdwa v115, v117 dst_sel:DWORD dst_unused:UNUSED_PAD src0_sel:WORD_1
	v_pk_mul_f32 v[120:121], v[108:109], v[120:121]
	v_pk_mul_f32 v[118:119], v[110:111], v[118:119]
	v_pk_mul_f32 v[122:123], v[104:105], v[122:123]
	v_pk_mul_f32 v[114:115], v[106:107], v[114:115]
	v_cvt_pk_f16_f32 v116, v122, v123
	v_cvt_pk_f16_f32 v117, v114, v115
	v_cvt_pk_f16_f32 v115, v118, v119
	v_cvt_pk_f16_f32 v114, v120, v121
	global_store_dwordx4 v[112:113], v[114:117], off sc1

.LBB0_758:
	s_andn2_b64 vcc, exec, s[18:19]
	s_cbranch_vccnz .LBB0_760
	global_load_dwordx4 v[106:109], v[104:105], off
	s_waitcnt vmcnt(0)
	v_cvt_f32_f16_e32 v110, v107
	v_cvt_f32_f16_sdwa v111, v107 dst_sel:DWORD dst_unused:UNUSED_PAD src0_sel:WORD_1
	v_cvt_f32_f16_e32 v112, v106
	v_cvt_f32_f16_sdwa v113, v106 dst_sel:DWORD dst_unused:UNUSED_PAD src0_sel:WORD_1
	v_cvt_f32_f16_e32 v106, v109
	v_cvt_f32_f16_e32 v114, v108
	v_cvt_f32_f16_sdwa v115, v108 dst_sel:DWORD dst_unused:UNUSED_PAD src0_sel:WORD_1
	v_cvt_f32_f16_sdwa v107, v109 dst_sel:DWORD dst_unused:UNUSED_PAD src0_sel:WORD_1
	v_pk_mul_f32 v[112:113], v[100:101], v[112:113]
	v_pk_mul_f32 v[110:111], v[102:103], v[110:111]
	v_pk_mul_f32 v[114:115], v[96:97], v[114:115]
	v_pk_mul_f32 v[106:107], v[98:99], v[106:107]
	v_cvt_pk_f16_f32 v108, v114, v115
	v_cvt_pk_f16_f32 v109, v106, v107
	v_cvt_pk_f16_f32 v107, v110, v111
	v_cvt_pk_f16_f32 v106, v112, v113
	global_store_dwordx4 v[104:105], v[106:109], off sc1

.LBB0_764:
	s_andn2_b64 vcc, exec, s[18:19]
	s_cbranch_vccnz .LBB0_766
	global_load_dwordx4 v[98:101], v[96:97], off
	s_waitcnt vmcnt(0)
	v_cvt_f32_f16_e32 v102, v99
	v_cvt_f32_f16_sdwa v103, v99 dst_sel:DWORD dst_unused:UNUSED_PAD src0_sel:WORD_1
	v_cvt_f32_f16_e32 v104, v98
	v_cvt_f32_f16_sdwa v105, v98 dst_sel:DWORD dst_unused:UNUSED_PAD src0_sel:WORD_1
	v_cvt_f32_f16_e32 v98, v101
	v_cvt_f32_f16_e32 v106, v100
	v_cvt_f32_f16_sdwa v107, v100 dst_sel:DWORD dst_unused:UNUSED_PAD src0_sel:WORD_1
	v_cvt_f32_f16_sdwa v99, v101 dst_sel:DWORD dst_unused:UNUSED_PAD src0_sel:WORD_1
	v_pk_mul_f32 v[104:105], v[92:93], v[104:105]
	v_pk_mul_f32 v[102:103], v[94:95], v[102:103]
	v_pk_mul_f32 v[106:107], v[88:89], v[106:107]
	v_pk_mul_f32 v[98:99], v[90:91], v[98:99]
	v_cvt_pk_f16_f32 v100, v106, v107
	v_cvt_pk_f16_f32 v101, v98, v99
	v_cvt_pk_f16_f32 v99, v102, v103
	v_cvt_pk_f16_f32 v98, v104, v105
	global_store_dwordx4 v[96:97], v[98:101], off sc1

.LBB0_770:
	s_andn2_b64 vcc, exec, s[18:19]
	s_cbranch_vccnz .LBB0_772
	global_load_dwordx4 v[90:93], v[88:89], off
	s_waitcnt vmcnt(0)
	v_cvt_f32_f16_e32 v94, v91
	v_cvt_f32_f16_sdwa v95, v91 dst_sel:DWORD dst_unused:UNUSED_PAD src0_sel:WORD_1
	v_cvt_f32_f16_e32 v96, v90
	v_cvt_f32_f16_sdwa v97, v90 dst_sel:DWORD dst_unused:UNUSED_PAD src0_sel:WORD_1
	v_cvt_f32_f16_e32 v90, v93
	v_cvt_f32_f16_e32 v98, v92
	v_cvt_f32_f16_sdwa v99, v92 dst_sel:DWORD dst_unused:UNUSED_PAD src0_sel:WORD_1
	v_cvt_f32_f16_sdwa v91, v93 dst_sel:DWORD dst_unused:UNUSED_PAD src0_sel:WORD_1
	v_pk_mul_f32 v[96:97], v[84:85], v[96:97]
	v_pk_mul_f32 v[94:95], v[86:87], v[94:95]
	v_pk_mul_f32 v[98:99], v[80:81], v[98:99]
	v_pk_mul_f32 v[90:91], v[82:83], v[90:91]
	v_cvt_pk_f16_f32 v92, v98, v99
	v_cvt_pk_f16_f32 v93, v90, v91
	v_cvt_pk_f16_f32 v91, v94, v95
	v_cvt_pk_f16_f32 v90, v96, v97
	global_store_dwordx4 v[88:89], v[90:93], off sc1

.LBB0_776:
	s_andn2_b64 vcc, exec, s[18:19]
	s_cbranch_vccnz .LBB0_778
	global_load_dwordx4 v[82:85], v[80:81], off
	s_waitcnt vmcnt(0)
	v_cvt_f32_f16_e32 v86, v83
	v_cvt_f32_f16_sdwa v87, v83 dst_sel:DWORD dst_unused:UNUSED_PAD src0_sel:WORD_1
	v_cvt_f32_f16_e32 v88, v82
	v_cvt_f32_f16_sdwa v89, v82 dst_sel:DWORD dst_unused:UNUSED_PAD src0_sel:WORD_1
	v_cvt_f32_f16_e32 v82, v85
	v_cvt_f32_f16_e32 v90, v84
	v_cvt_f32_f16_sdwa v91, v84 dst_sel:DWORD dst_unused:UNUSED_PAD src0_sel:WORD_1
	v_cvt_f32_f16_sdwa v83, v85 dst_sel:DWORD dst_unused:UNUSED_PAD src0_sel:WORD_1
	v_pk_mul_f32 v[88:89], v[76:77], v[88:89]
	v_pk_mul_f32 v[86:87], v[78:79], v[86:87]
	v_pk_mul_f32 v[90:91], v[72:73], v[90:91]
	v_pk_mul_f32 v[82:83], v[74:75], v[82:83]
	v_cvt_pk_f16_f32 v84, v90, v91
	v_cvt_pk_f16_f32 v85, v82, v83
	v_cvt_pk_f16_f32 v83, v86, v87
	v_cvt_pk_f16_f32 v82, v88, v89
	global_store_dwordx4 v[80:81], v[82:85], off sc1

.LBB0_782:
	s_andn2_b64 vcc, exec, s[18:19]
	s_cbranch_vccnz .LBB0_784
	global_load_dwordx4 v[74:77], v[72:73], off
	s_waitcnt vmcnt(0)
	v_cvt_f32_f16_e32 v78, v75
	v_cvt_f32_f16_sdwa v79, v75 dst_sel:DWORD dst_unused:UNUSED_PAD src0_sel:WORD_1
	v_cvt_f32_f16_e32 v80, v74
	v_cvt_f32_f16_sdwa v81, v74 dst_sel:DWORD dst_unused:UNUSED_PAD src0_sel:WORD_1
	v_cvt_f32_f16_e32 v74, v77
	v_cvt_f32_f16_e32 v82, v76
	v_cvt_f32_f16_sdwa v83, v76 dst_sel:DWORD dst_unused:UNUSED_PAD src0_sel:WORD_1
	v_cvt_f32_f16_sdwa v75, v77 dst_sel:DWORD dst_unused:UNUSED_PAD src0_sel:WORD_1
	v_pk_mul_f32 v[80:81], v[68:69], v[80:81]
	v_pk_mul_f32 v[78:79], v[70:71], v[78:79]
	v_pk_mul_f32 v[82:83], v[64:65], v[82:83]
	v_pk_mul_f32 v[74:75], v[66:67], v[74:75]
	v_cvt_pk_f16_f32 v76, v82, v83
	v_cvt_pk_f16_f32 v77, v74, v75
	v_cvt_pk_f16_f32 v75, v78, v79
	v_cvt_pk_f16_f32 v74, v80, v81
	global_store_dwordx4 v[72:73], v[74:77], off sc1

.LBB0_788:
	s_andn2_b64 vcc, exec, s[18:19]
	s_cbranch_vccnz .LBB0_790
	global_load_dwordx4 v[66:69], v[64:65], off
	s_waitcnt vmcnt(0)
	v_cvt_f32_f16_e32 v70, v67
	v_cvt_f32_f16_sdwa v71, v67 dst_sel:DWORD dst_unused:UNUSED_PAD src0_sel:WORD_1
	v_cvt_f32_f16_e32 v72, v66
	v_cvt_f32_f16_sdwa v73, v66 dst_sel:DWORD dst_unused:UNUSED_PAD src0_sel:WORD_1
	v_cvt_f32_f16_e32 v66, v69
	v_cvt_f32_f16_e32 v74, v68
	v_cvt_f32_f16_sdwa v75, v68 dst_sel:DWORD dst_unused:UNUSED_PAD src0_sel:WORD_1
	v_cvt_f32_f16_sdwa v67, v69 dst_sel:DWORD dst_unused:UNUSED_PAD src0_sel:WORD_1
	v_pk_mul_f32 v[72:73], v[60:61], v[72:73]
	v_pk_mul_f32 v[70:71], v[62:63], v[70:71]
	v_pk_mul_f32 v[74:75], v[56:57], v[74:75]
	v_pk_mul_f32 v[66:67], v[58:59], v[66:67]
	v_cvt_pk_f16_f32 v68, v74, v75
	v_cvt_pk_f16_f32 v69, v66, v67
	v_cvt_pk_f16_f32 v67, v70, v71
	v_cvt_pk_f16_f32 v66, v72, v73
	global_store_dwordx4 v[64:65], v[66:69], off sc1

.LBB0_794:
	s_andn2_b64 vcc, exec, s[18:19]
	s_cbranch_vccnz .LBB0_796
	global_load_dwordx4 v[58:61], v[56:57], off
	s_waitcnt vmcnt(0)
	v_cvt_f32_f16_e32 v62, v59
	v_cvt_f32_f16_sdwa v63, v59 dst_sel:DWORD dst_unused:UNUSED_PAD src0_sel:WORD_1
	v_cvt_f32_f16_e32 v64, v58
	v_cvt_f32_f16_sdwa v65, v58 dst_sel:DWORD dst_unused:UNUSED_PAD src0_sel:WORD_1
	v_cvt_f32_f16_e32 v58, v61
	v_cvt_f32_f16_e32 v66, v60
	v_cvt_f32_f16_sdwa v67, v60 dst_sel:DWORD dst_unused:UNUSED_PAD src0_sel:WORD_1
	v_cvt_f32_f16_sdwa v59, v61 dst_sel:DWORD dst_unused:UNUSED_PAD src0_sel:WORD_1
	v_pk_mul_f32 v[64:65], v[52:53], v[64:65]
	v_pk_mul_f32 v[62:63], v[54:55], v[62:63]
	v_pk_mul_f32 v[66:67], v[48:49], v[66:67]
	v_pk_mul_f32 v[58:59], v[50:51], v[58:59]
	v_cvt_pk_f16_f32 v60, v66, v67
	v_cvt_pk_f16_f32 v61, v58, v59
	v_cvt_pk_f16_f32 v59, v62, v63
	v_cvt_pk_f16_f32 v58, v64, v65
	global_store_dwordx4 v[56:57], v[58:61], off sc1

.LBB0_800:
	s_andn2_b64 vcc, exec, s[18:19]
	s_cbranch_vccnz .LBB0_802
	global_load_dwordx4 v[50:53], v[48:49], off
	s_waitcnt vmcnt(0)
	v_cvt_f32_f16_e32 v54, v51
	v_cvt_f32_f16_sdwa v55, v51 dst_sel:DWORD dst_unused:UNUSED_PAD src0_sel:WORD_1
	v_cvt_f32_f16_e32 v56, v50
	v_cvt_f32_f16_sdwa v57, v50 dst_sel:DWORD dst_unused:UNUSED_PAD src0_sel:WORD_1
	v_cvt_f32_f16_e32 v50, v53
	v_cvt_f32_f16_e32 v58, v52
	v_cvt_f32_f16_sdwa v59, v52 dst_sel:DWORD dst_unused:UNUSED_PAD src0_sel:WORD_1
	v_cvt_f32_f16_sdwa v51, v53 dst_sel:DWORD dst_unused:UNUSED_PAD src0_sel:WORD_1
	v_pk_mul_f32 v[56:57], v[44:45], v[56:57]
	v_pk_mul_f32 v[54:55], v[46:47], v[54:55]
	v_pk_mul_f32 v[58:59], v[40:41], v[58:59]
	v_pk_mul_f32 v[50:51], v[42:43], v[50:51]
	v_cvt_pk_f16_f32 v52, v58, v59
	v_cvt_pk_f16_f32 v53, v50, v51
	v_cvt_pk_f16_f32 v51, v54, v55
	v_cvt_pk_f16_f32 v50, v56, v57
	global_store_dwordx4 v[48:49], v[50:53], off sc1

.LBB0_806:
	s_andn2_b64 vcc, exec, s[18:19]
	s_cbranch_vccnz .LBB0_808
	global_load_dwordx4 v[42:45], v[40:41], off
	s_waitcnt vmcnt(0)
	v_cvt_f32_f16_e32 v46, v43
	v_cvt_f32_f16_sdwa v47, v43 dst_sel:DWORD dst_unused:UNUSED_PAD src0_sel:WORD_1
	v_cvt_f32_f16_e32 v48, v42
	v_cvt_f32_f16_sdwa v49, v42 dst_sel:DWORD dst_unused:UNUSED_PAD src0_sel:WORD_1
	v_cvt_f32_f16_e32 v42, v45
	v_cvt_f32_f16_e32 v50, v44
	v_cvt_f32_f16_sdwa v51, v44 dst_sel:DWORD dst_unused:UNUSED_PAD src0_sel:WORD_1
	v_cvt_f32_f16_sdwa v43, v45 dst_sel:DWORD dst_unused:UNUSED_PAD src0_sel:WORD_1
	v_pk_mul_f32 v[48:49], v[36:37], v[48:49]
	v_pk_mul_f32 v[46:47], v[38:39], v[46:47]
	v_pk_mul_f32 v[50:51], v[32:33], v[50:51]
	v_pk_mul_f32 v[42:43], v[34:35], v[42:43]
	v_cvt_pk_f16_f32 v44, v50, v51
	v_cvt_pk_f16_f32 v45, v42, v43
	v_cvt_pk_f16_f32 v43, v46, v47
	v_cvt_pk_f16_f32 v42, v48, v49
	global_store_dwordx4 v[40:41], v[42:45], off sc1

.LBB0_812:
	s_andn2_b64 vcc, exec, s[18:19]
	s_cbranch_vccnz .LBB0_814
	global_load_dwordx4 v[34:37], v[32:33], off
	s_waitcnt vmcnt(0)
	v_cvt_f32_f16_e32 v38, v35
	v_cvt_f32_f16_sdwa v39, v35 dst_sel:DWORD dst_unused:UNUSED_PAD src0_sel:WORD_1
	v_cvt_f32_f16_e32 v40, v34
	v_cvt_f32_f16_sdwa v41, v34 dst_sel:DWORD dst_unused:UNUSED_PAD src0_sel:WORD_1
	v_cvt_f32_f16_e32 v34, v37
	v_cvt_f32_f16_e32 v42, v36
	v_cvt_f32_f16_sdwa v43, v36 dst_sel:DWORD dst_unused:UNUSED_PAD src0_sel:WORD_1
	v_cvt_f32_f16_sdwa v35, v37 dst_sel:DWORD dst_unused:UNUSED_PAD src0_sel:WORD_1
	v_pk_mul_f32 v[40:41], v[28:29], v[40:41]
	v_pk_mul_f32 v[38:39], v[30:31], v[38:39]
	v_pk_mul_f32 v[42:43], v[24:25], v[42:43]
	v_pk_mul_f32 v[34:35], v[26:27], v[34:35]
	v_cvt_pk_f16_f32 v36, v42, v43
	v_cvt_pk_f16_f32 v37, v34, v35
	v_cvt_pk_f16_f32 v35, v38, v39
	v_cvt_pk_f16_f32 v34, v40, v41
	global_store_dwordx4 v[32:33], v[34:37], off sc1

.LBB0_818:
	s_andn2_b64 vcc, exec, s[18:19]
	s_cbranch_vccnz .LBB0_820
	global_load_dwordx4 v[26:29], v[24:25], off
	s_waitcnt vmcnt(0)
	v_cvt_f32_f16_e32 v30, v27
	v_cvt_f32_f16_sdwa v31, v27 dst_sel:DWORD dst_unused:UNUSED_PAD src0_sel:WORD_1
	v_cvt_f32_f16_e32 v32, v26
	v_cvt_f32_f16_sdwa v33, v26 dst_sel:DWORD dst_unused:UNUSED_PAD src0_sel:WORD_1
	v_cvt_f32_f16_e32 v26, v29
	v_cvt_f32_f16_e32 v34, v28
	v_cvt_f32_f16_sdwa v35, v28 dst_sel:DWORD dst_unused:UNUSED_PAD src0_sel:WORD_1
	v_cvt_f32_f16_sdwa v27, v29 dst_sel:DWORD dst_unused:UNUSED_PAD src0_sel:WORD_1
	v_pk_mul_f32 v[32:33], v[20:21], v[32:33]
	v_pk_mul_f32 v[30:31], v[22:23], v[30:31]
	v_pk_mul_f32 v[34:35], v[16:17], v[34:35]
	v_pk_mul_f32 v[26:27], v[18:19], v[26:27]
	v_cvt_pk_f16_f32 v28, v34, v35
	v_cvt_pk_f16_f32 v29, v26, v27
	v_cvt_pk_f16_f32 v27, v30, v31
	v_cvt_pk_f16_f32 v26, v32, v33
	global_store_dwordx4 v[24:25], v[26:29], off sc1

.LBB0_824:
	s_andn2_b64 vcc, exec, s[18:19]
	s_cbranch_vccnz .LBB0_826
	global_load_dwordx4 v[18:21], v[16:17], off
	s_waitcnt vmcnt(0)
	v_cvt_f32_f16_e32 v22, v19
	v_cvt_f32_f16_sdwa v23, v19 dst_sel:DWORD dst_unused:UNUSED_PAD src0_sel:WORD_1
	v_cvt_f32_f16_e32 v24, v18
	v_cvt_f32_f16_sdwa v25, v18 dst_sel:DWORD dst_unused:UNUSED_PAD src0_sel:WORD_1
	v_cvt_f32_f16_e32 v18, v21
	v_cvt_f32_f16_e32 v26, v20
	v_cvt_f32_f16_sdwa v27, v20 dst_sel:DWORD dst_unused:UNUSED_PAD src0_sel:WORD_1
	v_cvt_f32_f16_sdwa v19, v21 dst_sel:DWORD dst_unused:UNUSED_PAD src0_sel:WORD_1
	v_pk_mul_f32 v[24:25], v[12:13], v[24:25]
	v_pk_mul_f32 v[22:23], v[14:15], v[22:23]
	v_pk_mul_f32 v[26:27], v[8:9], v[26:27]
	v_pk_mul_f32 v[18:19], v[10:11], v[18:19]
	v_cvt_pk_f16_f32 v20, v26, v27
	v_cvt_pk_f16_f32 v21, v18, v19
	v_cvt_pk_f16_f32 v19, v22, v23
	v_cvt_pk_f16_f32 v18, v24, v25
	global_store_dwordx4 v[16:17], v[18:21], off sc1

.LBB0_830:
	s_andn2_b64 vcc, exec, s[4:5]
	s_cbranch_vccnz .LBB0_832
	global_load_dwordx4 v[10:13], v[8:9], off
	s_waitcnt vmcnt(0)
	v_cvt_f32_f16_e32 v14, v11
	v_cvt_f32_f16_sdwa v15, v11 dst_sel:DWORD dst_unused:UNUSED_PAD src0_sel:WORD_1
	v_cvt_f32_f16_e32 v16, v10
	v_cvt_f32_f16_sdwa v17, v10 dst_sel:DWORD dst_unused:UNUSED_PAD src0_sel:WORD_1
	v_cvt_f32_f16_e32 v10, v13
	v_cvt_f32_f16_e32 v18, v12
	v_cvt_f32_f16_sdwa v19, v12 dst_sel:DWORD dst_unused:UNUSED_PAD src0_sel:WORD_1
	v_cvt_f32_f16_sdwa v11, v13 dst_sel:DWORD dst_unused:UNUSED_PAD src0_sel:WORD_1
	v_pk_mul_f32 v[16:17], v[4:5], v[16:17]
	v_pk_mul_f32 v[14:15], v[6:7], v[14:15]
	v_pk_mul_f32 v[18:19], v[0:1], v[18:19]
	v_pk_mul_f32 v[10:11], v[2:3], v[10:11]
	v_cvt_pk_f16_f32 v12, v18, v19
	v_cvt_pk_f16_f32 v13, v10, v11
	v_cvt_pk_f16_f32 v11, v14, v15
	v_cvt_pk_f16_f32 v10, v16, v17
	global_store_dwordx4 v[8:9], v[10:13], off sc1

.LBB0_835:
	v_mul_f32_e32 v116, 0xbfb8aa3b, v116
	v_mul_f32_e32 v112, 0xbfb8aa3b, v112
	v_mul_f32_e32 v117, 0xbfb8aa3b, v117
	v_mul_f32_e32 v113, 0xbfb8aa3b, v113
	v_mul_f32_e32 v118, 0xbfb8aa3b, v118
	v_mul_f32_e32 v114, 0xbfb8aa3b, v114
	v_mul_f32_e32 v115, 0xbfb8aa3b, v115
	v_mul_f32_e32 v119, 0xbfb8aa3b, v119
	v_exp_f32_e32 v116, v116
	v_exp_f32_e32 v112, v112
	v_exp_f32_e32 v117, v117
	v_exp_f32_e32 v113, v113
	v_exp_f32_e32 v118, v118
	v_exp_f32_e32 v114, v114
	v_exp_f32_e32 v115, v115
	v_exp_f32_e32 v119, v119
	v_add_f32_e32 v116, 1.0, v116
	v_add_f32_e32 v112, 1.0, v112
	v_add_f32_e32 v117, 1.0, v117
	v_add_f32_e32 v113, 1.0, v113
	v_add_f32_e32 v118, 1.0, v118
	v_add_f32_e32 v114, 1.0, v114
	v_add_f32_e32 v115, 1.0, v115
	v_add_f32_e32 v119, 1.0, v119
	v_rcp_f32_e32 v116, v116
	v_rcp_f32_e32 v112, v112
	v_rcp_f32_e32 v113, v113
	v_rcp_f32_e32 v118, v118
	v_rcp_f32_e32 v114, v114
	v_rcp_f32_e32 v115, v115
	v_rcp_f32_e32 v119, v119
	v_rcp_f32_e32 v117, v117
	s_cmp_eq_u32 s41, 0
	v_cvt_pk_f16_f32 v115, v114, v115
	v_cvt_pk_f16_f32 v114, v112, v113
	v_cvt_pk_f16_f32 v113, v118, v119
	v_cvt_pk_f16_f32 v112, v116, v117
	s_cselect_b32 s19, s37, s39
	s_cselect_b32 s18, s36, s38
	global_store_dwordx4 v136, v[112:115], s[18:19] offset:256 sc1
	v_add_u32_e32 v136, s8, v146
	s_and_b64 vcc, exec, s[4:5]
	s_mov_b64 s[18:19], -1
	s_cbranch_vccz .LBB0_750

.LBB0_837:
	v_mul_f32_e32 v108, 0xbfb8aa3b, v108
	v_mul_f32_e32 v104, 0xbfb8aa3b, v104
	v_mul_f32_e32 v109, 0xbfb8aa3b, v109
	v_mul_f32_e32 v105, 0xbfb8aa3b, v105
	v_mul_f32_e32 v110, 0xbfb8aa3b, v110
	v_mul_f32_e32 v106, 0xbfb8aa3b, v106
	v_mul_f32_e32 v107, 0xbfb8aa3b, v107
	v_mul_f32_e32 v111, 0xbfb8aa3b, v111
	v_exp_f32_e32 v108, v108
	v_exp_f32_e32 v104, v104
	v_exp_f32_e32 v109, v109
	v_exp_f32_e32 v105, v105
	v_exp_f32_e32 v110, v110
	v_exp_f32_e32 v106, v106
	v_exp_f32_e32 v107, v107
	v_exp_f32_e32 v111, v111
	v_add_f32_e32 v108, 1.0, v108
	v_add_f32_e32 v104, 1.0, v104
	v_add_f32_e32 v109, 1.0, v109
	v_add_f32_e32 v105, 1.0, v105
	v_add_f32_e32 v110, 1.0, v110
	v_add_f32_e32 v106, 1.0, v106
	v_add_f32_e32 v107, 1.0, v107
	v_add_f32_e32 v111, 1.0, v111
	v_rcp_f32_e32 v108, v108
	v_rcp_f32_e32 v104, v104
	v_rcp_f32_e32 v105, v105
	v_rcp_f32_e32 v110, v110
	v_rcp_f32_e32 v106, v106
	v_rcp_f32_e32 v107, v107
	v_rcp_f32_e32 v111, v111
	v_rcp_f32_e32 v109, v109
	s_cmp_eq_u32 s41, 0
	v_cvt_pk_f16_f32 v107, v106, v107
	v_cvt_pk_f16_f32 v106, v104, v105
	v_cvt_pk_f16_f32 v105, v110, v111
	v_cvt_pk_f16_f32 v104, v108, v109
	s_cselect_b32 s19, s37, s39
	s_cselect_b32 s18, s36, s38
	global_store_dwordx4 v136, v[104:107], s[18:19] sc1
	s_and_b64 vcc, exec, s[4:5]
	s_mov_b64 s[18:19], -1
	s_cbranch_vccz .LBB0_756

.LBB0_839:
	v_mul_f32_e32 v100, 0xbfb8aa3b, v100
	v_mul_f32_e32 v96, 0xbfb8aa3b, v96
	v_mul_f32_e32 v101, 0xbfb8aa3b, v101
	v_mul_f32_e32 v97, 0xbfb8aa3b, v97
	v_mul_f32_e32 v102, 0xbfb8aa3b, v102
	v_mul_f32_e32 v98, 0xbfb8aa3b, v98
	v_mul_f32_e32 v99, 0xbfb8aa3b, v99
	v_mul_f32_e32 v103, 0xbfb8aa3b, v103
	v_exp_f32_e32 v100, v100
	v_exp_f32_e32 v96, v96
	v_exp_f32_e32 v101, v101
	v_exp_f32_e32 v97, v97
	v_exp_f32_e32 v102, v102
	v_exp_f32_e32 v98, v98
	v_exp_f32_e32 v99, v99
	v_exp_f32_e32 v103, v103
	v_add_f32_e32 v100, 1.0, v100
	v_add_f32_e32 v96, 1.0, v96
	v_add_f32_e32 v101, 1.0, v101
	v_add_f32_e32 v97, 1.0, v97
	v_add_f32_e32 v102, 1.0, v102
	v_add_f32_e32 v98, 1.0, v98
	v_add_f32_e32 v99, 1.0, v99
	v_add_f32_e32 v103, 1.0, v103
	v_rcp_f32_e32 v100, v100
	v_rcp_f32_e32 v96, v96
	v_rcp_f32_e32 v97, v97
	v_rcp_f32_e32 v102, v102
	v_rcp_f32_e32 v98, v98
	v_rcp_f32_e32 v99, v99
	v_rcp_f32_e32 v103, v103
	v_rcp_f32_e32 v101, v101
	s_cmp_eq_u32 s41, 0
	v_cvt_pk_f16_f32 v99, v98, v99
	v_cvt_pk_f16_f32 v98, v96, v97
	v_cvt_pk_f16_f32 v97, v102, v103
	v_cvt_pk_f16_f32 v96, v100, v101
	s_cselect_b32 s19, s37, s39
	s_cselect_b32 s18, s36, s38
	global_store_dwordx4 v136, v[96:99], s[18:19] offset:256 sc1
	v_add_u32_e32 v136, s8, v147
	s_and_b64 vcc, exec, s[4:5]
	s_mov_b64 s[18:19], -1
	s_cbranch_vccz .LBB0_762

.LBB0_841:
	v_mul_f32_e32 v92, 0xbfb8aa3b, v92
	v_mul_f32_e32 v88, 0xbfb8aa3b, v88
	v_mul_f32_e32 v93, 0xbfb8aa3b, v93
	v_mul_f32_e32 v89, 0xbfb8aa3b, v89
	v_mul_f32_e32 v94, 0xbfb8aa3b, v94
	v_mul_f32_e32 v90, 0xbfb8aa3b, v90
	v_mul_f32_e32 v91, 0xbfb8aa3b, v91
	v_mul_f32_e32 v95, 0xbfb8aa3b, v95
	v_exp_f32_e32 v92, v92
	v_exp_f32_e32 v88, v88
	v_exp_f32_e32 v93, v93
	v_exp_f32_e32 v89, v89
	v_exp_f32_e32 v94, v94
	v_exp_f32_e32 v90, v90
	v_exp_f32_e32 v91, v91
	v_exp_f32_e32 v95, v95
	v_add_f32_e32 v92, 1.0, v92
	v_add_f32_e32 v88, 1.0, v88
	v_add_f32_e32 v93, 1.0, v93
	v_add_f32_e32 v89, 1.0, v89
	v_add_f32_e32 v94, 1.0, v94
	v_add_f32_e32 v90, 1.0, v90
	v_add_f32_e32 v91, 1.0, v91
	v_add_f32_e32 v95, 1.0, v95
	v_rcp_f32_e32 v92, v92
	v_rcp_f32_e32 v88, v88
	v_rcp_f32_e32 v89, v89
	v_rcp_f32_e32 v94, v94
	v_rcp_f32_e32 v90, v90
	v_rcp_f32_e32 v91, v91
	v_rcp_f32_e32 v95, v95
	v_rcp_f32_e32 v93, v93
	s_cmp_eq_u32 s41, 0
	v_cvt_pk_f16_f32 v91, v90, v91
	v_cvt_pk_f16_f32 v90, v88, v89
	v_cvt_pk_f16_f32 v89, v94, v95
	v_cvt_pk_f16_f32 v88, v92, v93
	s_cselect_b32 s19, s37, s39
	s_cselect_b32 s18, s36, s38
	global_store_dwordx4 v136, v[88:91], s[18:19] sc1
	s_and_b64 vcc, exec, s[4:5]
	s_mov_b64 s[18:19], -1
	s_cbranch_vccz .LBB0_768

.LBB0_843:
	v_mul_f32_e32 v84, 0xbfb8aa3b, v84
	v_mul_f32_e32 v80, 0xbfb8aa3b, v80
	v_mul_f32_e32 v85, 0xbfb8aa3b, v85
	v_mul_f32_e32 v81, 0xbfb8aa3b, v81
	v_mul_f32_e32 v86, 0xbfb8aa3b, v86
	v_mul_f32_e32 v82, 0xbfb8aa3b, v82
	v_mul_f32_e32 v83, 0xbfb8aa3b, v83
	v_mul_f32_e32 v87, 0xbfb8aa3b, v87
	v_exp_f32_e32 v84, v84
	v_exp_f32_e32 v80, v80
	v_exp_f32_e32 v85, v85
	v_exp_f32_e32 v81, v81
	v_exp_f32_e32 v86, v86
	v_exp_f32_e32 v82, v82
	v_exp_f32_e32 v83, v83
	v_exp_f32_e32 v87, v87
	v_add_f32_e32 v84, 1.0, v84
	v_add_f32_e32 v80, 1.0, v80
	v_add_f32_e32 v85, 1.0, v85
	v_add_f32_e32 v81, 1.0, v81
	v_add_f32_e32 v86, 1.0, v86
	v_add_f32_e32 v82, 1.0, v82
	v_add_f32_e32 v83, 1.0, v83
	v_add_f32_e32 v87, 1.0, v87
	v_rcp_f32_e32 v84, v84
	v_rcp_f32_e32 v80, v80
	v_rcp_f32_e32 v81, v81
	v_rcp_f32_e32 v86, v86
	v_rcp_f32_e32 v82, v82
	v_rcp_f32_e32 v83, v83
	v_rcp_f32_e32 v87, v87
	v_rcp_f32_e32 v85, v85
	s_cmp_eq_u32 s41, 0
	v_cvt_pk_f16_f32 v83, v82, v83
	v_cvt_pk_f16_f32 v82, v80, v81
	v_cvt_pk_f16_f32 v81, v86, v87
	v_cvt_pk_f16_f32 v80, v84, v85
	s_cselect_b32 s19, s37, s39
	s_cselect_b32 s18, s36, s38
	global_store_dwordx4 v136, v[80:83], s[18:19] offset:256 sc1
	v_add_u32_e32 v136, s8, v148
	s_and_b64 vcc, exec, s[4:5]
	s_mov_b64 s[18:19], -1
	s_cbranch_vccz .LBB0_774

.LBB0_845:
	v_mul_f32_e32 v76, 0xbfb8aa3b, v76
	v_mul_f32_e32 v72, 0xbfb8aa3b, v72
	v_mul_f32_e32 v77, 0xbfb8aa3b, v77
	v_mul_f32_e32 v73, 0xbfb8aa3b, v73
	v_mul_f32_e32 v78, 0xbfb8aa3b, v78
	v_mul_f32_e32 v74, 0xbfb8aa3b, v74
	v_mul_f32_e32 v75, 0xbfb8aa3b, v75
	v_mul_f32_e32 v79, 0xbfb8aa3b, v79
	v_exp_f32_e32 v76, v76
	v_exp_f32_e32 v72, v72
	v_exp_f32_e32 v77, v77
	v_exp_f32_e32 v73, v73
	v_exp_f32_e32 v78, v78
	v_exp_f32_e32 v74, v74
	v_exp_f32_e32 v75, v75
	v_exp_f32_e32 v79, v79
	v_add_f32_e32 v76, 1.0, v76
	v_add_f32_e32 v72, 1.0, v72
	v_add_f32_e32 v77, 1.0, v77
	v_add_f32_e32 v73, 1.0, v73
	v_add_f32_e32 v78, 1.0, v78
	v_add_f32_e32 v74, 1.0, v74
	v_add_f32_e32 v75, 1.0, v75
	v_add_f32_e32 v79, 1.0, v79
	v_rcp_f32_e32 v76, v76
	v_rcp_f32_e32 v72, v72
	v_rcp_f32_e32 v73, v73
	v_rcp_f32_e32 v78, v78
	v_rcp_f32_e32 v74, v74
	v_rcp_f32_e32 v75, v75
	v_rcp_f32_e32 v79, v79
	v_rcp_f32_e32 v77, v77
	s_cmp_eq_u32 s41, 0
	v_cvt_pk_f16_f32 v75, v74, v75
	v_cvt_pk_f16_f32 v74, v72, v73
	v_cvt_pk_f16_f32 v73, v78, v79
	v_cvt_pk_f16_f32 v72, v76, v77
	s_cselect_b32 s19, s37, s39
	s_cselect_b32 s18, s36, s38
	global_store_dwordx4 v136, v[72:75], s[18:19] sc1
	s_and_b64 vcc, exec, s[4:5]
	s_mov_b64 s[18:19], -1
	s_cbranch_vccz .LBB0_780

.LBB0_847:
	v_mul_f32_e32 v68, 0xbfb8aa3b, v68
	v_mul_f32_e32 v64, 0xbfb8aa3b, v64
	v_mul_f32_e32 v69, 0xbfb8aa3b, v69
	v_mul_f32_e32 v65, 0xbfb8aa3b, v65
	v_mul_f32_e32 v70, 0xbfb8aa3b, v70
	v_mul_f32_e32 v66, 0xbfb8aa3b, v66
	v_mul_f32_e32 v67, 0xbfb8aa3b, v67
	v_mul_f32_e32 v71, 0xbfb8aa3b, v71
	v_exp_f32_e32 v68, v68
	v_exp_f32_e32 v64, v64
	v_exp_f32_e32 v69, v69
	v_exp_f32_e32 v65, v65
	v_exp_f32_e32 v70, v70
	v_exp_f32_e32 v66, v66
	v_exp_f32_e32 v67, v67
	v_exp_f32_e32 v71, v71
	v_add_f32_e32 v68, 1.0, v68
	v_add_f32_e32 v64, 1.0, v64
	v_add_f32_e32 v69, 1.0, v69
	v_add_f32_e32 v65, 1.0, v65
	v_add_f32_e32 v70, 1.0, v70
	v_add_f32_e32 v66, 1.0, v66
	v_add_f32_e32 v67, 1.0, v67
	v_add_f32_e32 v71, 1.0, v71
	v_rcp_f32_e32 v68, v68
	v_rcp_f32_e32 v64, v64
	v_rcp_f32_e32 v65, v65
	v_rcp_f32_e32 v70, v70
	v_rcp_f32_e32 v66, v66
	v_rcp_f32_e32 v67, v67
	v_rcp_f32_e32 v71, v71
	v_rcp_f32_e32 v69, v69
	s_cmp_eq_u32 s41, 0
	v_cvt_pk_f16_f32 v67, v66, v67
	v_cvt_pk_f16_f32 v66, v64, v65
	v_cvt_pk_f16_f32 v65, v70, v71
	v_cvt_pk_f16_f32 v64, v68, v69
	s_cselect_b32 s19, s37, s39
	s_cselect_b32 s18, s36, s38
	global_store_dwordx4 v136, v[64:67], s[18:19] offset:256 sc1
	v_add_u32_e32 v136, s8, v149
	s_and_b64 vcc, exec, s[4:5]
	s_mov_b64 s[18:19], -1
	s_cbranch_vccz .LBB0_786

.LBB0_849:
	v_mul_f32_e32 v60, 0xbfb8aa3b, v60
	v_mul_f32_e32 v56, 0xbfb8aa3b, v56
	v_mul_f32_e32 v61, 0xbfb8aa3b, v61
	v_mul_f32_e32 v57, 0xbfb8aa3b, v57
	v_mul_f32_e32 v62, 0xbfb8aa3b, v62
	v_mul_f32_e32 v58, 0xbfb8aa3b, v58
	v_mul_f32_e32 v59, 0xbfb8aa3b, v59
	v_mul_f32_e32 v63, 0xbfb8aa3b, v63
	v_exp_f32_e32 v60, v60
	v_exp_f32_e32 v56, v56
	v_exp_f32_e32 v61, v61
	v_exp_f32_e32 v57, v57
	v_exp_f32_e32 v62, v62
	v_exp_f32_e32 v58, v58
	v_exp_f32_e32 v59, v59
	v_exp_f32_e32 v63, v63
	v_add_f32_e32 v60, 1.0, v60
	v_add_f32_e32 v56, 1.0, v56
	v_add_f32_e32 v61, 1.0, v61
	v_add_f32_e32 v57, 1.0, v57
	v_add_f32_e32 v62, 1.0, v62
	v_add_f32_e32 v58, 1.0, v58
	v_add_f32_e32 v59, 1.0, v59
	v_add_f32_e32 v63, 1.0, v63
	v_rcp_f32_e32 v60, v60
	v_rcp_f32_e32 v56, v56
	v_rcp_f32_e32 v57, v57
	v_rcp_f32_e32 v62, v62
	v_rcp_f32_e32 v58, v58
	v_rcp_f32_e32 v59, v59
	v_rcp_f32_e32 v63, v63
	v_rcp_f32_e32 v61, v61
	s_cmp_eq_u32 s41, 0
	v_cvt_pk_f16_f32 v59, v58, v59
	v_cvt_pk_f16_f32 v58, v56, v57
	v_cvt_pk_f16_f32 v57, v62, v63
	v_cvt_pk_f16_f32 v56, v60, v61
	s_cselect_b32 s19, s37, s39
	s_cselect_b32 s18, s36, s38
	global_store_dwordx4 v136, v[56:59], s[18:19] sc1
	s_and_b64 vcc, exec, s[4:5]
	s_mov_b64 s[18:19], -1
	s_cbranch_vccz .LBB0_792

.LBB0_851:
	v_mul_f32_e32 v52, 0xbfb8aa3b, v52
	v_mul_f32_e32 v48, 0xbfb8aa3b, v48
	v_mul_f32_e32 v53, 0xbfb8aa3b, v53
	v_mul_f32_e32 v49, 0xbfb8aa3b, v49
	v_mul_f32_e32 v54, 0xbfb8aa3b, v54
	v_mul_f32_e32 v50, 0xbfb8aa3b, v50
	v_mul_f32_e32 v51, 0xbfb8aa3b, v51
	v_mul_f32_e32 v55, 0xbfb8aa3b, v55
	v_exp_f32_e32 v52, v52
	v_exp_f32_e32 v48, v48
	v_exp_f32_e32 v53, v53
	v_exp_f32_e32 v49, v49
	v_exp_f32_e32 v54, v54
	v_exp_f32_e32 v50, v50
	v_exp_f32_e32 v51, v51
	v_exp_f32_e32 v55, v55
	v_add_f32_e32 v52, 1.0, v52
	v_add_f32_e32 v48, 1.0, v48
	v_add_f32_e32 v53, 1.0, v53
	v_add_f32_e32 v49, 1.0, v49
	v_add_f32_e32 v54, 1.0, v54
	v_add_f32_e32 v50, 1.0, v50
	v_add_f32_e32 v51, 1.0, v51
	v_add_f32_e32 v55, 1.0, v55
	v_rcp_f32_e32 v52, v52
	v_rcp_f32_e32 v48, v48
	v_rcp_f32_e32 v49, v49
	v_rcp_f32_e32 v54, v54
	v_rcp_f32_e32 v50, v50
	v_rcp_f32_e32 v51, v51
	v_rcp_f32_e32 v55, v55
	v_rcp_f32_e32 v53, v53
	s_cmp_eq_u32 s41, 0
	v_cvt_pk_f16_f32 v51, v50, v51
	v_cvt_pk_f16_f32 v50, v48, v49
	v_cvt_pk_f16_f32 v49, v54, v55
	v_cvt_pk_f16_f32 v48, v52, v53
	s_cselect_b32 s19, s37, s39
	s_cselect_b32 s18, s36, s38
	global_store_dwordx4 v136, v[48:51], s[18:19] offset:256 sc1
	v_add_u32_e32 v136, s8, v150
	s_and_b64 vcc, exec, s[4:5]
	s_mov_b64 s[18:19], -1
	s_cbranch_vccz .LBB0_798

.LBB0_853:
	v_mul_f32_e32 v44, 0xbfb8aa3b, v44
	v_mul_f32_e32 v40, 0xbfb8aa3b, v40
	v_mul_f32_e32 v45, 0xbfb8aa3b, v45
	v_mul_f32_e32 v41, 0xbfb8aa3b, v41
	v_mul_f32_e32 v46, 0xbfb8aa3b, v46
	v_mul_f32_e32 v42, 0xbfb8aa3b, v42
	v_mul_f32_e32 v43, 0xbfb8aa3b, v43
	v_mul_f32_e32 v47, 0xbfb8aa3b, v47
	v_exp_f32_e32 v44, v44
	v_exp_f32_e32 v40, v40
	v_exp_f32_e32 v45, v45
	v_exp_f32_e32 v41, v41
	v_exp_f32_e32 v46, v46
	v_exp_f32_e32 v42, v42
	v_exp_f32_e32 v43, v43
	v_exp_f32_e32 v47, v47
	v_add_f32_e32 v44, 1.0, v44
	v_add_f32_e32 v40, 1.0, v40
	v_add_f32_e32 v45, 1.0, v45
	v_add_f32_e32 v41, 1.0, v41
	v_add_f32_e32 v46, 1.0, v46
	v_add_f32_e32 v42, 1.0, v42
	v_add_f32_e32 v43, 1.0, v43
	v_add_f32_e32 v47, 1.0, v47
	v_rcp_f32_e32 v44, v44
	v_rcp_f32_e32 v40, v40
	v_rcp_f32_e32 v41, v41
	v_rcp_f32_e32 v46, v46
	v_rcp_f32_e32 v42, v42
	v_rcp_f32_e32 v43, v43
	v_rcp_f32_e32 v47, v47
	v_rcp_f32_e32 v45, v45
	s_cmp_eq_u32 s41, 0
	v_cvt_pk_f16_f32 v43, v42, v43
	v_cvt_pk_f16_f32 v42, v40, v41
	v_cvt_pk_f16_f32 v41, v46, v47
	v_cvt_pk_f16_f32 v40, v44, v45
	s_cselect_b32 s19, s37, s39
	s_cselect_b32 s18, s36, s38
	global_store_dwordx4 v136, v[40:43], s[18:19] sc1
	s_and_b64 vcc, exec, s[4:5]
	s_mov_b64 s[18:19], -1
	s_cbranch_vccz .LBB0_804

.LBB0_855:
	v_mul_f32_e32 v36, 0xbfb8aa3b, v36
	v_mul_f32_e32 v32, 0xbfb8aa3b, v32
	v_mul_f32_e32 v37, 0xbfb8aa3b, v37
	v_mul_f32_e32 v33, 0xbfb8aa3b, v33
	v_mul_f32_e32 v38, 0xbfb8aa3b, v38
	v_mul_f32_e32 v34, 0xbfb8aa3b, v34
	v_mul_f32_e32 v35, 0xbfb8aa3b, v35
	v_mul_f32_e32 v39, 0xbfb8aa3b, v39
	v_exp_f32_e32 v36, v36
	v_exp_f32_e32 v32, v32
	v_exp_f32_e32 v37, v37
	v_exp_f32_e32 v33, v33
	v_exp_f32_e32 v38, v38
	v_exp_f32_e32 v34, v34
	v_exp_f32_e32 v35, v35
	v_exp_f32_e32 v39, v39
	v_add_f32_e32 v36, 1.0, v36
	v_add_f32_e32 v32, 1.0, v32
	v_add_f32_e32 v37, 1.0, v37
	v_add_f32_e32 v33, 1.0, v33
	v_add_f32_e32 v38, 1.0, v38
	v_add_f32_e32 v34, 1.0, v34
	v_add_f32_e32 v35, 1.0, v35
	v_add_f32_e32 v39, 1.0, v39
	v_rcp_f32_e32 v36, v36
	v_rcp_f32_e32 v32, v32
	v_rcp_f32_e32 v33, v33
	v_rcp_f32_e32 v38, v38
	v_rcp_f32_e32 v34, v34
	v_rcp_f32_e32 v35, v35
	v_rcp_f32_e32 v39, v39
	v_rcp_f32_e32 v37, v37
	s_cmp_eq_u32 s41, 0
	v_cvt_pk_f16_f32 v35, v34, v35
	v_cvt_pk_f16_f32 v34, v32, v33
	v_cvt_pk_f16_f32 v33, v38, v39
	v_cvt_pk_f16_f32 v32, v36, v37
	s_cselect_b32 s19, s37, s39
	s_cselect_b32 s18, s36, s38
	global_store_dwordx4 v136, v[32:35], s[18:19] offset:256 sc1
	v_add_u32_e32 v136, s8, v151
	s_and_b64 vcc, exec, s[4:5]
	s_mov_b64 s[18:19], -1
	s_cbranch_vccz .LBB0_810

.LBB0_857:
	v_mul_f32_e32 v28, 0xbfb8aa3b, v28
	v_mul_f32_e32 v24, 0xbfb8aa3b, v24
	v_mul_f32_e32 v29, 0xbfb8aa3b, v29
	v_mul_f32_e32 v25, 0xbfb8aa3b, v25
	v_mul_f32_e32 v30, 0xbfb8aa3b, v30
	v_mul_f32_e32 v26, 0xbfb8aa3b, v26
	v_mul_f32_e32 v27, 0xbfb8aa3b, v27
	v_mul_f32_e32 v31, 0xbfb8aa3b, v31
	v_exp_f32_e32 v28, v28
	v_exp_f32_e32 v24, v24
	v_exp_f32_e32 v29, v29
	v_exp_f32_e32 v25, v25
	v_exp_f32_e32 v30, v30
	v_exp_f32_e32 v26, v26
	v_exp_f32_e32 v27, v27
	v_exp_f32_e32 v31, v31
	v_add_f32_e32 v28, 1.0, v28
	v_add_f32_e32 v24, 1.0, v24
	v_add_f32_e32 v29, 1.0, v29
	v_add_f32_e32 v25, 1.0, v25
	v_add_f32_e32 v30, 1.0, v30
	v_add_f32_e32 v26, 1.0, v26
	v_add_f32_e32 v27, 1.0, v27
	v_add_f32_e32 v31, 1.0, v31
	v_rcp_f32_e32 v28, v28
	v_rcp_f32_e32 v24, v24
	v_rcp_f32_e32 v25, v25
	v_rcp_f32_e32 v30, v30
	v_rcp_f32_e32 v26, v26
	v_rcp_f32_e32 v27, v27
	v_rcp_f32_e32 v31, v31
	v_rcp_f32_e32 v29, v29
	s_cmp_eq_u32 s41, 0
	v_cvt_pk_f16_f32 v27, v26, v27
	v_cvt_pk_f16_f32 v26, v24, v25
	v_cvt_pk_f16_f32 v25, v30, v31
	v_cvt_pk_f16_f32 v24, v28, v29
	s_cselect_b32 s19, s37, s39
	s_cselect_b32 s18, s36, s38
	global_store_dwordx4 v136, v[24:27], s[18:19] sc1
	s_and_b64 vcc, exec, s[4:5]
	s_mov_b64 s[18:19], -1
	s_cbranch_vccz .LBB0_816

.LBB0_859:
	v_mul_f32_e32 v20, 0xbfb8aa3b, v20
	v_mul_f32_e32 v16, 0xbfb8aa3b, v16
	v_mul_f32_e32 v21, 0xbfb8aa3b, v21
	v_mul_f32_e32 v17, 0xbfb8aa3b, v17
	v_mul_f32_e32 v22, 0xbfb8aa3b, v22
	v_mul_f32_e32 v18, 0xbfb8aa3b, v18
	v_mul_f32_e32 v19, 0xbfb8aa3b, v19
	v_mul_f32_e32 v23, 0xbfb8aa3b, v23
	v_exp_f32_e32 v20, v20
	v_exp_f32_e32 v16, v16
	v_exp_f32_e32 v21, v21
	v_exp_f32_e32 v17, v17
	v_exp_f32_e32 v22, v22
	v_exp_f32_e32 v18, v18
	v_exp_f32_e32 v19, v19
	v_exp_f32_e32 v23, v23
	v_add_f32_e32 v20, 1.0, v20
	v_add_f32_e32 v16, 1.0, v16
	v_add_f32_e32 v21, 1.0, v21
	v_add_f32_e32 v17, 1.0, v17
	v_add_f32_e32 v22, 1.0, v22
	v_add_f32_e32 v18, 1.0, v18
	v_add_f32_e32 v19, 1.0, v19
	v_add_f32_e32 v23, 1.0, v23
	v_rcp_f32_e32 v20, v20
	v_rcp_f32_e32 v16, v16
	v_rcp_f32_e32 v17, v17
	v_rcp_f32_e32 v22, v22
	v_rcp_f32_e32 v18, v18
	v_rcp_f32_e32 v19, v19
	v_rcp_f32_e32 v23, v23
	v_rcp_f32_e32 v21, v21
	s_cmp_eq_u32 s41, 0
	v_cvt_pk_f16_f32 v19, v18, v19
	v_cvt_pk_f16_f32 v18, v16, v17
	v_cvt_pk_f16_f32 v17, v22, v23
	v_cvt_pk_f16_f32 v16, v20, v21
	s_cselect_b32 s19, s37, s39
	s_cselect_b32 s18, s36, s38
	global_store_dwordx4 v136, v[16:19], s[18:19] offset:256 sc1
	v_add_u32_e32 v136, s8, v152
	s_and_b64 vcc, exec, s[4:5]
	s_mov_b64 s[18:19], -1
	s_cbranch_vccz .LBB0_822

.LBB0_861:
	v_mul_f32_e32 v12, 0xbfb8aa3b, v12
	v_mul_f32_e32 v8, 0xbfb8aa3b, v8
	v_mul_f32_e32 v13, 0xbfb8aa3b, v13
	v_mul_f32_e32 v9, 0xbfb8aa3b, v9
	v_mul_f32_e32 v14, 0xbfb8aa3b, v14
	v_mul_f32_e32 v10, 0xbfb8aa3b, v10
	v_mul_f32_e32 v11, 0xbfb8aa3b, v11
	v_mul_f32_e32 v15, 0xbfb8aa3b, v15
	v_exp_f32_e32 v12, v12
	v_exp_f32_e32 v8, v8
	v_exp_f32_e32 v13, v13
	v_exp_f32_e32 v9, v9
	v_exp_f32_e32 v14, v14
	v_exp_f32_e32 v10, v10
	v_exp_f32_e32 v11, v11
	v_exp_f32_e32 v15, v15
	v_add_f32_e32 v12, 1.0, v12
	v_add_f32_e32 v8, 1.0, v8
	v_add_f32_e32 v13, 1.0, v13
	v_add_f32_e32 v9, 1.0, v9
	v_add_f32_e32 v14, 1.0, v14
	v_add_f32_e32 v10, 1.0, v10
	v_add_f32_e32 v11, 1.0, v11
	v_add_f32_e32 v15, 1.0, v15
	v_rcp_f32_e32 v12, v12
	v_rcp_f32_e32 v8, v8
	v_rcp_f32_e32 v9, v9
	v_rcp_f32_e32 v14, v14
	v_rcp_f32_e32 v10, v10
	v_rcp_f32_e32 v11, v11
	v_rcp_f32_e32 v15, v15
	v_rcp_f32_e32 v13, v13
	s_cmp_eq_u32 s41, 0
	v_cvt_pk_f16_f32 v11, v10, v11
	v_cvt_pk_f16_f32 v10, v8, v9
	v_cvt_pk_f16_f32 v9, v14, v15
	v_cvt_pk_f16_f32 v8, v12, v13
	s_cselect_b32 s19, s37, s39
	s_cselect_b32 s18, s36, s38
	global_store_dwordx4 v136, v[8:11], s[18:19] sc1
	s_and_b64 vcc, exec, s[4:5]
	s_mov_b64 s[4:5], -1
	s_cbranch_vccz .LBB0_828

.LBB0_863:
	v_mul_f32_e32 v4, 0xbfb8aa3b, v4
	v_mul_f32_e32 v0, 0xbfb8aa3b, v0
	v_mul_f32_e32 v5, 0xbfb8aa3b, v5
	v_mul_f32_e32 v1, 0xbfb8aa3b, v1
	v_mul_f32_e32 v6, 0xbfb8aa3b, v6
	v_mul_f32_e32 v2, 0xbfb8aa3b, v2
	v_mul_f32_e32 v3, 0xbfb8aa3b, v3
	v_mul_f32_e32 v7, 0xbfb8aa3b, v7
	v_exp_f32_e32 v4, v4
	v_exp_f32_e32 v0, v0
	v_exp_f32_e32 v5, v5
	v_exp_f32_e32 v1, v1
	v_exp_f32_e32 v6, v6
	v_exp_f32_e32 v2, v2
	v_exp_f32_e32 v3, v3
	v_exp_f32_e32 v7, v7
	v_add_f32_e32 v4, 1.0, v4
	v_add_f32_e32 v0, 1.0, v0
	v_add_f32_e32 v5, 1.0, v5
	v_add_f32_e32 v1, 1.0, v1
	v_add_f32_e32 v6, 1.0, v6
	v_add_f32_e32 v2, 1.0, v2
	v_add_f32_e32 v3, 1.0, v3
	v_add_f32_e32 v7, 1.0, v7
	v_rcp_f32_e32 v4, v4
	v_rcp_f32_e32 v0, v0
	v_rcp_f32_e32 v1, v1
	v_rcp_f32_e32 v6, v6
	v_rcp_f32_e32 v2, v2
	v_rcp_f32_e32 v3, v3
	v_rcp_f32_e32 v7, v7
	v_rcp_f32_e32 v5, v5
	s_cmp_eq_u32 s41, 0
	v_cvt_pk_f16_f32 v3, v2, v3
	v_cvt_pk_f16_f32 v2, v0, v1
	v_cvt_pk_f16_f32 v1, v6, v7
	v_cvt_pk_f16_f32 v0, v4, v5
	s_cselect_b32 s5, s37, s39
	s_cselect_b32 s4, s36, s38
	global_store_dwordx4 v136, v[0:3], s[4:5] offset:256 sc1
	s_cmp_eq_u32 s40, 3
	s_mov_b64 s[4:5], -1
	s_cbranch_scc1 .LBB0_723

.LBB0_936:
	v_mov_b32_e32 v129, 0
	v_add_u32_e32 v145, 0x8000, v144
	v_or_b32_e32 v133, s54, v128
	v_lshl_add_u64 v[130:131], s[12:13], 0, v[128:129]
	v_min_i32_e32 v128, 0x807f, v145
	v_lshlrev_b32_e32 v128, 6, v128
	v_lshl_add_u64 v[134:135], v[130:131], 0, v[128:129]
	global_load_dwordx4 v[134:137], v[134:135], off
	v_add_u32_e32 v148, 0x8010, v144
	v_min_i32_e32 v128, 0x807f, v148
	v_lshlrev_b32_e32 v128, 6, v128
	v_lshl_add_u64 v[138:139], v[130:131], 0, v[128:129]
	global_load_dwordx4 v[138:141], v[138:139], off
	v_lshl_add_u32 v128, v145, 11, s46
	v_or_b32_e32 v145, v128, v133
	v_mov_b32_e32 v132, 0x358637bd
	s_mov_b32 m0, s44
	s_add_u32 s44, s76, 0xfc00000
	s_addc_u32 s45, s77, 0
	s_lshl_b64 s[4:5], s[30:31], 17
	s_add_u32 s3, s76, s4
	s_addc_u32 s13, s77, s5
	s_add_u32 s4, s3, 0x1e00000
	s_addc_u32 s5, s13, 0
	s_add_u32 s10, s3, 0x1e10000
	s_addc_u32 s11, s13, 0
	s_add_u32 s6, s76, 0x7900000
	s_addc_u32 s7, s77, 0
	s_add_u32 s8, s76, 0x7910000
	s_addc_u32 s9, s77, 0
	s_add_u32 s14, s76, 0x7900080
	s_addc_u32 s15, s77, 0
	s_add_u32 s12, s3, 0x1e10080
	s_mov_b32 s3, 0x201000
	s_mov_b64 s[16:17], 0x80
	s_addc_u32 s13, s13, 0
	s_waitcnt vmcnt(0)
	v_mov_b32_e32 v146, v135
	v_mov_b32_e32 v147, v136
	v_mov_b32_e32 v135, v137
	v_pk_add_f32 v[134:135], v[146:147], v[134:135]
	s_nop 0
	v_add_f32_e32 v128, v134, v135
	ds_bpermute_b32 v134, v142, v128
	v_mov_b32_e32 v135, v140
	s_waitcnt lgkmcnt(0)
	v_add_f32_e32 v128, v128, v134
	ds_bpermute_b32 v136, v143, v128
	v_mov_b32_e32 v134, v139
	v_mov_b32_e32 v139, v141
	v_pk_add_f32 v[134:135], v[134:135], v[138:139]
	s_waitcnt lgkmcnt(0)
	v_add_f32_e32 v128, v128, v136
	v_fmamk_f32 v128, v128, 0x3a800000, v132
	v_rsq_f32_e32 v128, v128
	v_add_f32_e32 v134, v134, v135
	ds_bpermute_b32 v135, v142, v134
	v_mul_f32_e32 v128, 0xbfb8aa3b, v128
	v_mul_f32_e32 v124, v124, v128
	v_mul_f32_e32 v120, v120, v128
	v_mul_f32_e32 v125, v125, v128
	v_mul_f32_e32 v121, v121, v128
	v_mul_f32_e32 v126, v126, v128
	v_mul_f32_e32 v122, v122, v128
	v_mul_f32_e32 v127, v127, v128
	v_mul_f32_e32 v123, v123, v128
	v_exp_f32_e32 v124, v124
	v_exp_f32_e32 v120, v120
	v_exp_f32_e32 v125, v125
	v_exp_f32_e32 v121, v121
	v_exp_f32_e32 v126, v126
	v_exp_f32_e32 v122, v122
	v_exp_f32_e32 v127, v127
	v_exp_f32_e32 v123, v123
	v_mul_f32_e32 v112, v112, v128
	v_mul_f32_e32 v117, v117, v128
	v_mul_f32_e32 v113, v113, v128
	v_mul_f32_e32 v118, v118, v128
	v_mul_f32_e32 v114, v114, v128
	v_mul_f32_e32 v115, v115, v128
	v_mul_f32_e32 v116, v116, v128
	v_mul_f32_e32 v119, v119, v128
	v_exp_f32_e32 v112, v112
	v_exp_f32_e32 v117, v117
	v_exp_f32_e32 v113, v113
	v_exp_f32_e32 v118, v118
	v_exp_f32_e32 v114, v114
	v_exp_f32_e32 v128, v115
	v_add_f32_e32 v115, 1.0, v124
	v_add_f32_e32 v120, 1.0, v120
	v_add_f32_e32 v124, 1.0, v125
	v_add_f32_e32 v121, 1.0, v121
	v_add_f32_e32 v125, 1.0, v126
	v_add_f32_e32 v122, 1.0, v122
	v_add_f32_e32 v126, 1.0, v127
	v_add_f32_e32 v123, 1.0, v123
	v_rcp_f32_e32 v127, v115
	v_rcp_f32_e32 v120, v120
	v_rcp_f32_e32 v124, v124
	v_rcp_f32_e32 v121, v121
	v_rcp_f32_e32 v125, v125
	v_rcp_f32_e32 v115, v122
	v_rcp_f32_e32 v122, v126
	v_rcp_f32_e32 v123, v123
	v_exp_f32_e32 v119, v119
	v_add_f32_e32 v112, 1.0, v112
	v_add_f32_e32 v117, 1.0, v117
	v_add_f32_e32 v113, 1.0, v113
	v_add_f32_e32 v118, 1.0, v118
	v_add_f32_e32 v114, 1.0, v114
	v_rcp_f32_e32 v126, v112
	v_rcp_f32_e32 v136, v117
	v_rcp_f32_e32 v117, v113
	v_rcp_f32_e32 v137, v118
	v_rcp_f32_e32 v118, v114
	v_cvt_pk_f16_f32 v115, v115, v123
	v_cvt_pk_f16_f32 v114, v120, v121
	v_cvt_pk_f16_f32 v113, v125, v122
	v_cvt_pk_f16_f32 v112, v127, v124
	global_store_dwordx4 v145, v[112:115], s[44:45] sc1
	v_add_u32_e32 v123, 0x8020, v144
	s_waitcnt lgkmcnt(0)
	v_add_f32_e32 v121, v134, v135
	v_add_f32_e32 v112, 1.0, v119
	v_rcp_f32_e32 v120, v112
	v_min_i32_e32 v112, 0x807f, v123
	v_add_f32_e32 v119, 1.0, v128
	v_lshlrev_b32_e32 v128, 6, v112
	v_lshl_add_u64 v[112:113], v[130:131], 0, v[128:129]
	global_load_dwordx4 v[112:115], v[112:113], off
	ds_bpermute_b32 v122, v143, v121
	v_rcp_f32_e32 v119, v119
	v_exp_f32_e32 v116, v116
	s_waitcnt lgkmcnt(0)
	v_add_f32_e32 v121, v121, v122
	v_fmamk_f32 v121, v121, 0x3a800000, v132
	v_rsq_f32_e32 v121, v121
	v_cvt_pk_f16_f32 v119, v118, v119
	v_cvt_pk_f16_f32 v118, v126, v117
	v_cvt_pk_f16_f32 v117, v137, v120
	v_mul_f32_e32 v120, 0xbfb8aa3b, v121
	v_mul_f32_e32 v108, v108, v120
	v_mul_f32_e32 v104, v104, v120
	v_mul_f32_e32 v109, v109, v120
	v_mul_f32_e32 v105, v105, v120
	v_mul_f32_e32 v106, v106, v120
	v_mul_f32_e32 v107, v107, v120
	v_exp_f32_e32 v108, v108
	v_exp_f32_e32 v104, v104
	v_exp_f32_e32 v109, v109
	v_exp_f32_e32 v105, v105
	v_exp_f32_e32 v106, v106
	v_exp_f32_e32 v107, v107
	v_mul_f32_e32 v96, v96, v120
	v_add_f32_e32 v108, 1.0, v108
	v_add_f32_e32 v104, 1.0, v104
	v_add_f32_e32 v109, 1.0, v109
	v_add_f32_e32 v105, 1.0, v105
	v_add_f32_e32 v106, 1.0, v106
	v_add_f32_e32 v107, 1.0, v107
	v_exp_f32_e32 v96, v96
	v_mul_f32_e32 v101, v101, v120
	v_rcp_f32_e32 v108, v108
	v_rcp_f32_e32 v104, v104
	v_rcp_f32_e32 v105, v105
	v_rcp_f32_e32 v106, v106
	v_rcp_f32_e32 v107, v107
	v_rcp_f32_e32 v109, v109
	v_exp_f32_e32 v101, v101
	v_mul_f32_e32 v97, v97, v120
	v_mul_f32_e32 v110, v110, v120
	v_mul_f32_e32 v111, v111, v120
	v_exp_f32_e32 v97, v97
	v_exp_f32_e32 v110, v110
	v_exp_f32_e32 v111, v111
	v_add_f32_e32 v96, 1.0, v96
	v_cvt_pk_f16_f32 v107, v106, v107
	v_cvt_pk_f16_f32 v106, v104, v105
	v_cvt_pk_f16_f32 v104, v108, v109
	v_rcp_f32_e32 v109, v96
	v_add_f32_e32 v96, 1.0, v101
	v_rcp_f32_e32 v101, v96
	v_add_f32_e32 v96, 1.0, v97
	v_mul_f32_e32 v97, v102, v120
	v_add_f32_e32 v110, 1.0, v110
	v_add_f32_e32 v111, 1.0, v111
	v_exp_f32_e32 v97, v97
	v_mul_f32_e32 v98, v98, v120
	v_rcp_f32_e32 v110, v110
	v_rcp_f32_e32 v111, v111
	v_exp_f32_e32 v98, v98
	v_add_f32_e32 v116, 1.0, v116
	v_rcp_f32_e32 v116, v116
	v_rcp_f32_e32 v102, v96
	v_add_f32_e32 v96, 1.0, v97
	v_cvt_pk_f16_f32 v105, v110, v111
	v_rcp_f32_e32 v110, v96
	v_add_f32_e32 v96, 1.0, v98
	v_add_u32_e32 v111, 0x8030, v144
	v_rcp_f32_e32 v98, v96
	v_min_i32_e32 v96, 0x807f, v111
	v_lshl_add_u32 v108, v148, 11, s46
	v_lshlrev_b32_e32 v128, 6, v96
	v_cvt_pk_f16_f32 v116, v116, v136
	v_or_b32_e32 v121, 0x100, v145
	v_or_b32_e32 v108, v108, v133
	v_lshl_add_u64 v[96:97], v[130:131], 0, v[128:129]
	global_store_dwordx4 v121, v[116:119], s[44:45] sc1
	global_store_dwordx4 v108, v[104:107], s[44:45] sc1
	global_load_dwordx4 v[104:107], v[96:97], off
	s_waitcnt vmcnt(3)
	v_mov_b32_e32 v96, v113
	v_mov_b32_e32 v97, v114
	v_mov_b32_e32 v113, v115
	v_pk_add_f32 v[96:97], v[96:97], v[112:113]
	v_mul_f32_e32 v99, v99, v120
	v_add_f32_e32 v96, v96, v97
	ds_bpermute_b32 v97, v142, v96
	v_exp_f32_e32 v99, v99
	v_mul_f32_e32 v100, v100, v120
	v_mul_f32_e32 v103, v103, v120
	v_exp_f32_e32 v100, v100
	s_waitcnt lgkmcnt(0)
	v_add_f32_e32 v96, v96, v97
	ds_bpermute_b32 v97, v143, v96
	v_add_f32_e32 v99, 1.0, v99
	v_rcp_f32_e32 v99, v99
	v_exp_f32_e32 v103, v103
	v_add_f32_e32 v100, 1.0, v100
	s_waitcnt lgkmcnt(0)
	v_add_f32_e32 v96, v96, v97
	v_fmamk_f32 v96, v96, 0x3a800000, v132
	v_rsq_f32_e32 v96, v96
	v_cvt_pk_f16_f32 v99, v98, v99
	v_cvt_pk_f16_f32 v98, v109, v102
	v_add_f32_e32 v103, 1.0, v103
	v_mul_f32_e32 v102, 0xbfb8aa3b, v96
	v_mul_f32_e32 v92, v92, v102
	v_mul_f32_e32 v88, v88, v102
	v_mul_f32_e32 v93, v93, v102
	v_mul_f32_e32 v89, v89, v102
	v_mul_f32_e32 v90, v90, v102
	v_mul_f32_e32 v91, v91, v102
	v_exp_f32_e32 v92, v92
	v_exp_f32_e32 v88, v88
	v_exp_f32_e32 v93, v93
	v_exp_f32_e32 v89, v89
	v_mul_f32_e32 v94, v94, v102
	v_exp_f32_e32 v90, v90
	v_exp_f32_e32 v91, v91
	v_mul_f32_e32 v95, v95, v102
	v_exp_f32_e32 v94, v94
	v_exp_f32_e32 v95, v95
	v_add_f32_e32 v92, 1.0, v92
	v_add_f32_e32 v88, 1.0, v88
	v_add_f32_e32 v93, 1.0, v93
	v_add_f32_e32 v89, 1.0, v89
	v_add_f32_e32 v90, 1.0, v90
	v_add_f32_e32 v91, 1.0, v91
	v_rcp_f32_e32 v92, v92
	v_rcp_f32_e32 v88, v88
	v_rcp_f32_e32 v89, v89
	v_add_f32_e32 v94, 1.0, v94
	v_rcp_f32_e32 v90, v90
	v_rcp_f32_e32 v91, v91
	v_add_f32_e32 v95, 1.0, v95
	v_rcp_f32_e32 v93, v93
	v_mul_f32_e32 v84, v84, v102
	v_rcp_f32_e32 v100, v100
	v_rcp_f32_e32 v103, v103
	v_rcp_f32_e32 v94, v94
	v_rcp_f32_e32 v95, v95
	v_exp_f32_e32 v84, v84
	v_cvt_pk_f16_f32 v91, v90, v91
	v_cvt_pk_f16_f32 v90, v88, v89
	v_cvt_pk_f16_f32 v88, v92, v93
	v_lshl_add_u32 v92, v123, 11, s46
	v_cvt_pk_f16_f32 v97, v110, v103
	v_cvt_pk_f16_f32 v96, v100, v101
	v_or_b32_e32 v100, 0x100, v108
	v_cvt_pk_f16_f32 v89, v94, v95
	v_or_b32_e32 v92, v92, v133
	v_mul_f32_e32 v80, v80, v102
	v_add_f32_e32 v84, 1.0, v84
	global_store_dwordx4 v100, v[96:99], s[44:45] sc1
	v_exp_f32_e32 v80, v80
	global_store_dwordx4 v92, v[88:91], s[44:45] sc1
	v_mul_f32_e32 v81, v81, v102
	v_exp_f32_e32 v81, v81
	v_rcp_f32_e32 v90, v84
	v_mul_f32_e32 v84, v85, v102
	v_exp_f32_e32 v84, v84
	v_add_f32_e32 v80, 1.0, v80
	v_rcp_f32_e32 v88, v80
	v_mul_f32_e32 v82, v82, v102
	v_add_f32_e32 v80, 1.0, v84
	v_rcp_f32_e32 v91, v80
	v_add_f32_e32 v80, 1.0, v81
	v_mul_f32_e32 v81, v86, v102
	v_exp_f32_e32 v81, v81
	v_exp_f32_e32 v82, v82
	v_rcp_f32_e32 v86, v80
	v_add_co_u32_e32 v84, vcc, s3, v130
	v_add_f32_e32 v80, 1.0, v81
	v_rcp_f32_e32 v93, v80
	v_add_f32_e32 v80, 1.0, v82
	v_rcp_f32_e32 v89, v80
	s_waitcnt vmcnt(2)
	v_mov_b32_e32 v80, v105
	v_mov_b32_e32 v81, v106
	v_mov_b32_e32 v105, v107
	v_pk_add_f32 v[80:81], v[80:81], v[104:105]
	v_mul_f32_e32 v82, v87, v102
	v_add_f32_e32 v80, v80, v81
	ds_bpermute_b32 v81, v142, v80
	v_exp_f32_e32 v87, v82
	v_mul_f32_e32 v82, v83, v102
	v_addc_co_u32_e32 v85, vcc, 0, v131, vcc
	v_exp_f32_e32 v94, v82
	s_waitcnt lgkmcnt(0)
	v_add_f32_e32 v95, v80, v81
	global_load_dwordx4 v[80:83], v[84:85], off offset:4032
	ds_bpermute_b32 v96, v143, v95
	v_add_f32_e32 v87, 1.0, v87
	v_rcp_f32_e32 v87, v87
	v_add_f32_e32 v94, 1.0, v94
	v_rcp_f32_e32 v94, v94
	s_waitcnt lgkmcnt(0)
	v_add_f32_e32 v95, v95, v96
	v_fmamk_f32 v95, v95, 0x3a800000, v132
	v_rsq_f32_e32 v95, v95
	v_cvt_pk_f16_f32 v87, v93, v87
	v_cvt_pk_f16_f32 v89, v89, v94
	v_cvt_pk_f16_f32 v88, v88, v86
	v_mul_f32_e32 v93, 0xbfb8aa3b, v95
	v_mul_f32_e32 v76, v76, v93
	v_mul_f32_e32 v72, v72, v93
	v_mul_f32_e32 v77, v77, v93
	v_mul_f32_e32 v73, v73, v93
	v_mul_f32_e32 v74, v74, v93
	v_mul_f32_e32 v75, v75, v93
	v_exp_f32_e32 v76, v76
	v_exp_f32_e32 v72, v72
	v_exp_f32_e32 v77, v77
	v_exp_f32_e32 v73, v73
	v_mul_f32_e32 v78, v78, v93
	v_exp_f32_e32 v74, v74
	v_exp_f32_e32 v75, v75
	v_mul_f32_e32 v79, v79, v93
	v_exp_f32_e32 v78, v78
	v_exp_f32_e32 v79, v79
	v_add_f32_e32 v76, 1.0, v76
	v_add_f32_e32 v72, 1.0, v72
	v_add_f32_e32 v77, 1.0, v77
	v_add_f32_e32 v73, 1.0, v73
	v_add_f32_e32 v74, 1.0, v74
	v_add_f32_e32 v75, 1.0, v75
	v_rcp_f32_e32 v76, v76
	v_rcp_f32_e32 v72, v72
	v_rcp_f32_e32 v73, v73
	v_add_f32_e32 v78, 1.0, v78
	v_rcp_f32_e32 v74, v74
	v_rcp_f32_e32 v75, v75
	v_add_f32_e32 v79, 1.0, v79
	v_rcp_f32_e32 v77, v77
	v_mul_f32_e32 v64, v64, v93
	v_rcp_f32_e32 v78, v78
	v_rcp_f32_e32 v79, v79
	v_exp_f32_e32 v64, v64
	v_mul_f32_e32 v68, v68, v93
	v_exp_f32_e32 v68, v68
	v_mul_f32_e32 v65, v65, v93
	v_exp_f32_e32 v65, v65
	v_cvt_pk_f16_f32 v75, v74, v75
	v_cvt_pk_f16_f32 v74, v72, v73
	v_cvt_pk_f16_f32 v72, v76, v77
	v_lshl_add_u32 v76, v111, 11, s46
	v_cvt_pk_f16_f32 v86, v90, v91
	v_or_b32_e32 v90, 0x100, v92
	v_cvt_pk_f16_f32 v73, v78, v79
	v_or_b32_e32 v76, v76, v133
	v_add_f32_e32 v64, 1.0, v64
	global_store_dwordx4 v90, v[86:89], s[44:45] sc1
	global_store_dwordx4 v76, v[72:75], s[44:45] sc1
	v_mul_f32_e32 v67, v67, v93
	v_exp_f32_e32 v67, v67
	v_rcp_f32_e32 v72, v64
	v_add_f32_e32 v64, 1.0, v68
	v_rcp_f32_e32 v73, v64
	v_add_f32_e32 v64, 1.0, v65
	v_rcp_f32_e32 v74, v64
	v_mul_f32_e32 v64, v69, v93
	v_exp_f32_e32 v64, v64
	v_mul_f32_e32 v65, v66, v93
	v_mul_f32_e32 v66, v70, v93
	v_exp_f32_e32 v66, v66
	v_add_f32_e32 v64, 1.0, v64
	v_rcp_f32_e32 v75, v64
	v_exp_f32_e32 v65, v65
	v_add_f32_e32 v64, 1.0, v66
	v_rcp_f32_e32 v66, v64
	v_mul_f32_e32 v64, v71, v93
	global_load_dwordx4 v[68:71], v[84:85], off offset:4032
	v_add_f32_e32 v77, 1.0, v65
	v_exp_f32_e32 v78, v64
	s_waitcnt vmcnt(3)
	v_mov_b32_e32 v64, v81
	v_mov_b32_e32 v65, v82
	v_mov_b32_e32 v81, v83
	v_pk_add_f32 v[64:65], v[64:65], v[80:81]
	v_add_f32_e32 v78, 1.0, v78
	v_add_f32_e32 v64, v64, v65
	ds_bpermute_b32 v65, v142, v64
	v_rcp_f32_e32 v78, v78
	v_add_f32_e32 v67, 1.0, v67
	v_rcp_f32_e32 v79, v67
	v_rcp_f32_e32 v77, v77
	s_waitcnt lgkmcnt(0)
	v_add_f32_e32 v64, v64, v65
	ds_bpermute_b32 v65, v143, v64
	v_cvt_pk_f16_f32 v67, v66, v78
	v_cvt_pk_f16_f32 v66, v73, v75
	v_or_b32_e32 v73, 0x100, v76
	s_mov_b32 s3, 0x7fffe0
	s_waitcnt lgkmcnt(0)
	v_add_f32_e32 v64, v64, v65
	v_fmamk_f32 v64, v64, 0x3a800000, v132
	v_rsq_f32_e32 v78, v64
	v_cvt_pk_f16_f32 v64, v72, v74
	v_cvt_pk_f16_f32 v65, v77, v79
	global_store_dwordx4 v73, v[64:67], s[44:45] sc1
	v_mul_f32_e32 v72, 0xbfb8aa3b, v78
	v_mul_f32_e32 v60, v60, v72
	v_mul_f32_e32 v56, v56, v72
	v_mul_f32_e32 v61, v61, v72
	v_mul_f32_e32 v57, v57, v72
	v_mul_f32_e32 v58, v58, v72
	v_mul_f32_e32 v59, v59, v72
	v_exp_f32_e32 v60, v60
	v_exp_f32_e32 v56, v56
	v_exp_f32_e32 v61, v61
	v_exp_f32_e32 v57, v57
	v_mul_f32_e32 v62, v62, v72
	v_exp_f32_e32 v58, v58
	v_exp_f32_e32 v59, v59
	v_mul_f32_e32 v63, v63, v72
	v_mul_f32_e32 v52, v52, v72
	v_mul_f32_e32 v48, v48, v72
	v_mul_f32_e32 v53, v53, v72
	v_mul_f32_e32 v49, v49, v72
	v_mul_f32_e32 v54, v54, v72
	v_mul_f32_e32 v50, v50, v72
	v_mul_f32_e32 v51, v51, v72
	v_mul_f32_e32 v55, v55, v72
	v_mul_f32_e32 v44, v44, v72
	v_mul_f32_e32 v40, v40, v72
	v_mul_f32_e32 v45, v45, v72
	v_mul_f32_e32 v41, v41, v72
	v_mul_f32_e32 v46, v46, v72
	v_mul_f32_e32 v42, v42, v72
	v_mul_f32_e32 v43, v43, v72
	v_mul_f32_e32 v47, v47, v72
	v_exp_f32_e32 v62, v62
	v_exp_f32_e32 v63, v63
	v_exp_f32_e32 v52, v52
	v_exp_f32_e32 v48, v48
	v_exp_f32_e32 v53, v53
	v_exp_f32_e32 v49, v49
	v_exp_f32_e32 v54, v54
	v_exp_f32_e32 v50, v50
	v_exp_f32_e32 v51, v51
	v_exp_f32_e32 v55, v55
	v_exp_f32_e32 v44, v44
	v_exp_f32_e32 v40, v40
	v_exp_f32_e32 v45, v45
	v_exp_f32_e32 v41, v41
	v_exp_f32_e32 v46, v46
	v_exp_f32_e32 v42, v42
	v_exp_f32_e32 v43, v43
	v_exp_f32_e32 v47, v47
	v_add_f32_e32 v60, 1.0, v60
	v_add_f32_e32 v56, 1.0, v56
	v_add_f32_e32 v61, 1.0, v61
	v_add_f32_e32 v57, 1.0, v57
	v_add_f32_e32 v58, 1.0, v58
	v_add_f32_e32 v59, 1.0, v59
	v_rcp_f32_e32 v60, v60
	v_rcp_f32_e32 v56, v56
	v_rcp_f32_e32 v57, v57
	v_add_f32_e32 v62, 1.0, v62
	v_rcp_f32_e32 v58, v58
	v_rcp_f32_e32 v59, v59
	v_add_f32_e32 v63, 1.0, v63
	v_rcp_f32_e32 v61, v61
	v_add_f32_e32 v52, 1.0, v52
	v_add_f32_e32 v48, 1.0, v48
	v_add_f32_e32 v53, 1.0, v53
	v_add_f32_e32 v49, 1.0, v49
	v_add_f32_e32 v54, 1.0, v54
	v_add_f32_e32 v50, 1.0, v50
	v_add_f32_e32 v51, 1.0, v51
	v_add_f32_e32 v55, 1.0, v55
	v_add_f32_e32 v44, 1.0, v44
	v_add_f32_e32 v40, 1.0, v40
	v_add_f32_e32 v45, 1.0, v45
	v_add_f32_e32 v41, 1.0, v41
	v_add_f32_e32 v46, 1.0, v46
	v_add_f32_e32 v42, 1.0, v42
	v_add_f32_e32 v43, 1.0, v43
	v_add_f32_e32 v47, 1.0, v47
	v_mul_f32_e32 v32, v32, v72
	v_rcp_f32_e32 v62, v62
	v_rcp_f32_e32 v63, v63
	v_rcp_f32_e32 v52, v52
	v_rcp_f32_e32 v48, v48
	v_rcp_f32_e32 v49, v49
	v_rcp_f32_e32 v54, v54
	v_rcp_f32_e32 v50, v50
	v_rcp_f32_e32 v51, v51
	v_rcp_f32_e32 v55, v55
	v_rcp_f32_e32 v53, v53
	v_rcp_f32_e32 v44, v44
	v_rcp_f32_e32 v40, v40
	v_rcp_f32_e32 v41, v41
	v_rcp_f32_e32 v46, v46
	v_rcp_f32_e32 v42, v42
	v_rcp_f32_e32 v43, v43
	v_rcp_f32_e32 v47, v47
	v_rcp_f32_e32 v45, v45
	v_exp_f32_e32 v32, v32
	v_mul_f32_e32 v37, v37, v72
	v_exp_f32_e32 v37, v37
	v_mul_f32_e32 v33, v33, v72
	v_lshlrev_b32_e32 v64, 11, v144
	v_exp_f32_e32 v33, v33
	v_cvt_pk_f16_f32 v59, v58, v59
	v_cvt_pk_f16_f32 v58, v56, v57
	v_cvt_pk_f16_f32 v56, v60, v61
	v_add3_u32 v60, v64, s46, v133
	v_cvt_pk_f16_f32 v57, v62, v63
	v_add_u32_e32 v61, 0x4040000, v60
	v_cvt_pk_f16_f32 v51, v50, v51
	v_cvt_pk_f16_f32 v50, v48, v49
	v_cvt_pk_f16_f32 v49, v54, v55
	v_cvt_pk_f16_f32 v48, v52, v53
	v_add_u32_e32 v52, 0x4040100, v60
	v_cvt_pk_f16_f32 v43, v42, v43
	v_cvt_pk_f16_f32 v42, v40, v41
	v_cvt_pk_f16_f32 v41, v46, v47
	v_cvt_pk_f16_f32 v40, v44, v45
	v_add_u32_e32 v44, 0x4048000, v60
	v_add_f32_e32 v32, 1.0, v32
	global_store_dwordx4 v61, v[56:59], s[44:45] sc1
	global_store_dwordx4 v52, v[48:51], s[44:45] sc1
	global_store_dwordx4 v44, v[40:43], s[44:45] sc1
	v_mul_f32_e32 v34, v34, v72
	v_exp_f32_e32 v34, v34
	v_rcp_f32_e32 v40, v32
	v_add_f32_e32 v32, 1.0, v37
	v_rcp_f32_e32 v41, v32
	v_add_f32_e32 v32, 1.0, v33
	v_mul_f32_e32 v33, v38, v72
	v_exp_f32_e32 v33, v33
	v_rcp_f32_e32 v37, v32
	v_mul_f32_e32 v45, v35, v72
	v_exp_f32_e32 v45, v45
	v_add_f32_e32 v32, 1.0, v33
	v_rcp_f32_e32 v42, v32
	v_add_f32_e32 v32, 1.0, v34
	v_rcp_f32_e32 v38, v32
	s_waitcnt vmcnt(4)
	v_mov_b32_e32 v32, v69
	v_mov_b32_e32 v33, v70
	v_mov_b32_e32 v69, v71
	v_mul_f32_e32 v34, v39, v72
	v_pk_add_f32 v[32:33], v[32:33], v[68:69]
	v_exp_f32_e32 v44, v34
	v_add_f32_e32 v39, v32, v33
	global_load_dwordx4 v[32:35], v[84:85], off offset:4032
	ds_bpermute_b32 v43, v142, v39
	v_add_f32_e32 v45, 1.0, v45
	v_rcp_f32_e32 v45, v45
	v_mul_f32_e32 v36, v36, v72
	v_exp_f32_e32 v36, v36
	s_waitcnt lgkmcnt(0)
	v_add_f32_e32 v39, v39, v43
	ds_bpermute_b32 v43, v143, v39
	v_add_f32_e32 v44, 1.0, v44
	v_add_f32_e32 v36, 1.0, v36
	v_rcp_f32_e32 v36, v36
	v_rcp_f32_e32 v44, v44
	s_waitcnt lgkmcnt(0)
	v_add_f32_e32 v39, v39, v43
	v_fmamk_f32 v39, v39, 0x3a800000, v132
	v_rsq_f32_e32 v43, v39
	v_cvt_pk_f16_f32 v39, v38, v45
	v_cvt_pk_f16_f32 v38, v40, v37
	v_cvt_pk_f16_f32 v37, v42, v44
	v_mul_f32_e32 v40, 0xbfb8aa3b, v43
	v_mul_f32_e32 v28, v28, v40
	v_mul_f32_e32 v24, v24, v40
	v_mul_f32_e32 v29, v29, v40
	v_mul_f32_e32 v25, v25, v40
	v_mul_f32_e32 v30, v30, v40
	v_mul_f32_e32 v26, v26, v40
	v_mul_f32_e32 v27, v27, v40
	v_mul_f32_e32 v31, v31, v40
	v_exp_f32_e32 v28, v28
	v_exp_f32_e32 v24, v24
	v_exp_f32_e32 v29, v29
	v_exp_f32_e32 v25, v25
	v_exp_f32_e32 v30, v30
	v_exp_f32_e32 v26, v26
	v_exp_f32_e32 v27, v27
	v_exp_f32_e32 v31, v31
	v_add_f32_e32 v28, 1.0, v28
	v_add_f32_e32 v24, 1.0, v24
	v_add_f32_e32 v29, 1.0, v29
	v_add_f32_e32 v25, 1.0, v25
	v_add_f32_e32 v30, 1.0, v30
	v_add_f32_e32 v26, 1.0, v26
	v_add_f32_e32 v27, 1.0, v27
	v_add_f32_e32 v31, 1.0, v31
	v_mul_f32_e32 v16, v16, v40
	v_rcp_f32_e32 v28, v28
	v_rcp_f32_e32 v24, v24
	v_rcp_f32_e32 v25, v25
	v_rcp_f32_e32 v30, v30
	v_rcp_f32_e32 v26, v26
	v_rcp_f32_e32 v27, v27
	v_rcp_f32_e32 v31, v31
	v_rcp_f32_e32 v29, v29
	v_exp_f32_e32 v16, v16
	v_mul_f32_e32 v21, v21, v40
	v_exp_f32_e32 v21, v21
	v_mul_f32_e32 v17, v17, v40
	v_exp_f32_e32 v17, v17
	v_cvt_pk_f16_f32 v36, v36, v41
	v_add_u32_e32 v41, 0x4048100, v60
	v_cvt_pk_f16_f32 v27, v26, v27
	v_cvt_pk_f16_f32 v26, v24, v25
	v_cvt_pk_f16_f32 v25, v30, v31
	v_cvt_pk_f16_f32 v24, v28, v29
	v_add_u32_e32 v28, 0x4050000, v60
	v_add_f32_e32 v16, 1.0, v16
	global_store_dwordx4 v41, v[36:39], s[44:45] sc1
	global_store_dwordx4 v28, v[24:27], s[44:45] sc1
	v_mul_f32_e32 v18, v18, v40
	v_exp_f32_e32 v18, v18
	v_rcp_f32_e32 v24, v16
	v_add_f32_e32 v16, 1.0, v21
	v_rcp_f32_e32 v21, v16
	v_add_f32_e32 v16, 1.0, v17
	v_mul_f32_e32 v17, v22, v40
	v_exp_f32_e32 v17, v17
	v_rcp_f32_e32 v22, v16
	v_mul_f32_e32 v19, v19, v40
	v_exp_f32_e32 v19, v19
	v_add_f32_e32 v16, 1.0, v17
	v_rcp_f32_e32 v25, v16
	v_add_f32_e32 v16, 1.0, v18
	v_rcp_f32_e32 v18, v16
	s_waitcnt vmcnt(2)
	v_mov_b32_e32 v16, v33
	v_mov_b32_e32 v17, v34
	v_mov_b32_e32 v33, v35
	v_pk_add_f32 v[16:17], v[16:17], v[32:33]
	v_add_f32_e32 v19, 1.0, v19
	v_add_f32_e32 v16, v16, v17
	ds_bpermute_b32 v17, v142, v16
	v_rcp_f32_e32 v19, v19
	v_mul_f32_e32 v20, v20, v40
	v_mul_f32_e32 v23, v23, v40
	v_exp_f32_e32 v20, v20
	s_waitcnt lgkmcnt(0)
	v_add_f32_e32 v16, v16, v17
	ds_bpermute_b32 v17, v143, v16
	v_cvt_pk_f16_f32 v19, v18, v19
	v_cvt_pk_f16_f32 v18, v24, v22
	v_exp_f32_e32 v23, v23
	v_add_f32_e32 v20, 1.0, v20
	s_waitcnt lgkmcnt(0)
	v_add_f32_e32 v16, v16, v17
	v_fmac_f32_e32 v132, 0x3a800000, v16
	v_rsq_f32_e32 v16, v132
	v_add_f32_e32 v23, 1.0, v23
	v_rcp_f32_e32 v20, v20
	v_rcp_f32_e32 v23, v23
	v_mul_f32_e32 v22, 0xbfb8aa3b, v16
	v_mul_f32_e32 v12, v12, v22
	v_mul_f32_e32 v8, v8, v22
	v_mul_f32_e32 v13, v13, v22
	v_mul_f32_e32 v9, v9, v22
	v_mul_f32_e32 v14, v14, v22
	v_mul_f32_e32 v10, v10, v22
	v_mul_f32_e32 v11, v11, v22
	v_mul_f32_e32 v15, v15, v22
	v_mul_f32_e32 v4, v4, v22
	v_mul_f32_e32 v0, v0, v22
	v_mul_f32_e32 v5, v5, v22
	v_mul_f32_e32 v1, v1, v22
	v_mul_f32_e32 v6, v6, v22
	v_mul_f32_e32 v2, v2, v22
	v_mul_f32_e32 v3, v3, v22
	v_mul_f32_e32 v7, v7, v22
	v_exp_f32_e32 v12, v12
	v_exp_f32_e32 v8, v8
	v_exp_f32_e32 v13, v13
	v_exp_f32_e32 v9, v9
	v_exp_f32_e32 v14, v14
	v_exp_f32_e32 v10, v10
	v_exp_f32_e32 v11, v11
	v_exp_f32_e32 v15, v15
	v_exp_f32_e32 v4, v4
	v_exp_f32_e32 v0, v0
	v_exp_f32_e32 v5, v5
	v_exp_f32_e32 v1, v1
	v_exp_f32_e32 v6, v6
	v_exp_f32_e32 v2, v2
	v_exp_f32_e32 v3, v3
	v_exp_f32_e32 v7, v7
	v_add_f32_e32 v12, 1.0, v12
	v_add_f32_e32 v8, 1.0, v8
	v_add_f32_e32 v13, 1.0, v13
	v_add_f32_e32 v9, 1.0, v9
	v_add_f32_e32 v14, 1.0, v14
	v_add_f32_e32 v10, 1.0, v10
	v_add_f32_e32 v11, 1.0, v11
	v_add_f32_e32 v15, 1.0, v15
	v_add_f32_e32 v4, 1.0, v4
	v_add_f32_e32 v0, 1.0, v0
	v_add_f32_e32 v5, 1.0, v5
	v_add_f32_e32 v1, 1.0, v1
	v_add_f32_e32 v6, 1.0, v6
	v_add_f32_e32 v2, 1.0, v2
	v_add_f32_e32 v3, 1.0, v3
	v_add_f32_e32 v7, 1.0, v7
	v_rcp_f32_e32 v12, v12
	v_rcp_f32_e32 v8, v8
	v_rcp_f32_e32 v9, v9
	v_rcp_f32_e32 v14, v14
	v_rcp_f32_e32 v10, v10
	v_rcp_f32_e32 v11, v11
	v_rcp_f32_e32 v15, v15
	v_rcp_f32_e32 v13, v13
	v_rcp_f32_e32 v4, v4
	v_rcp_f32_e32 v0, v0
	v_rcp_f32_e32 v1, v1
	v_rcp_f32_e32 v6, v6
	v_rcp_f32_e32 v2, v2
	v_rcp_f32_e32 v3, v3
	v_rcp_f32_e32 v7, v7
	v_rcp_f32_e32 v5, v5
	v_cvt_pk_f16_f32 v17, v25, v23
	v_cvt_pk_f16_f32 v16, v20, v21
	v_add_u32_e32 v20, 0x4050100, v60
	v_cvt_pk_f16_f32 v11, v10, v11
	v_cvt_pk_f16_f32 v10, v8, v9
	v_cvt_pk_f16_f32 v9, v14, v15
	v_cvt_pk_f16_f32 v8, v12, v13
	v_add_u32_e32 v12, 0x4058000, v60
	v_cvt_pk_f16_f32 v3, v2, v3
	v_cvt_pk_f16_f32 v2, v0, v1
	v_cvt_pk_f16_f32 v1, v6, v7
	v_cvt_pk_f16_f32 v0, v4, v5
	v_add_u32_e32 v4, 0x4058100, v60
	global_store_dwordx4 v20, v[16:19], s[44:45] sc1
	global_store_dwordx4 v12, v[8:11], s[44:45] sc1
	global_store_dwordx4 v4, v[0:3], s[44:45] sc1
	s_waitcnt vmcnt(0)
	s_barrier
	s_waitcnt vmcnt(0)
	s_barrier
	v_mbcnt_lo_u32_b32 v34, -1, 0
	v_mbcnt_hi_u32_b32 v34, -1, v34
	v_mov_b32_e32 v33, v129
	v_lshl_or_b32 v0, v34, 4, s66
	v_ashrrev_i32_e32 v1, 31, v0
	v_lshrrev_b32_e32 v1, 22, v1
	v_add_u32_e32 v1, v0, v1
	v_ashrrev_i32_e32 v1, 10, v1
	v_mul_i32_i24_e32 v2, 0x400, v1
	v_sub_u32_e32 v2, v0, v2
	v_lshrrev_b32_e32 v3, 4, v2
	v_bitop3_b32 v2, v3, v2, 32 bitop3:0x6c
	v_ashrrev_i32_e32 v4, 31, v2
	v_lshrrev_b32_e32 v4, 26, v4
	v_lshlrev_b32_e32 v3, 3, v1
	v_add_u32_e32 v4, v2, v4
	v_and_b32_e32 v3, -16, v3
	v_ashrrev_i32_e32 v5, 6, v4
	v_and_b32_e32 v4, 0xc0, v4
	v_add_u32_e32 v3, v5, v3
	v_sub_u32_e32 v2, v2, v4
	v_mov_b32_e32 v4, 1
	v_lshlrev_b32_e32 v1, 5, v1
	v_ashrrev_i16_sdwa v2, v4, sext(v2) dst_sel:DWORD dst_unused:UNUSED_PAD src0_sel:DWORD src1_sel:BYTE_0
	v_lshlrev_b32_e32 v6, 1, v3
	v_lshrrev_b32_e32 v7, 2, v3
	v_and_b32_e32 v5, 3, v5
	v_and_b32_e32 v1, 32, v1
	v_bfe_i32 v2, v2, 0, 16
	v_and_b32_e32 v6, 24, v6
	v_and_b32_e32 v7, 4, v7
	v_and_or_b32 v5, v3, s3, v5
	v_or3_b32 v5, v5, v7, v6
	v_add_lshl_u32 v1, v1, v2, 1
	v_add_u32_e32 v0, 0x2000, v0
	v_lshl_add_u32 v20, v3, 9, v1
	v_lshl_add_u32 v128, v5, 9, v1
	v_ashrrev_i32_e32 v1, 31, v0
	v_lshrrev_b32_e32 v1, 22, v1
	v_add_u32_e32 v1, v0, v1
	v_ashrrev_i32_e32 v1, 10, v1
	v_mul_i32_i24_e32 v2, 0x400, v1
	v_sub_u32_e32 v0, v0, v2
	v_lshrrev_b32_e32 v2, 4, v0
	v_bitop3_b32 v0, v2, v0, 32 bitop3:0x6c
	v_ashrrev_i32_e32 v3, 31, v0
	v_lshrrev_b32_e32 v3, 26, v3
	v_add_u32_e32 v3, v0, v3
	v_ashrrev_i32_e32 v5, 6, v3
	v_and_b32_e32 v3, 0xffc0, v3
	v_sub_u32_e32 v0, v0, v3
	v_lshlrev_b32_e32 v2, 3, v1
	v_lshrrev_b16_e32 v3, 7, v0
	v_and_b32_e32 v2, -16, v2
	v_and_b32_e32 v3, 1, v3
	v_add_u32_e32 v2, v5, v2
	v_add_u16_e32 v0, v0, v3
	v_lshlrev_b32_e32 v1, 5, v1
	v_ashrrev_i16_sdwa v0, v4, sext(v0) dst_sel:DWORD dst_unused:UNUSED_PAD src0_sel:DWORD src1_sel:BYTE_0
	v_lshlrev_b32_e32 v3, 1, v2
	v_lshrrev_b32_e32 v4, 2, v2
	v_and_b32_e32 v5, 3, v5
	v_and_b32_e32 v1, 32, v1
	v_bfe_i32 v0, v0, 0, 16
	v_and_b32_e32 v3, 24, v3
	v_and_b32_e32 v4, 4, v4
	v_and_or_b32 v5, v2, s3, v5
	v_or3_b32 v3, v5, v4, v3
	v_add_lshl_u32 v0, v1, v0, 1
	v_lshl_add_u32 v32, v3, 9, v0
	global_load_lds_dwordx4 v128, s[4:5]
	s_mov_b32 m0, s93
	v_lshl_add_u32 v30, v2, 9, v0
	global_load_lds_dwordx4 v32, s[4:5]
	s_mov_b32 m0, s94
	v_lshl_add_u64 v[16:17], s[4:5], 0, v[128:129]
	global_load_lds_dwordx4 v128, s[10:11]
	s_mov_b32 m0, s95
	v_lshl_add_u64 v[18:19], s[4:5], 0, v[32:33]
	global_load_lds_dwordx4 v32, s[10:11]
	s_mov_b32 m0, s61
	v_lshl_add_u64 v[0:1], v[16:17], 0, s[16:17]
	global_load_lds_dwordx4 v20, s[6:7]
	s_mov_b32 m0, s71
	v_lshl_add_u64 v[2:3], v[18:19], 0, s[16:17]
	global_load_lds_dwordx4 v30, s[6:7]
	s_mov_b32 m0, s47
	v_mov_b32_e32 v21, v129
	global_load_lds_dwordx4 v20, s[8:9]
	s_mov_b32 m0, s58
	v_mov_b32_e32 v31, v129
	global_load_lds_dwordx4 v30, s[8:9]
	s_mov_b32 m0, s89
	v_lshl_add_u64 v[28:29], s[10:11], 0, v[128:129]
	global_load_lds_dwordx4 v[0:1], off
	s_mov_b32 m0, s90
	v_lshl_add_u64 v[22:23], s[10:11], 0, v[32:33]
	global_load_lds_dwordx4 v[2:3], off
	s_mov_b32 m0, s34
	v_lshl_add_u64 v[24:25], s[6:7], 0, v[20:21]
	global_load_lds_dwordx4 v20, s[14:15]
	s_mov_b32 m0, s35
	v_lshl_add_u64 v[26:27], s[6:7], 0, v[30:31]
	global_load_lds_dwordx4 v30, s[14:15]
	s_mov_b32 m0, s91
	v_lshl_add_u64 v[14:15], s[8:9], 0, v[20:21]
	global_load_lds_dwordx4 v128, s[12:13]
	s_mov_b32 m0, s92
	v_lshl_add_u64 v[12:13], s[8:9], 0, v[30:31]
	global_load_lds_dwordx4 v32, s[12:13]
	v_lshl_add_u64 v[6:7], s[14:15], 0, v[20:21]
	v_lshl_add_u64 v[4:5], s[14:15], 0, v[30:31]
	v_lshl_add_u64 v[8:9], s[12:13], 0, v[128:129]
	s_and_b64 vcc, exec, s[0:1]
	v_lshl_add_u64 v[10:11], s[12:13], 0, v[32:33]
	s_cbranch_vccnz .LBB0_938
	s_barrier

.LBB0_1005:
	s_or_b64 exec, exec, s[34:35]
	s_lshl_b32 s3, s69, 2
	s_add_i32 s3, s3, 0
	s_add_i32 s3, s3, 0x21000
	v_lshl_add_u32 v133, v133, 2, s3
	s_lshl_b32 s3, s68, 5
	s_lshl_b32 s20, s30, 8
	s_or_b32 s21, s20, 0x80
	s_waitcnt vmcnt(0) lgkmcnt(0)
	s_barrier
	v_lshl_add_u32 v128, v132, 3, s3
	v_add_u32_e32 v130, s20, v128
	v_add_u32_e32 v128, s21, v128
	v_ashrrev_i32_e32 v131, 31, v130
	v_ashrrev_i32_e32 v129, 31, v128
	s_and_saveexec_b64 s[20:21], s[4:5]
	s_cbranch_execz .LBB0_1013
	v_readlane_b32 s80, v255, 0
	v_readlane_b32 s84, v255, 4
	v_readlane_b32 s85, v255, 5
	v_readlane_b32 s86, v255, 6
	v_readlane_b32 s87, v255, 7
	s_mov_b64 s[44:45], s[84:85]
	v_lshl_add_u64 v[146:147], v[130:131], 2, s[44:45]
	global_load_dwordx4 v[142:145], v[146:147], off
	ds_read_b32 v132, v133
	v_lshlrev_b32_e32 v134, 12, v134
	s_mov_b64 s[46:47], s[86:87]
	v_lshl_add_u32 v148, v130, 2, v134
	v_readlane_b32 s81, v255, 1
	s_waitcnt lgkmcnt(0)
	v_pk_mul_f32 v[126:127], v[126:127], v[132:133] op_sel_hi:[1,0]
	v_pk_mul_f32 v[124:125], v[124:125], v[132:133] op_sel_hi:[1,0]
	v_pk_mul_f32 v[118:119], v[118:119], v[132:133] op_sel_hi:[1,0]
	v_pk_mul_f32 v[116:117], v[116:117], v[132:133] op_sel_hi:[1,0]
	v_pk_mul_f32 v[122:123], v[122:123], v[132:133] op_sel_hi:[1,0]
	v_pk_mul_f32 v[120:121], v[120:121], v[132:133] op_sel_hi:[1,0]
	v_pk_mul_f32 v[114:115], v[114:115], v[132:133] op_sel_hi:[1,0]
	v_pk_mul_f32 v[112:113], v[112:113], v[132:133] op_sel_hi:[1,0]
	v_readlane_b32 s82, v255, 2
	v_readlane_b32 s83, v255, 3
	s_waitcnt vmcnt(0)
	v_pk_mul_f32 v[126:127], v[144:145], v[126:127]
	v_pk_mul_f32 v[124:125], v[142:143], v[124:125]
	global_store_dwordx4 v148, v[124:127], s[46:47] sc1
	global_load_dwordx4 v[124:127], v[146:147], off offset:16
	v_lshl_add_u64 v[142:143], v[128:129], 2, s[44:45]
	s_waitcnt vmcnt(0)
	v_pk_mul_f32 v[118:119], v[118:119], v[126:127]
	v_pk_mul_f32 v[116:117], v[116:117], v[124:125]
	global_store_dwordx4 v148, v[116:119], s[46:47] offset:16 sc1
	global_load_dwordx4 v[116:119], v[142:143], off
	v_lshl_add_u32 v124, v128, 2, v134
	s_waitcnt vmcnt(0)
	v_pk_mul_f32 v[118:119], v[122:123], v[118:119]
	v_pk_mul_f32 v[116:117], v[120:121], v[116:117]
	global_store_dwordx4 v124, v[116:119], s[46:47] sc1
	global_load_dwordx4 v[116:119], v[142:143], off offset:16
	s_waitcnt vmcnt(0)
	v_pk_mul_f32 v[114:115], v[114:115], v[118:119]
	v_pk_mul_f32 v[112:113], v[112:113], v[116:117]
	global_store_dwordx4 v124, v[112:115], s[46:47] offset:16 sc1
	s_or_b64 exec, exec, s[20:21]
	s_and_saveexec_b64 s[4:5], s[6:7]
	s_cbranch_execnz .LBB0_1014

.LBB0_1008:
	v_readlane_b32 s80, v255, 0
	v_readlane_b32 s84, v255, 4
	v_readlane_b32 s85, v255, 5
	v_readlane_b32 s86, v255, 6
	v_readlane_b32 s87, v255, 7
	s_mov_b64 s[44:45], s[84:85]
	v_lshl_add_u64 v[100:101], v[130:131], 2, s[44:45]
	global_load_dwordx4 v[96:99], v[100:101], off
	ds_read_b32 v102, v133 offset:128
	v_lshlrev_b32_e32 v103, 12, v136
	s_mov_b64 s[46:47], s[86:87]
	v_lshl_add_u32 v104, v130, 2, v103
	v_readlane_b32 s81, v255, 1
	s_waitcnt lgkmcnt(0)
	v_pk_mul_f32 v[94:95], v[94:95], v[102:103] op_sel_hi:[1,0]
	v_pk_mul_f32 v[92:93], v[92:93], v[102:103] op_sel_hi:[1,0]
	v_pk_mul_f32 v[86:87], v[86:87], v[102:103] op_sel_hi:[1,0]
	v_pk_mul_f32 v[84:85], v[84:85], v[102:103] op_sel_hi:[1,0]
	v_pk_mul_f32 v[90:91], v[90:91], v[102:103] op_sel_hi:[1,0]
	v_pk_mul_f32 v[88:89], v[88:89], v[102:103] op_sel_hi:[1,0]
	v_pk_mul_f32 v[82:83], v[82:83], v[102:103] op_sel_hi:[1,0]
	v_pk_mul_f32 v[80:81], v[80:81], v[102:103] op_sel_hi:[1,0]
	v_readlane_b32 s82, v255, 2
	v_readlane_b32 s83, v255, 3
	s_waitcnt vmcnt(0)
	v_pk_mul_f32 v[94:95], v[98:99], v[94:95]
	v_pk_mul_f32 v[92:93], v[96:97], v[92:93]
	global_store_dwordx4 v104, v[92:95], s[46:47] sc1
	global_load_dwordx4 v[92:95], v[100:101], off offset:16
	v_lshl_add_u64 v[96:97], v[128:129], 2, s[44:45]
	s_waitcnt vmcnt(0)
	v_pk_mul_f32 v[86:87], v[86:87], v[94:95]
	v_pk_mul_f32 v[84:85], v[84:85], v[92:93]
	global_store_dwordx4 v104, v[84:87], s[46:47] offset:16 sc1
	global_load_dwordx4 v[84:87], v[96:97], off
	v_lshl_add_u32 v92, v128, 2, v103
	s_waitcnt vmcnt(0)
	v_pk_mul_f32 v[86:87], v[90:91], v[86:87]
	v_pk_mul_f32 v[84:85], v[88:89], v[84:85]
	global_store_dwordx4 v92, v[84:87], s[46:47] sc1
	global_load_dwordx4 v[84:87], v[96:97], off offset:16
	s_waitcnt vmcnt(0)
	v_pk_mul_f32 v[82:83], v[82:83], v[86:87]
	v_pk_mul_f32 v[80:81], v[80:81], v[84:85]
	global_store_dwordx4 v92, v[80:83], s[46:47] offset:16 sc1
	s_or_b64 exec, exec, s[4:5]
	s_and_saveexec_b64 s[4:5], s[10:11]
	s_cbranch_execnz .LBB0_1016

.LBB0_1010:
	v_readlane_b32 s80, v255, 0
	v_readlane_b32 s84, v255, 4
	v_readlane_b32 s85, v255, 5
	v_readlane_b32 s86, v255, 6
	v_readlane_b32 s87, v255, 7
	s_mov_b64 s[8:9], s[84:85]
	v_lshl_add_u64 v[68:69], v[130:131], 2, s[8:9]
	global_load_dwordx4 v[64:67], v[68:69], off
	ds_read_b32 v70, v133 offset:512
	v_lshlrev_b32_e32 v71, 12, v138
	s_mov_b64 s[10:11], s[86:87]
	v_lshl_add_u32 v72, v130, 2, v71
	v_readlane_b32 s81, v255, 1
	s_waitcnt lgkmcnt(0)
	v_pk_mul_f32 v[62:63], v[62:63], v[70:71] op_sel_hi:[1,0]
	v_pk_mul_f32 v[60:61], v[60:61], v[70:71] op_sel_hi:[1,0]
	v_pk_mul_f32 v[54:55], v[54:55], v[70:71] op_sel_hi:[1,0]
	v_pk_mul_f32 v[52:53], v[52:53], v[70:71] op_sel_hi:[1,0]
	v_pk_mul_f32 v[58:59], v[58:59], v[70:71] op_sel_hi:[1,0]
	v_pk_mul_f32 v[56:57], v[56:57], v[70:71] op_sel_hi:[1,0]
	v_pk_mul_f32 v[50:51], v[50:51], v[70:71] op_sel_hi:[1,0]
	v_pk_mul_f32 v[48:49], v[48:49], v[70:71] op_sel_hi:[1,0]
	v_readlane_b32 s82, v255, 2
	v_readlane_b32 s83, v255, 3
	s_waitcnt vmcnt(0)
	v_pk_mul_f32 v[62:63], v[66:67], v[62:63]
	v_pk_mul_f32 v[60:61], v[64:65], v[60:61]
	global_store_dwordx4 v72, v[60:63], s[10:11] sc1
	global_load_dwordx4 v[60:63], v[68:69], off offset:16
	v_lshl_add_u64 v[64:65], v[128:129], 2, s[8:9]
	s_waitcnt vmcnt(0)
	v_pk_mul_f32 v[54:55], v[54:55], v[62:63]
	v_pk_mul_f32 v[52:53], v[52:53], v[60:61]
	global_store_dwordx4 v72, v[52:55], s[10:11] offset:16 sc1
	global_load_dwordx4 v[52:55], v[64:65], off
	v_lshl_add_u32 v60, v128, 2, v71
	s_waitcnt vmcnt(0)
	v_pk_mul_f32 v[54:55], v[58:59], v[54:55]
	v_pk_mul_f32 v[52:53], v[56:57], v[52:53]
	global_store_dwordx4 v60, v[52:55], s[10:11] sc1
	global_load_dwordx4 v[52:55], v[64:65], off offset:16
	s_waitcnt vmcnt(0)
	v_pk_mul_f32 v[50:51], v[50:51], v[54:55]
	v_pk_mul_f32 v[48:49], v[48:49], v[52:53]
	global_store_dwordx4 v60, v[48:51], s[10:11] offset:16 sc1
	s_or_b64 exec, exec, s[4:5]
	s_and_saveexec_b64 s[4:5], s[14:15]
	s_cbranch_execnz .LBB0_1018

.LBB0_1012:
	v_readlane_b32 s8, v255, 0
	v_readlane_b32 s9, v255, 1
	v_readlane_b32 s10, v255, 2
	v_readlane_b32 s11, v255, 3
	v_readlane_b32 s12, v255, 4
	v_readlane_b32 s13, v255, 5
	v_readlane_b32 s14, v255, 6
	v_readlane_b32 s15, v255, 7
	s_mov_b64 s[8:9], s[12:13]
	v_lshl_add_u64 v[36:37], v[130:131], 2, s[8:9]
	global_load_dwordx4 v[32:35], v[36:37], off
	ds_read_b32 v38, v133 offset:640
	v_lshlrev_b32_e32 v39, 12, v140
	s_mov_b64 s[10:11], s[14:15]
	v_lshl_add_u32 v40, v130, 2, v39
	s_waitcnt lgkmcnt(0)
	v_pk_mul_f32 v[30:31], v[30:31], v[38:39] op_sel_hi:[1,0]
	v_pk_mul_f32 v[28:29], v[28:29], v[38:39] op_sel_hi:[1,0]
	v_pk_mul_f32 v[22:23], v[22:23], v[38:39] op_sel_hi:[1,0]
	v_pk_mul_f32 v[20:21], v[20:21], v[38:39] op_sel_hi:[1,0]
	v_pk_mul_f32 v[26:27], v[26:27], v[38:39] op_sel_hi:[1,0]
	v_pk_mul_f32 v[24:25], v[24:25], v[38:39] op_sel_hi:[1,0]
	v_pk_mul_f32 v[18:19], v[18:19], v[38:39] op_sel_hi:[1,0]
	v_pk_mul_f32 v[16:17], v[16:17], v[38:39] op_sel_hi:[1,0]
	s_waitcnt vmcnt(0)
	v_pk_mul_f32 v[30:31], v[34:35], v[30:31]
	v_pk_mul_f32 v[28:29], v[32:33], v[28:29]
	global_store_dwordx4 v40, v[28:31], s[10:11] sc1
	global_load_dwordx4 v[28:31], v[36:37], off offset:16
	v_lshl_add_u64 v[32:33], v[128:129], 2, s[8:9]
	s_waitcnt vmcnt(0)
	v_pk_mul_f32 v[22:23], v[22:23], v[30:31]
	v_pk_mul_f32 v[20:21], v[20:21], v[28:29]
	global_store_dwordx4 v40, v[20:23], s[10:11] offset:16 sc1
	global_load_dwordx4 v[20:23], v[32:33], off
	v_lshl_add_u32 v28, v128, 2, v39
	s_waitcnt vmcnt(0)
	v_pk_mul_f32 v[22:23], v[26:27], v[22:23]
	v_pk_mul_f32 v[20:21], v[24:25], v[20:21]
	global_store_dwordx4 v28, v[20:23], s[10:11] sc1
	global_load_dwordx4 v[20:23], v[32:33], off offset:16
	s_waitcnt vmcnt(0)
	v_pk_mul_f32 v[18:19], v[18:19], v[22:23]
	v_pk_mul_f32 v[16:17], v[16:17], v[20:21]
	global_store_dwordx4 v28, v[16:19], s[10:11] offset:16 sc1
	s_or_b64 exec, exec, s[4:5]
	s_and_saveexec_b64 s[4:5], s[18:19]
	s_cbranch_execnz .LBB0_1020
	s_branch .LBB0_1021

.LBB0_1014:
	v_readlane_b32 s80, v255, 0
	v_readlane_b32 s84, v255, 4
	v_readlane_b32 s85, v255, 5
	v_readlane_b32 s86, v255, 6
	v_readlane_b32 s87, v255, 7
	s_mov_b64 s[44:45], s[84:85]
	v_lshl_add_u64 v[116:117], v[130:131], 2, s[44:45]
	global_load_dwordx4 v[112:115], v[116:117], off
	ds_read_b32 v118, v133 offset:64
	v_lshlrev_b32_e32 v119, 12, v135
	s_mov_b64 s[46:47], s[86:87]
	v_lshl_add_u32 v120, v130, 2, v119
	v_readlane_b32 s81, v255, 1
	s_waitcnt lgkmcnt(0)
	v_pk_mul_f32 v[110:111], v[110:111], v[118:119] op_sel_hi:[1,0]
	v_pk_mul_f32 v[108:109], v[108:109], v[118:119] op_sel_hi:[1,0]
	v_pk_mul_f32 v[102:103], v[102:103], v[118:119] op_sel_hi:[1,0]
	v_pk_mul_f32 v[100:101], v[100:101], v[118:119] op_sel_hi:[1,0]
	v_pk_mul_f32 v[106:107], v[106:107], v[118:119] op_sel_hi:[1,0]
	v_pk_mul_f32 v[104:105], v[104:105], v[118:119] op_sel_hi:[1,0]
	v_pk_mul_f32 v[98:99], v[98:99], v[118:119] op_sel_hi:[1,0]
	v_pk_mul_f32 v[96:97], v[96:97], v[118:119] op_sel_hi:[1,0]
	v_readlane_b32 s82, v255, 2
	v_readlane_b32 s83, v255, 3
	s_waitcnt vmcnt(0)
	v_pk_mul_f32 v[110:111], v[114:115], v[110:111]
	v_pk_mul_f32 v[108:109], v[112:113], v[108:109]
	global_store_dwordx4 v120, v[108:111], s[46:47] sc1
	global_load_dwordx4 v[108:111], v[116:117], off offset:16
	v_lshl_add_u64 v[112:113], v[128:129], 2, s[44:45]
	s_waitcnt vmcnt(0)
	v_pk_mul_f32 v[102:103], v[102:103], v[110:111]
	v_pk_mul_f32 v[100:101], v[100:101], v[108:109]
	global_store_dwordx4 v120, v[100:103], s[46:47] offset:16 sc1
	global_load_dwordx4 v[100:103], v[112:113], off
	v_lshl_add_u32 v108, v128, 2, v119
	s_waitcnt vmcnt(0)
	v_pk_mul_f32 v[102:103], v[106:107], v[102:103]
	v_pk_mul_f32 v[100:101], v[104:105], v[100:101]
	global_store_dwordx4 v108, v[100:103], s[46:47] sc1
	global_load_dwordx4 v[100:103], v[112:113], off offset:16
	s_waitcnt vmcnt(0)
	v_pk_mul_f32 v[98:99], v[98:99], v[102:103]
	v_pk_mul_f32 v[96:97], v[96:97], v[100:101]
	global_store_dwordx4 v108, v[96:99], s[46:47] offset:16 sc1
	s_or_b64 exec, exec, s[4:5]
	s_and_saveexec_b64 s[4:5], s[8:9]
	s_cbranch_execnz .LBB0_1008

.LBB0_1016:
	v_readlane_b32 s80, v255, 0
	v_readlane_b32 s84, v255, 4
	v_readlane_b32 s85, v255, 5
	v_readlane_b32 s86, v255, 6
	v_readlane_b32 s87, v255, 7
	s_mov_b64 s[8:9], s[84:85]
	v_lshl_add_u64 v[84:85], v[130:131], 2, s[8:9]
	global_load_dwordx4 v[80:83], v[84:85], off
	ds_read_b32 v86, v133 offset:192
	v_lshlrev_b32_e32 v87, 12, v137
	s_mov_b64 s[10:11], s[86:87]
	v_lshl_add_u32 v88, v130, 2, v87
	v_readlane_b32 s81, v255, 1
	s_waitcnt lgkmcnt(0)
	v_pk_mul_f32 v[78:79], v[78:79], v[86:87] op_sel_hi:[1,0]
	v_pk_mul_f32 v[76:77], v[76:77], v[86:87] op_sel_hi:[1,0]
	v_pk_mul_f32 v[70:71], v[70:71], v[86:87] op_sel_hi:[1,0]
	v_pk_mul_f32 v[68:69], v[68:69], v[86:87] op_sel_hi:[1,0]
	v_pk_mul_f32 v[74:75], v[74:75], v[86:87] op_sel_hi:[1,0]
	v_pk_mul_f32 v[72:73], v[72:73], v[86:87] op_sel_hi:[1,0]
	v_pk_mul_f32 v[66:67], v[66:67], v[86:87] op_sel_hi:[1,0]
	v_pk_mul_f32 v[64:65], v[64:65], v[86:87] op_sel_hi:[1,0]
	v_readlane_b32 s82, v255, 2
	v_readlane_b32 s83, v255, 3
	s_waitcnt vmcnt(0)
	v_pk_mul_f32 v[78:79], v[82:83], v[78:79]
	v_pk_mul_f32 v[76:77], v[80:81], v[76:77]
	global_store_dwordx4 v88, v[76:79], s[10:11] sc1
	global_load_dwordx4 v[76:79], v[84:85], off offset:16
	v_lshl_add_u64 v[80:81], v[128:129], 2, s[8:9]
	s_waitcnt vmcnt(0)
	v_pk_mul_f32 v[70:71], v[70:71], v[78:79]
	v_pk_mul_f32 v[68:69], v[68:69], v[76:77]
	global_store_dwordx4 v88, v[68:71], s[10:11] offset:16 sc1
	global_load_dwordx4 v[68:71], v[80:81], off
	v_lshl_add_u32 v76, v128, 2, v87
	s_waitcnt vmcnt(0)
	v_pk_mul_f32 v[70:71], v[74:75], v[70:71]
	v_pk_mul_f32 v[68:69], v[72:73], v[68:69]
	global_store_dwordx4 v76, v[68:71], s[10:11] sc1
	global_load_dwordx4 v[68:71], v[80:81], off offset:16
	s_waitcnt vmcnt(0)
	v_pk_mul_f32 v[66:67], v[66:67], v[70:71]
	v_pk_mul_f32 v[64:65], v[64:65], v[68:69]
	global_store_dwordx4 v76, v[64:67], s[10:11] offset:16 sc1
	s_or_b64 exec, exec, s[4:5]
	s_and_saveexec_b64 s[4:5], s[12:13]
	s_cbranch_execnz .LBB0_1010

.LBB0_1018:
	v_readlane_b32 s8, v255, 0
	v_readlane_b32 s9, v255, 1
	v_readlane_b32 s10, v255, 2
	v_readlane_b32 s11, v255, 3
	v_readlane_b32 s12, v255, 4
	v_readlane_b32 s13, v255, 5
	v_readlane_b32 s14, v255, 6
	v_readlane_b32 s15, v255, 7
	s_mov_b64 s[8:9], s[12:13]
	v_lshl_add_u64 v[52:53], v[130:131], 2, s[8:9]
	global_load_dwordx4 v[48:51], v[52:53], off
	ds_read_b32 v54, v133 offset:576
	v_lshlrev_b32_e32 v55, 12, v139
	s_mov_b64 s[10:11], s[14:15]
	v_lshl_add_u32 v56, v130, 2, v55
	s_waitcnt lgkmcnt(0)
	v_pk_mul_f32 v[46:47], v[46:47], v[54:55] op_sel_hi:[1,0]
	v_pk_mul_f32 v[44:45], v[44:45], v[54:55] op_sel_hi:[1,0]
	v_pk_mul_f32 v[38:39], v[38:39], v[54:55] op_sel_hi:[1,0]
	v_pk_mul_f32 v[36:37], v[36:37], v[54:55] op_sel_hi:[1,0]
	v_pk_mul_f32 v[42:43], v[42:43], v[54:55] op_sel_hi:[1,0]
	v_pk_mul_f32 v[40:41], v[40:41], v[54:55] op_sel_hi:[1,0]
	v_pk_mul_f32 v[34:35], v[34:35], v[54:55] op_sel_hi:[1,0]
	v_pk_mul_f32 v[32:33], v[32:33], v[54:55] op_sel_hi:[1,0]
	s_waitcnt vmcnt(0)
	v_pk_mul_f32 v[46:47], v[50:51], v[46:47]
	v_pk_mul_f32 v[44:45], v[48:49], v[44:45]
	global_store_dwordx4 v56, v[44:47], s[10:11] sc1
	global_load_dwordx4 v[44:47], v[52:53], off offset:16
	v_lshl_add_u64 v[48:49], v[128:129], 2, s[8:9]
	s_waitcnt vmcnt(0)
	v_pk_mul_f32 v[38:39], v[38:39], v[46:47]
	v_pk_mul_f32 v[36:37], v[36:37], v[44:45]
	global_store_dwordx4 v56, v[36:39], s[10:11] offset:16 sc1
	global_load_dwordx4 v[36:39], v[48:49], off
	v_lshl_add_u32 v44, v128, 2, v55
	s_waitcnt vmcnt(0)
	v_pk_mul_f32 v[38:39], v[42:43], v[38:39]
	v_pk_mul_f32 v[36:37], v[40:41], v[36:37]
	global_store_dwordx4 v44, v[36:39], s[10:11] sc1
	global_load_dwordx4 v[36:39], v[48:49], off offset:16
	s_waitcnt vmcnt(0)
	v_pk_mul_f32 v[34:35], v[34:35], v[38:39]
	v_pk_mul_f32 v[32:33], v[32:33], v[36:37]
	global_store_dwordx4 v44, v[32:35], s[10:11] offset:16 sc1
	s_or_b64 exec, exec, s[4:5]
	s_and_saveexec_b64 s[4:5], s[16:17]
	s_cbranch_execnz .LBB0_1012

.LBB0_1020:
	v_readlane_b32 s8, v255, 0
	v_readlane_b32 s9, v255, 1
	v_readlane_b32 s10, v255, 2
	v_readlane_b32 s11, v255, 3
	v_readlane_b32 s12, v255, 4
	v_readlane_b32 s13, v255, 5
	v_readlane_b32 s14, v255, 6
	v_readlane_b32 s15, v255, 7
	s_mov_b64 s[8:9], s[12:13]
	v_lshl_add_u64 v[20:21], v[130:131], 2, s[8:9]
	global_load_dwordx4 v[16:19], v[20:21], off
	ds_read_b32 v22, v133 offset:704
	v_lshlrev_b32_e32 v23, 12, v141
	s_mov_b64 s[10:11], s[14:15]
	v_lshl_add_u32 v24, v130, 2, v23
	s_waitcnt lgkmcnt(0)
	v_pk_mul_f32 v[14:15], v[14:15], v[22:23] op_sel_hi:[1,0]
	v_pk_mul_f32 v[12:13], v[12:13], v[22:23] op_sel_hi:[1,0]
	v_pk_mul_f32 v[6:7], v[6:7], v[22:23] op_sel_hi:[1,0]
	v_pk_mul_f32 v[4:5], v[4:5], v[22:23] op_sel_hi:[1,0]
	v_pk_mul_f32 v[10:11], v[10:11], v[22:23] op_sel_hi:[1,0]
	v_pk_mul_f32 v[8:9], v[8:9], v[22:23] op_sel_hi:[1,0]
	v_pk_mul_f32 v[2:3], v[2:3], v[22:23] op_sel_hi:[1,0]
	v_pk_mul_f32 v[0:1], v[0:1], v[22:23] op_sel_hi:[1,0]
	s_waitcnt vmcnt(0)
	v_pk_mul_f32 v[14:15], v[18:19], v[14:15]
	v_pk_mul_f32 v[12:13], v[16:17], v[12:13]
	global_store_dwordx4 v24, v[12:15], s[10:11] sc1
	global_load_dwordx4 v[12:15], v[20:21], off offset:16
	v_lshl_add_u64 v[16:17], v[128:129], 2, s[8:9]
	s_waitcnt vmcnt(0)
	v_pk_mul_f32 v[6:7], v[6:7], v[14:15]
	v_pk_mul_f32 v[4:5], v[4:5], v[12:13]
	global_store_dwordx4 v24, v[4:7], s[10:11] offset:16 sc1
	global_load_dwordx4 v[4:7], v[16:17], off
	v_lshl_add_u32 v12, v128, 2, v23
	s_waitcnt vmcnt(0)
	v_pk_mul_f32 v[6:7], v[10:11], v[6:7]
	v_pk_mul_f32 v[4:5], v[8:9], v[4:5]
	global_store_dwordx4 v12, v[4:7], s[10:11] sc1
	global_load_dwordx4 v[4:7], v[16:17], off offset:16
	s_waitcnt vmcnt(0)
	v_pk_mul_f32 v[2:3], v[2:3], v[6:7]
	v_pk_mul_f32 v[0:1], v[0:1], v[4:5]
	global_store_dwordx4 v12, v[0:3], s[10:11] offset:16 sc1

.LBB0_1050:
	s_andn2_b64 vcc, exec, s[4:5]
	s_cbranch_vccnz .LBB0_1052
	global_load_dwordx4 v[156:159], v[142:143], off
	s_waitcnt vmcnt(0)
	v_cvt_f32_f16_e32 v160, v157
	v_cvt_f32_f16_sdwa v161, v157 dst_sel:DWORD dst_unused:UNUSED_PAD src0_sel:WORD_1
	v_cvt_f32_f16_e32 v162, v156
	v_cvt_f32_f16_sdwa v163, v156 dst_sel:DWORD dst_unused:UNUSED_PAD src0_sel:WORD_1
	v_cvt_f32_f16_e32 v156, v159
	v_cvt_f32_f16_e32 v164, v158
	v_cvt_f32_f16_sdwa v165, v158 dst_sel:DWORD dst_unused:UNUSED_PAD src0_sel:WORD_1
	v_cvt_f32_f16_sdwa v157, v159 dst_sel:DWORD dst_unused:UNUSED_PAD src0_sel:WORD_1
	v_pk_mul_f32 v[162:163], v[124:125], v[162:163]
	v_pk_mul_f32 v[160:161], v[126:127], v[160:161]
	v_pk_mul_f32 v[164:165], v[120:121], v[164:165]
	v_pk_mul_f32 v[156:157], v[122:123], v[156:157]
	v_cvt_pk_f16_f32 v158, v164, v165
	v_cvt_pk_f16_f32 v159, v156, v157
	v_cvt_pk_f16_f32 v157, v160, v161
	v_cvt_pk_f16_f32 v156, v162, v163
	global_store_dwordx4 v[142:143], v[156:159], off sc1

.LBB0_1053:
	s_andn2_b64 vcc, exec, s[4:5]
	s_cbranch_vccnz .LBB0_1055
	v_mul_f32_e32 v124, 0xbfb8aa3b, v124
	v_mul_f32_e32 v120, 0xbfb8aa3b, v120
	v_mul_f32_e32 v125, 0xbfb8aa3b, v125
	v_mul_f32_e32 v121, 0xbfb8aa3b, v121
	v_mul_f32_e32 v126, 0xbfb8aa3b, v126
	v_mul_f32_e32 v122, 0xbfb8aa3b, v122
	v_mul_f32_e32 v123, 0xbfb8aa3b, v123
	v_mul_f32_e32 v127, 0xbfb8aa3b, v127
	v_exp_f32_e32 v124, v124
	v_exp_f32_e32 v120, v120
	v_exp_f32_e32 v125, v125
	v_exp_f32_e32 v121, v121
	v_exp_f32_e32 v126, v126
	v_exp_f32_e32 v122, v122
	v_exp_f32_e32 v123, v123
	v_exp_f32_e32 v127, v127
	v_add_f32_e32 v124, 1.0, v124
	v_add_f32_e32 v120, 1.0, v120
	v_add_f32_e32 v125, 1.0, v125
	v_add_f32_e32 v121, 1.0, v121
	v_add_f32_e32 v126, 1.0, v126
	v_add_f32_e32 v122, 1.0, v122
	v_add_f32_e32 v123, 1.0, v123
	v_add_f32_e32 v127, 1.0, v127
	v_rcp_f32_e32 v124, v124
	v_rcp_f32_e32 v120, v120
	v_rcp_f32_e32 v121, v121
	v_rcp_f32_e32 v126, v126
	v_rcp_f32_e32 v122, v122
	v_rcp_f32_e32 v123, v123
	v_rcp_f32_e32 v127, v127
	v_rcp_f32_e32 v125, v125
	s_cmp_eq_u32 s63, 0
	v_cvt_pk_f16_f32 v123, v122, v123
	v_cvt_pk_f16_f32 v122, v120, v121
	v_cvt_pk_f16_f32 v121, v126, v127
	v_cvt_pk_f16_f32 v120, v124, v125
	s_cselect_b32 s5, s43, s45
	s_cselect_b32 s4, s42, s44
	global_store_dwordx4 v136, v[120:123], s[4:5] sc1

.LBB0_1058:
	s_andn2_b64 vcc, exec, s[34:35]
	s_cbranch_vccnz .LBB0_1060
	global_load_dwordx4 v[120:123], v136, s[44:45] offset:256
	s_waitcnt vmcnt(0)
	v_cvt_f32_f16_e32 v124, v121
	v_cvt_f32_f16_sdwa v125, v121 dst_sel:DWORD dst_unused:UNUSED_PAD src0_sel:WORD_1
	v_cvt_f32_f16_e32 v126, v120
	v_cvt_f32_f16_sdwa v127, v120 dst_sel:DWORD dst_unused:UNUSED_PAD src0_sel:WORD_1
	v_cvt_f32_f16_e32 v120, v123
	v_cvt_f32_f16_e32 v142, v122
	v_cvt_f32_f16_sdwa v143, v122 dst_sel:DWORD dst_unused:UNUSED_PAD src0_sel:WORD_1
	v_cvt_f32_f16_sdwa v121, v123 dst_sel:DWORD dst_unused:UNUSED_PAD src0_sel:WORD_1
	v_pk_mul_f32 v[126:127], v[116:117], v[126:127]
	v_pk_mul_f32 v[124:125], v[118:119], v[124:125]
	v_pk_mul_f32 v[142:143], v[112:113], v[142:143]
	v_pk_mul_f32 v[120:121], v[114:115], v[120:121]
	v_cvt_pk_f16_f32 v122, v142, v143
	v_cvt_pk_f16_f32 v123, v120, v121
	v_cvt_pk_f16_f32 v121, v124, v125
	v_cvt_pk_f16_f32 v120, v126, v127
	global_store_dwordx4 v136, v[120:123], s[44:45] offset:256 sc1

.LBB0_1064:
	s_andn2_b64 vcc, exec, s[34:35]
	s_cbranch_vccnz .LBB0_1066
	global_load_dwordx4 v[114:117], v[112:113], off
	s_waitcnt vmcnt(0)
	v_cvt_f32_f16_e32 v118, v115
	v_cvt_f32_f16_sdwa v119, v115 dst_sel:DWORD dst_unused:UNUSED_PAD src0_sel:WORD_1
	v_cvt_f32_f16_e32 v120, v114
	v_cvt_f32_f16_sdwa v121, v114 dst_sel:DWORD dst_unused:UNUSED_PAD src0_sel:WORD_1
	v_cvt_f32_f16_e32 v114, v117
	v_cvt_f32_f16_e32 v122, v116
	v_cvt_f32_f16_sdwa v123, v116 dst_sel:DWORD dst_unused:UNUSED_PAD src0_sel:WORD_1
	v_cvt_f32_f16_sdwa v115, v117 dst_sel:DWORD dst_unused:UNUSED_PAD src0_sel:WORD_1
	v_pk_mul_f32 v[120:121], v[108:109], v[120:121]
	v_pk_mul_f32 v[118:119], v[110:111], v[118:119]
	v_pk_mul_f32 v[122:123], v[104:105], v[122:123]
	v_pk_mul_f32 v[114:115], v[106:107], v[114:115]
	v_cvt_pk_f16_f32 v116, v122, v123
	v_cvt_pk_f16_f32 v117, v114, v115
	v_cvt_pk_f16_f32 v115, v118, v119
	v_cvt_pk_f16_f32 v114, v120, v121
	global_store_dwordx4 v[112:113], v[114:117], off sc1

.LBB0_1070:
	s_andn2_b64 vcc, exec, s[34:35]
	s_cbranch_vccnz .LBB0_1072
	global_load_dwordx4 v[104:107], v136, s[44:45] offset:256
	s_waitcnt vmcnt(0)
	v_cvt_f32_f16_e32 v108, v105
	v_cvt_f32_f16_sdwa v109, v105 dst_sel:DWORD dst_unused:UNUSED_PAD src0_sel:WORD_1
	v_cvt_f32_f16_e32 v110, v104
	v_cvt_f32_f16_sdwa v111, v104 dst_sel:DWORD dst_unused:UNUSED_PAD src0_sel:WORD_1
	v_cvt_f32_f16_e32 v104, v107
	v_cvt_f32_f16_e32 v112, v106
	v_cvt_f32_f16_sdwa v113, v106 dst_sel:DWORD dst_unused:UNUSED_PAD src0_sel:WORD_1
	v_cvt_f32_f16_sdwa v105, v107 dst_sel:DWORD dst_unused:UNUSED_PAD src0_sel:WORD_1
	v_pk_mul_f32 v[110:111], v[100:101], v[110:111]
	v_pk_mul_f32 v[108:109], v[102:103], v[108:109]
	v_pk_mul_f32 v[112:113], v[96:97], v[112:113]
	v_pk_mul_f32 v[104:105], v[98:99], v[104:105]
	v_cvt_pk_f16_f32 v106, v112, v113
	v_cvt_pk_f16_f32 v107, v104, v105
	v_cvt_pk_f16_f32 v105, v108, v109
	v_cvt_pk_f16_f32 v104, v110, v111
	global_store_dwordx4 v136, v[104:107], s[44:45] offset:256 sc1

.LBB0_1076:
	s_andn2_b64 vcc, exec, s[34:35]
	s_cbranch_vccnz .LBB0_1078
	global_load_dwordx4 v[98:101], v[96:97], off
	s_waitcnt vmcnt(0)
	v_cvt_f32_f16_e32 v102, v99
	v_cvt_f32_f16_sdwa v103, v99 dst_sel:DWORD dst_unused:UNUSED_PAD src0_sel:WORD_1
	v_cvt_f32_f16_e32 v104, v98
	v_cvt_f32_f16_sdwa v105, v98 dst_sel:DWORD dst_unused:UNUSED_PAD src0_sel:WORD_1
	v_cvt_f32_f16_e32 v98, v101
	v_cvt_f32_f16_e32 v106, v100
	v_cvt_f32_f16_sdwa v107, v100 dst_sel:DWORD dst_unused:UNUSED_PAD src0_sel:WORD_1
	v_cvt_f32_f16_sdwa v99, v101 dst_sel:DWORD dst_unused:UNUSED_PAD src0_sel:WORD_1
	v_pk_mul_f32 v[104:105], v[92:93], v[104:105]
	v_pk_mul_f32 v[102:103], v[94:95], v[102:103]
	v_pk_mul_f32 v[106:107], v[88:89], v[106:107]
	v_pk_mul_f32 v[98:99], v[90:91], v[98:99]
	v_cvt_pk_f16_f32 v100, v106, v107
	v_cvt_pk_f16_f32 v101, v98, v99
	v_cvt_pk_f16_f32 v99, v102, v103
	v_cvt_pk_f16_f32 v98, v104, v105
	global_store_dwordx4 v[96:97], v[98:101], off sc1

.LBB0_1082:
	s_andn2_b64 vcc, exec, s[34:35]
	s_cbranch_vccnz .LBB0_1084
	global_load_dwordx4 v[88:91], v136, s[44:45] offset:256
	s_waitcnt vmcnt(0)
	v_cvt_f32_f16_e32 v92, v89
	v_cvt_f32_f16_sdwa v93, v89 dst_sel:DWORD dst_unused:UNUSED_PAD src0_sel:WORD_1
	v_cvt_f32_f16_e32 v94, v88
	v_cvt_f32_f16_sdwa v95, v88 dst_sel:DWORD dst_unused:UNUSED_PAD src0_sel:WORD_1
	v_cvt_f32_f16_e32 v88, v91
	v_cvt_f32_f16_e32 v96, v90
	v_cvt_f32_f16_sdwa v97, v90 dst_sel:DWORD dst_unused:UNUSED_PAD src0_sel:WORD_1
	v_cvt_f32_f16_sdwa v89, v91 dst_sel:DWORD dst_unused:UNUSED_PAD src0_sel:WORD_1
	v_pk_mul_f32 v[94:95], v[84:85], v[94:95]
	v_pk_mul_f32 v[92:93], v[86:87], v[92:93]
	v_pk_mul_f32 v[96:97], v[80:81], v[96:97]
	v_pk_mul_f32 v[88:89], v[82:83], v[88:89]
	v_cvt_pk_f16_f32 v90, v96, v97
	v_cvt_pk_f16_f32 v91, v88, v89
	v_cvt_pk_f16_f32 v89, v92, v93
	v_cvt_pk_f16_f32 v88, v94, v95
	global_store_dwordx4 v136, v[88:91], s[44:45] offset:256 sc1

.LBB0_1088:
	s_andn2_b64 vcc, exec, s[34:35]
	s_cbranch_vccnz .LBB0_1090
	global_load_dwordx4 v[82:85], v[80:81], off
	s_waitcnt vmcnt(0)
	v_cvt_f32_f16_e32 v86, v83
	v_cvt_f32_f16_sdwa v87, v83 dst_sel:DWORD dst_unused:UNUSED_PAD src0_sel:WORD_1
	v_cvt_f32_f16_e32 v88, v82
	v_cvt_f32_f16_sdwa v89, v82 dst_sel:DWORD dst_unused:UNUSED_PAD src0_sel:WORD_1
	v_cvt_f32_f16_e32 v82, v85
	v_cvt_f32_f16_e32 v90, v84
	v_cvt_f32_f16_sdwa v91, v84 dst_sel:DWORD dst_unused:UNUSED_PAD src0_sel:WORD_1
	v_cvt_f32_f16_sdwa v83, v85 dst_sel:DWORD dst_unused:UNUSED_PAD src0_sel:WORD_1
	v_pk_mul_f32 v[88:89], v[76:77], v[88:89]
	v_pk_mul_f32 v[86:87], v[78:79], v[86:87]
	v_pk_mul_f32 v[90:91], v[72:73], v[90:91]
	v_pk_mul_f32 v[82:83], v[74:75], v[82:83]
	v_cvt_pk_f16_f32 v84, v90, v91
	v_cvt_pk_f16_f32 v85, v82, v83
	v_cvt_pk_f16_f32 v83, v86, v87
	v_cvt_pk_f16_f32 v82, v88, v89
	global_store_dwordx4 v[80:81], v[82:85], off sc1

.LBB0_1094:
	s_andn2_b64 vcc, exec, s[34:35]
	s_cbranch_vccnz .LBB0_1096
	global_load_dwordx4 v[72:75], v136, s[44:45] offset:256
	s_waitcnt vmcnt(0)
	v_cvt_f32_f16_e32 v76, v73
	v_cvt_f32_f16_sdwa v77, v73 dst_sel:DWORD dst_unused:UNUSED_PAD src0_sel:WORD_1
	v_cvt_f32_f16_e32 v78, v72
	v_cvt_f32_f16_sdwa v79, v72 dst_sel:DWORD dst_unused:UNUSED_PAD src0_sel:WORD_1
	v_cvt_f32_f16_e32 v72, v75
	v_cvt_f32_f16_e32 v80, v74
	v_cvt_f32_f16_sdwa v81, v74 dst_sel:DWORD dst_unused:UNUSED_PAD src0_sel:WORD_1
	v_cvt_f32_f16_sdwa v73, v75 dst_sel:DWORD dst_unused:UNUSED_PAD src0_sel:WORD_1
	v_pk_mul_f32 v[78:79], v[68:69], v[78:79]
	v_pk_mul_f32 v[76:77], v[70:71], v[76:77]
	v_pk_mul_f32 v[80:81], v[64:65], v[80:81]
	v_pk_mul_f32 v[72:73], v[66:67], v[72:73]
	v_cvt_pk_f16_f32 v74, v80, v81
	v_cvt_pk_f16_f32 v75, v72, v73
	v_cvt_pk_f16_f32 v73, v76, v77
	v_cvt_pk_f16_f32 v72, v78, v79
	global_store_dwordx4 v136, v[72:75], s[44:45] offset:256 sc1

.LBB0_1100:
	s_andn2_b64 vcc, exec, s[34:35]
	s_cbranch_vccnz .LBB0_1102
	global_load_dwordx4 v[66:69], v[64:65], off
	s_waitcnt vmcnt(0)
	v_cvt_f32_f16_e32 v70, v67
	v_cvt_f32_f16_sdwa v71, v67 dst_sel:DWORD dst_unused:UNUSED_PAD src0_sel:WORD_1
	v_cvt_f32_f16_e32 v72, v66
	v_cvt_f32_f16_sdwa v73, v66 dst_sel:DWORD dst_unused:UNUSED_PAD src0_sel:WORD_1
	v_cvt_f32_f16_e32 v66, v69
	v_cvt_f32_f16_e32 v74, v68
	v_cvt_f32_f16_sdwa v75, v68 dst_sel:DWORD dst_unused:UNUSED_PAD src0_sel:WORD_1
	v_cvt_f32_f16_sdwa v67, v69 dst_sel:DWORD dst_unused:UNUSED_PAD src0_sel:WORD_1
	v_pk_mul_f32 v[72:73], v[60:61], v[72:73]
	v_pk_mul_f32 v[70:71], v[62:63], v[70:71]
	v_pk_mul_f32 v[74:75], v[56:57], v[74:75]
	v_pk_mul_f32 v[66:67], v[58:59], v[66:67]
	v_cvt_pk_f16_f32 v68, v74, v75
	v_cvt_pk_f16_f32 v69, v66, v67
	v_cvt_pk_f16_f32 v67, v70, v71
	v_cvt_pk_f16_f32 v66, v72, v73
	global_store_dwordx4 v[64:65], v[66:69], off sc1

.LBB0_1106:
	s_andn2_b64 vcc, exec, s[34:35]
	s_cbranch_vccnz .LBB0_1108
	global_load_dwordx4 v[56:59], v136, s[44:45] offset:256
	s_waitcnt vmcnt(0)
	v_cvt_f32_f16_e32 v60, v57
	v_cvt_f32_f16_sdwa v61, v57 dst_sel:DWORD dst_unused:UNUSED_PAD src0_sel:WORD_1
	v_cvt_f32_f16_e32 v62, v56
	v_cvt_f32_f16_sdwa v63, v56 dst_sel:DWORD dst_unused:UNUSED_PAD src0_sel:WORD_1
	v_cvt_f32_f16_e32 v56, v59
	v_cvt_f32_f16_e32 v64, v58
	v_cvt_f32_f16_sdwa v65, v58 dst_sel:DWORD dst_unused:UNUSED_PAD src0_sel:WORD_1
	v_cvt_f32_f16_sdwa v57, v59 dst_sel:DWORD dst_unused:UNUSED_PAD src0_sel:WORD_1
	v_pk_mul_f32 v[62:63], v[52:53], v[62:63]
	v_pk_mul_f32 v[60:61], v[54:55], v[60:61]
	v_pk_mul_f32 v[64:65], v[48:49], v[64:65]
	v_pk_mul_f32 v[56:57], v[50:51], v[56:57]
	v_cvt_pk_f16_f32 v58, v64, v65
	v_cvt_pk_f16_f32 v59, v56, v57
	v_cvt_pk_f16_f32 v57, v60, v61
	v_cvt_pk_f16_f32 v56, v62, v63
	global_store_dwordx4 v136, v[56:59], s[44:45] offset:256 sc1

.LBB0_1112:
	s_andn2_b64 vcc, exec, s[34:35]
	s_cbranch_vccnz .LBB0_1114
	global_load_dwordx4 v[50:53], v[48:49], off
	s_waitcnt vmcnt(0)
	v_cvt_f32_f16_e32 v54, v51
	v_cvt_f32_f16_sdwa v55, v51 dst_sel:DWORD dst_unused:UNUSED_PAD src0_sel:WORD_1
	v_cvt_f32_f16_e32 v56, v50
	v_cvt_f32_f16_sdwa v57, v50 dst_sel:DWORD dst_unused:UNUSED_PAD src0_sel:WORD_1
	v_cvt_f32_f16_e32 v50, v53
	v_cvt_f32_f16_e32 v58, v52
	v_cvt_f32_f16_sdwa v59, v52 dst_sel:DWORD dst_unused:UNUSED_PAD src0_sel:WORD_1
	v_cvt_f32_f16_sdwa v51, v53 dst_sel:DWORD dst_unused:UNUSED_PAD src0_sel:WORD_1
	v_pk_mul_f32 v[56:57], v[44:45], v[56:57]
	v_pk_mul_f32 v[54:55], v[46:47], v[54:55]
	v_pk_mul_f32 v[58:59], v[40:41], v[58:59]
	v_pk_mul_f32 v[50:51], v[42:43], v[50:51]
	v_cvt_pk_f16_f32 v52, v58, v59
	v_cvt_pk_f16_f32 v53, v50, v51
	v_cvt_pk_f16_f32 v51, v54, v55
	v_cvt_pk_f16_f32 v50, v56, v57
	global_store_dwordx4 v[48:49], v[50:53], off sc1

.LBB0_1118:
	s_andn2_b64 vcc, exec, s[34:35]
	s_cbranch_vccnz .LBB0_1120
	global_load_dwordx4 v[40:43], v136, s[44:45] offset:256
	s_waitcnt vmcnt(0)
	v_cvt_f32_f16_e32 v44, v41
	v_cvt_f32_f16_sdwa v45, v41 dst_sel:DWORD dst_unused:UNUSED_PAD src0_sel:WORD_1
	v_cvt_f32_f16_e32 v46, v40
	v_cvt_f32_f16_sdwa v47, v40 dst_sel:DWORD dst_unused:UNUSED_PAD src0_sel:WORD_1
	v_cvt_f32_f16_e32 v40, v43
	v_cvt_f32_f16_e32 v48, v42
	v_cvt_f32_f16_sdwa v49, v42 dst_sel:DWORD dst_unused:UNUSED_PAD src0_sel:WORD_1
	v_cvt_f32_f16_sdwa v41, v43 dst_sel:DWORD dst_unused:UNUSED_PAD src0_sel:WORD_1
	v_pk_mul_f32 v[46:47], v[36:37], v[46:47]
	v_pk_mul_f32 v[44:45], v[38:39], v[44:45]
	v_pk_mul_f32 v[48:49], v[32:33], v[48:49]
	v_pk_mul_f32 v[40:41], v[34:35], v[40:41]
	v_cvt_pk_f16_f32 v42, v48, v49
	v_cvt_pk_f16_f32 v43, v40, v41
	v_cvt_pk_f16_f32 v41, v44, v45
	v_cvt_pk_f16_f32 v40, v46, v47
	global_store_dwordx4 v136, v[40:43], s[44:45] offset:256 sc1

.LBB0_1124:
	s_andn2_b64 vcc, exec, s[34:35]
	s_cbranch_vccnz .LBB0_1126
	global_load_dwordx4 v[34:37], v[32:33], off
	s_waitcnt vmcnt(0)
	v_cvt_f32_f16_e32 v38, v35
	v_cvt_f32_f16_sdwa v39, v35 dst_sel:DWORD dst_unused:UNUSED_PAD src0_sel:WORD_1
	v_cvt_f32_f16_e32 v40, v34
	v_cvt_f32_f16_sdwa v41, v34 dst_sel:DWORD dst_unused:UNUSED_PAD src0_sel:WORD_1
	v_cvt_f32_f16_e32 v34, v37
	v_cvt_f32_f16_e32 v42, v36
	v_cvt_f32_f16_sdwa v43, v36 dst_sel:DWORD dst_unused:UNUSED_PAD src0_sel:WORD_1
	v_cvt_f32_f16_sdwa v35, v37 dst_sel:DWORD dst_unused:UNUSED_PAD src0_sel:WORD_1
	v_pk_mul_f32 v[40:41], v[28:29], v[40:41]
	v_pk_mul_f32 v[38:39], v[30:31], v[38:39]
	v_pk_mul_f32 v[42:43], v[24:25], v[42:43]
	v_pk_mul_f32 v[34:35], v[26:27], v[34:35]
	v_cvt_pk_f16_f32 v36, v42, v43
	v_cvt_pk_f16_f32 v37, v34, v35
	v_cvt_pk_f16_f32 v35, v38, v39
	v_cvt_pk_f16_f32 v34, v40, v41
	global_store_dwordx4 v[32:33], v[34:37], off sc1

.LBB0_1130:
	s_andn2_b64 vcc, exec, s[34:35]
	s_cbranch_vccnz .LBB0_1132
	global_load_dwordx4 v[24:27], v136, s[44:45] offset:256
	s_waitcnt vmcnt(0)
	v_cvt_f32_f16_e32 v28, v25
	v_cvt_f32_f16_sdwa v29, v25 dst_sel:DWORD dst_unused:UNUSED_PAD src0_sel:WORD_1
	v_cvt_f32_f16_e32 v30, v24
	v_cvt_f32_f16_sdwa v31, v24 dst_sel:DWORD dst_unused:UNUSED_PAD src0_sel:WORD_1
	v_cvt_f32_f16_e32 v24, v27
	v_cvt_f32_f16_e32 v32, v26
	v_cvt_f32_f16_sdwa v33, v26 dst_sel:DWORD dst_unused:UNUSED_PAD src0_sel:WORD_1
	v_cvt_f32_f16_sdwa v25, v27 dst_sel:DWORD dst_unused:UNUSED_PAD src0_sel:WORD_1
	v_pk_mul_f32 v[30:31], v[20:21], v[30:31]
	v_pk_mul_f32 v[28:29], v[22:23], v[28:29]
	v_pk_mul_f32 v[32:33], v[16:17], v[32:33]
	v_pk_mul_f32 v[24:25], v[18:19], v[24:25]
	v_cvt_pk_f16_f32 v26, v32, v33
	v_cvt_pk_f16_f32 v27, v24, v25
	v_cvt_pk_f16_f32 v25, v28, v29
	v_cvt_pk_f16_f32 v24, v30, v31
	global_store_dwordx4 v136, v[24:27], s[44:45] offset:256 sc1

.LBB0_1136:
	s_andn2_b64 vcc, exec, s[34:35]
	s_cbranch_vccnz .LBB0_1138
	global_load_dwordx4 v[18:21], v[16:17], off
	s_waitcnt vmcnt(0)
	v_cvt_f32_f16_e32 v22, v19
	v_cvt_f32_f16_sdwa v23, v19 dst_sel:DWORD dst_unused:UNUSED_PAD src0_sel:WORD_1
	v_cvt_f32_f16_e32 v24, v18
	v_cvt_f32_f16_sdwa v25, v18 dst_sel:DWORD dst_unused:UNUSED_PAD src0_sel:WORD_1
	v_cvt_f32_f16_e32 v18, v21
	v_cvt_f32_f16_e32 v26, v20
	v_cvt_f32_f16_sdwa v27, v20 dst_sel:DWORD dst_unused:UNUSED_PAD src0_sel:WORD_1
	v_cvt_f32_f16_sdwa v19, v21 dst_sel:DWORD dst_unused:UNUSED_PAD src0_sel:WORD_1
	v_pk_mul_f32 v[24:25], v[12:13], v[24:25]
	v_pk_mul_f32 v[22:23], v[14:15], v[22:23]
	v_pk_mul_f32 v[26:27], v[8:9], v[26:27]
	v_pk_mul_f32 v[18:19], v[10:11], v[18:19]
	v_cvt_pk_f16_f32 v20, v26, v27
	v_cvt_pk_f16_f32 v21, v18, v19
	v_cvt_pk_f16_f32 v19, v22, v23
	v_cvt_pk_f16_f32 v18, v24, v25
	global_store_dwordx4 v[16:17], v[18:21], off sc1

.LBB0_1142:
	s_andn2_b64 vcc, exec, s[4:5]
	s_cbranch_vccnz .LBB0_1144
	global_load_dwordx4 v[8:11], v136, s[44:45] offset:256
	s_waitcnt vmcnt(0)
	v_cvt_f32_f16_e32 v12, v9
	v_cvt_f32_f16_sdwa v13, v9 dst_sel:DWORD dst_unused:UNUSED_PAD src0_sel:WORD_1
	v_cvt_f32_f16_e32 v14, v8
	v_cvt_f32_f16_sdwa v15, v8 dst_sel:DWORD dst_unused:UNUSED_PAD src0_sel:WORD_1
	v_cvt_f32_f16_e32 v8, v11
	v_cvt_f32_f16_e32 v16, v10
	v_cvt_f32_f16_sdwa v17, v10 dst_sel:DWORD dst_unused:UNUSED_PAD src0_sel:WORD_1
	v_cvt_f32_f16_sdwa v9, v11 dst_sel:DWORD dst_unused:UNUSED_PAD src0_sel:WORD_1
	v_pk_mul_f32 v[14:15], v[4:5], v[14:15]
	v_pk_mul_f32 v[12:13], v[6:7], v[12:13]
	v_pk_mul_f32 v[16:17], v[0:1], v[16:17]
	v_pk_mul_f32 v[8:9], v[2:3], v[8:9]
	v_cvt_pk_f16_f32 v10, v16, v17
	v_cvt_pk_f16_f32 v11, v8, v9
	v_cvt_pk_f16_f32 v9, v12, v13
	v_cvt_pk_f16_f32 v8, v14, v15
	global_store_dwordx4 v136, v[8:11], s[44:45] offset:256 sc1

.LBB0_1147:
	v_mul_f32_e32 v116, 0xbfb8aa3b, v116
	v_mul_f32_e32 v112, 0xbfb8aa3b, v112
	v_mul_f32_e32 v117, 0xbfb8aa3b, v117
	v_mul_f32_e32 v113, 0xbfb8aa3b, v113
	v_mul_f32_e32 v118, 0xbfb8aa3b, v118
	v_mul_f32_e32 v114, 0xbfb8aa3b, v114
	v_mul_f32_e32 v115, 0xbfb8aa3b, v115
	v_mul_f32_e32 v119, 0xbfb8aa3b, v119
	v_exp_f32_e32 v116, v116
	v_exp_f32_e32 v112, v112
	v_exp_f32_e32 v117, v117
	v_exp_f32_e32 v113, v113
	v_exp_f32_e32 v118, v118
	v_exp_f32_e32 v114, v114
	v_exp_f32_e32 v115, v115
	v_exp_f32_e32 v119, v119
	v_add_f32_e32 v116, 1.0, v116
	v_add_f32_e32 v112, 1.0, v112
	v_add_f32_e32 v117, 1.0, v117
	v_add_f32_e32 v113, 1.0, v113
	v_add_f32_e32 v118, 1.0, v118
	v_add_f32_e32 v114, 1.0, v114
	v_add_f32_e32 v115, 1.0, v115
	v_add_f32_e32 v119, 1.0, v119
	v_rcp_f32_e32 v116, v116
	v_rcp_f32_e32 v112, v112
	v_rcp_f32_e32 v113, v113
	v_rcp_f32_e32 v118, v118
	v_rcp_f32_e32 v114, v114
	v_rcp_f32_e32 v115, v115
	v_rcp_f32_e32 v119, v119
	v_rcp_f32_e32 v117, v117
	s_cmp_eq_u32 s63, 0
	v_cvt_pk_f16_f32 v115, v114, v115
	v_cvt_pk_f16_f32 v114, v112, v113
	v_cvt_pk_f16_f32 v113, v118, v119
	v_cvt_pk_f16_f32 v112, v116, v117
	s_cselect_b32 s35, s43, s45
	s_cselect_b32 s34, s42, s44
	global_store_dwordx4 v136, v[112:115], s[34:35] offset:256 sc1
	v_add_u32_e32 v136, s28, v146
	s_and_b64 vcc, exec, s[4:5]
	s_mov_b64 s[34:35], -1
	s_cbranch_vccz .LBB0_1062

.LBB0_1149:
	v_mul_f32_e32 v108, 0xbfb8aa3b, v108
	v_mul_f32_e32 v104, 0xbfb8aa3b, v104
	v_mul_f32_e32 v109, 0xbfb8aa3b, v109
	v_mul_f32_e32 v105, 0xbfb8aa3b, v105
	v_mul_f32_e32 v110, 0xbfb8aa3b, v110
	v_mul_f32_e32 v106, 0xbfb8aa3b, v106
	v_mul_f32_e32 v107, 0xbfb8aa3b, v107
	v_mul_f32_e32 v111, 0xbfb8aa3b, v111
	v_exp_f32_e32 v108, v108
	v_exp_f32_e32 v104, v104
	v_exp_f32_e32 v109, v109
	v_exp_f32_e32 v105, v105
	v_exp_f32_e32 v110, v110
	v_exp_f32_e32 v106, v106
	v_exp_f32_e32 v107, v107
	v_exp_f32_e32 v111, v111
	v_add_f32_e32 v108, 1.0, v108
	v_add_f32_e32 v104, 1.0, v104
	v_add_f32_e32 v109, 1.0, v109
	v_add_f32_e32 v105, 1.0, v105
	v_add_f32_e32 v110, 1.0, v110
	v_add_f32_e32 v106, 1.0, v106
	v_add_f32_e32 v107, 1.0, v107
	v_add_f32_e32 v111, 1.0, v111
	v_rcp_f32_e32 v108, v108
	v_rcp_f32_e32 v104, v104
	v_rcp_f32_e32 v105, v105
	v_rcp_f32_e32 v110, v110
	v_rcp_f32_e32 v106, v106
	v_rcp_f32_e32 v107, v107
	v_rcp_f32_e32 v111, v111
	v_rcp_f32_e32 v109, v109
	s_cmp_eq_u32 s63, 0
	v_cvt_pk_f16_f32 v107, v106, v107
	v_cvt_pk_f16_f32 v106, v104, v105
	v_cvt_pk_f16_f32 v105, v110, v111
	v_cvt_pk_f16_f32 v104, v108, v109
	s_cselect_b32 s35, s43, s45
	s_cselect_b32 s34, s42, s44
	global_store_dwordx4 v136, v[104:107], s[34:35] sc1
	s_and_b64 vcc, exec, s[4:5]
	s_mov_b64 s[34:35], -1
	s_cbranch_vccz .LBB0_1068

.LBB0_1151:
	v_mul_f32_e32 v100, 0xbfb8aa3b, v100
	v_mul_f32_e32 v96, 0xbfb8aa3b, v96
	v_mul_f32_e32 v101, 0xbfb8aa3b, v101
	v_mul_f32_e32 v97, 0xbfb8aa3b, v97
	v_mul_f32_e32 v102, 0xbfb8aa3b, v102
	v_mul_f32_e32 v98, 0xbfb8aa3b, v98
	v_mul_f32_e32 v99, 0xbfb8aa3b, v99
	v_mul_f32_e32 v103, 0xbfb8aa3b, v103
	v_exp_f32_e32 v100, v100
	v_exp_f32_e32 v96, v96
	v_exp_f32_e32 v101, v101
	v_exp_f32_e32 v97, v97
	v_exp_f32_e32 v102, v102
	v_exp_f32_e32 v98, v98
	v_exp_f32_e32 v99, v99
	v_exp_f32_e32 v103, v103
	v_add_f32_e32 v100, 1.0, v100
	v_add_f32_e32 v96, 1.0, v96
	v_add_f32_e32 v101, 1.0, v101
	v_add_f32_e32 v97, 1.0, v97
	v_add_f32_e32 v102, 1.0, v102
	v_add_f32_e32 v98, 1.0, v98
	v_add_f32_e32 v99, 1.0, v99
	v_add_f32_e32 v103, 1.0, v103
	v_rcp_f32_e32 v100, v100
	v_rcp_f32_e32 v96, v96
	v_rcp_f32_e32 v97, v97
	v_rcp_f32_e32 v102, v102
	v_rcp_f32_e32 v98, v98
	v_rcp_f32_e32 v99, v99
	v_rcp_f32_e32 v103, v103
	v_rcp_f32_e32 v101, v101
	s_cmp_eq_u32 s63, 0
	v_cvt_pk_f16_f32 v99, v98, v99
	v_cvt_pk_f16_f32 v98, v96, v97
	v_cvt_pk_f16_f32 v97, v102, v103
	v_cvt_pk_f16_f32 v96, v100, v101
	s_cselect_b32 s35, s43, s45
	s_cselect_b32 s34, s42, s44
	global_store_dwordx4 v136, v[96:99], s[34:35] offset:256 sc1
	v_add_u32_e32 v136, s28, v147
	s_and_b64 vcc, exec, s[4:5]
	s_mov_b64 s[34:35], -1
	s_cbranch_vccz .LBB0_1074

.LBB0_1153:
	v_mul_f32_e32 v92, 0xbfb8aa3b, v92
	v_mul_f32_e32 v88, 0xbfb8aa3b, v88
	v_mul_f32_e32 v93, 0xbfb8aa3b, v93
	v_mul_f32_e32 v89, 0xbfb8aa3b, v89
	v_mul_f32_e32 v94, 0xbfb8aa3b, v94
	v_mul_f32_e32 v90, 0xbfb8aa3b, v90
	v_mul_f32_e32 v91, 0xbfb8aa3b, v91
	v_mul_f32_e32 v95, 0xbfb8aa3b, v95
	v_exp_f32_e32 v92, v92
	v_exp_f32_e32 v88, v88
	v_exp_f32_e32 v93, v93
	v_exp_f32_e32 v89, v89
	v_exp_f32_e32 v94, v94
	v_exp_f32_e32 v90, v90
	v_exp_f32_e32 v91, v91
	v_exp_f32_e32 v95, v95
	v_add_f32_e32 v92, 1.0, v92
	v_add_f32_e32 v88, 1.0, v88
	v_add_f32_e32 v93, 1.0, v93
	v_add_f32_e32 v89, 1.0, v89
	v_add_f32_e32 v94, 1.0, v94
	v_add_f32_e32 v90, 1.0, v90
	v_add_f32_e32 v91, 1.0, v91
	v_add_f32_e32 v95, 1.0, v95
	v_rcp_f32_e32 v92, v92
	v_rcp_f32_e32 v88, v88
	v_rcp_f32_e32 v89, v89
	v_rcp_f32_e32 v94, v94
	v_rcp_f32_e32 v90, v90
	v_rcp_f32_e32 v91, v91
	v_rcp_f32_e32 v95, v95
	v_rcp_f32_e32 v93, v93
	s_cmp_eq_u32 s63, 0
	v_cvt_pk_f16_f32 v91, v90, v91
	v_cvt_pk_f16_f32 v90, v88, v89
	v_cvt_pk_f16_f32 v89, v94, v95
	v_cvt_pk_f16_f32 v88, v92, v93
	s_cselect_b32 s35, s43, s45
	s_cselect_b32 s34, s42, s44
	global_store_dwordx4 v136, v[88:91], s[34:35] sc1
	s_and_b64 vcc, exec, s[4:5]
	s_mov_b64 s[34:35], -1
	s_cbranch_vccz .LBB0_1080

.LBB0_1155:
	v_mul_f32_e32 v84, 0xbfb8aa3b, v84
	v_mul_f32_e32 v80, 0xbfb8aa3b, v80
	v_mul_f32_e32 v85, 0xbfb8aa3b, v85
	v_mul_f32_e32 v81, 0xbfb8aa3b, v81
	v_mul_f32_e32 v86, 0xbfb8aa3b, v86
	v_mul_f32_e32 v82, 0xbfb8aa3b, v82
	v_mul_f32_e32 v83, 0xbfb8aa3b, v83
	v_mul_f32_e32 v87, 0xbfb8aa3b, v87
	v_exp_f32_e32 v84, v84
	v_exp_f32_e32 v80, v80
	v_exp_f32_e32 v85, v85
	v_exp_f32_e32 v81, v81
	v_exp_f32_e32 v86, v86
	v_exp_f32_e32 v82, v82
	v_exp_f32_e32 v83, v83
	v_exp_f32_e32 v87, v87
	v_add_f32_e32 v84, 1.0, v84
	v_add_f32_e32 v80, 1.0, v80
	v_add_f32_e32 v85, 1.0, v85
	v_add_f32_e32 v81, 1.0, v81
	v_add_f32_e32 v86, 1.0, v86
	v_add_f32_e32 v82, 1.0, v82
	v_add_f32_e32 v83, 1.0, v83
	v_add_f32_e32 v87, 1.0, v87
	v_rcp_f32_e32 v84, v84
	v_rcp_f32_e32 v80, v80
	v_rcp_f32_e32 v81, v81
	v_rcp_f32_e32 v86, v86
	v_rcp_f32_e32 v82, v82
	v_rcp_f32_e32 v83, v83
	v_rcp_f32_e32 v87, v87
	v_rcp_f32_e32 v85, v85
	s_cmp_eq_u32 s63, 0
	v_cvt_pk_f16_f32 v83, v82, v83
	v_cvt_pk_f16_f32 v82, v80, v81
	v_cvt_pk_f16_f32 v81, v86, v87
	v_cvt_pk_f16_f32 v80, v84, v85
	s_cselect_b32 s35, s43, s45
	s_cselect_b32 s34, s42, s44
	global_store_dwordx4 v136, v[80:83], s[34:35] offset:256 sc1
	v_add_u32_e32 v136, s28, v148
	s_and_b64 vcc, exec, s[4:5]
	s_mov_b64 s[34:35], -1
	s_cbranch_vccz .LBB0_1086

.LBB0_1157:
	v_mul_f32_e32 v76, 0xbfb8aa3b, v76
	v_mul_f32_e32 v72, 0xbfb8aa3b, v72
	v_mul_f32_e32 v77, 0xbfb8aa3b, v77
	v_mul_f32_e32 v73, 0xbfb8aa3b, v73
	v_mul_f32_e32 v78, 0xbfb8aa3b, v78
	v_mul_f32_e32 v74, 0xbfb8aa3b, v74
	v_mul_f32_e32 v75, 0xbfb8aa3b, v75
	v_mul_f32_e32 v79, 0xbfb8aa3b, v79
	v_exp_f32_e32 v76, v76
	v_exp_f32_e32 v72, v72
	v_exp_f32_e32 v77, v77
	v_exp_f32_e32 v73, v73
	v_exp_f32_e32 v78, v78
	v_exp_f32_e32 v74, v74
	v_exp_f32_e32 v75, v75
	v_exp_f32_e32 v79, v79
	v_add_f32_e32 v76, 1.0, v76
	v_add_f32_e32 v72, 1.0, v72
	v_add_f32_e32 v77, 1.0, v77
	v_add_f32_e32 v73, 1.0, v73
	v_add_f32_e32 v78, 1.0, v78
	v_add_f32_e32 v74, 1.0, v74
	v_add_f32_e32 v75, 1.0, v75
	v_add_f32_e32 v79, 1.0, v79
	v_rcp_f32_e32 v76, v76
	v_rcp_f32_e32 v72, v72
	v_rcp_f32_e32 v73, v73
	v_rcp_f32_e32 v78, v78
	v_rcp_f32_e32 v74, v74
	v_rcp_f32_e32 v75, v75
	v_rcp_f32_e32 v79, v79
	v_rcp_f32_e32 v77, v77
	s_cmp_eq_u32 s63, 0
	v_cvt_pk_f16_f32 v75, v74, v75
	v_cvt_pk_f16_f32 v74, v72, v73
	v_cvt_pk_f16_f32 v73, v78, v79
	v_cvt_pk_f16_f32 v72, v76, v77
	s_cselect_b32 s35, s43, s45
	s_cselect_b32 s34, s42, s44
	global_store_dwordx4 v136, v[72:75], s[34:35] sc1
	s_and_b64 vcc, exec, s[4:5]
	s_mov_b64 s[34:35], -1
	s_cbranch_vccz .LBB0_1092

.LBB0_1159:
	v_mul_f32_e32 v68, 0xbfb8aa3b, v68
	v_mul_f32_e32 v64, 0xbfb8aa3b, v64
	v_mul_f32_e32 v69, 0xbfb8aa3b, v69
	v_mul_f32_e32 v65, 0xbfb8aa3b, v65
	v_mul_f32_e32 v70, 0xbfb8aa3b, v70
	v_mul_f32_e32 v66, 0xbfb8aa3b, v66
	v_mul_f32_e32 v67, 0xbfb8aa3b, v67
	v_mul_f32_e32 v71, 0xbfb8aa3b, v71
	v_exp_f32_e32 v68, v68
	v_exp_f32_e32 v64, v64
	v_exp_f32_e32 v69, v69
	v_exp_f32_e32 v65, v65
	v_exp_f32_e32 v70, v70
	v_exp_f32_e32 v66, v66
	v_exp_f32_e32 v67, v67
	v_exp_f32_e32 v71, v71
	v_add_f32_e32 v68, 1.0, v68
	v_add_f32_e32 v64, 1.0, v64
	v_add_f32_e32 v69, 1.0, v69
	v_add_f32_e32 v65, 1.0, v65
	v_add_f32_e32 v70, 1.0, v70
	v_add_f32_e32 v66, 1.0, v66
	v_add_f32_e32 v67, 1.0, v67
	v_add_f32_e32 v71, 1.0, v71
	v_rcp_f32_e32 v68, v68
	v_rcp_f32_e32 v64, v64
	v_rcp_f32_e32 v65, v65
	v_rcp_f32_e32 v70, v70
	v_rcp_f32_e32 v66, v66
	v_rcp_f32_e32 v67, v67
	v_rcp_f32_e32 v71, v71
	v_rcp_f32_e32 v69, v69
	s_cmp_eq_u32 s63, 0
	v_cvt_pk_f16_f32 v67, v66, v67
	v_cvt_pk_f16_f32 v66, v64, v65
	v_cvt_pk_f16_f32 v65, v70, v71
	v_cvt_pk_f16_f32 v64, v68, v69
	s_cselect_b32 s35, s43, s45
	s_cselect_b32 s34, s42, s44
	global_store_dwordx4 v136, v[64:67], s[34:35] offset:256 sc1
	v_add_u32_e32 v136, s28, v149
	s_and_b64 vcc, exec, s[4:5]
	s_mov_b64 s[34:35], -1
	s_cbranch_vccz .LBB0_1098

.LBB0_1161:
	v_mul_f32_e32 v60, 0xbfb8aa3b, v60
	v_mul_f32_e32 v56, 0xbfb8aa3b, v56
	v_mul_f32_e32 v61, 0xbfb8aa3b, v61
	v_mul_f32_e32 v57, 0xbfb8aa3b, v57
	v_mul_f32_e32 v62, 0xbfb8aa3b, v62
	v_mul_f32_e32 v58, 0xbfb8aa3b, v58
	v_mul_f32_e32 v59, 0xbfb8aa3b, v59
	v_mul_f32_e32 v63, 0xbfb8aa3b, v63
	v_exp_f32_e32 v60, v60
	v_exp_f32_e32 v56, v56
	v_exp_f32_e32 v61, v61
	v_exp_f32_e32 v57, v57
	v_exp_f32_e32 v62, v62
	v_exp_f32_e32 v58, v58
	v_exp_f32_e32 v59, v59
	v_exp_f32_e32 v63, v63
	v_add_f32_e32 v60, 1.0, v60
	v_add_f32_e32 v56, 1.0, v56
	v_add_f32_e32 v61, 1.0, v61
	v_add_f32_e32 v57, 1.0, v57
	v_add_f32_e32 v62, 1.0, v62
	v_add_f32_e32 v58, 1.0, v58
	v_add_f32_e32 v59, 1.0, v59
	v_add_f32_e32 v63, 1.0, v63
	v_rcp_f32_e32 v60, v60
	v_rcp_f32_e32 v56, v56
	v_rcp_f32_e32 v57, v57
	v_rcp_f32_e32 v62, v62
	v_rcp_f32_e32 v58, v58
	v_rcp_f32_e32 v59, v59
	v_rcp_f32_e32 v63, v63
	v_rcp_f32_e32 v61, v61
	s_cmp_eq_u32 s63, 0
	v_cvt_pk_f16_f32 v59, v58, v59
	v_cvt_pk_f16_f32 v58, v56, v57
	v_cvt_pk_f16_f32 v57, v62, v63
	v_cvt_pk_f16_f32 v56, v60, v61
	s_cselect_b32 s35, s43, s45
	s_cselect_b32 s34, s42, s44
	global_store_dwordx4 v136, v[56:59], s[34:35] sc1
	s_and_b64 vcc, exec, s[4:5]
	s_mov_b64 s[34:35], -1
	s_cbranch_vccz .LBB0_1104

.LBB0_1163:
	v_mul_f32_e32 v52, 0xbfb8aa3b, v52
	v_mul_f32_e32 v48, 0xbfb8aa3b, v48
	v_mul_f32_e32 v53, 0xbfb8aa3b, v53
	v_mul_f32_e32 v49, 0xbfb8aa3b, v49
	v_mul_f32_e32 v54, 0xbfb8aa3b, v54
	v_mul_f32_e32 v50, 0xbfb8aa3b, v50
	v_mul_f32_e32 v51, 0xbfb8aa3b, v51
	v_mul_f32_e32 v55, 0xbfb8aa3b, v55
	v_exp_f32_e32 v52, v52
	v_exp_f32_e32 v48, v48
	v_exp_f32_e32 v53, v53
	v_exp_f32_e32 v49, v49
	v_exp_f32_e32 v54, v54
	v_exp_f32_e32 v50, v50
	v_exp_f32_e32 v51, v51
	v_exp_f32_e32 v55, v55
	v_add_f32_e32 v52, 1.0, v52
	v_add_f32_e32 v48, 1.0, v48
	v_add_f32_e32 v53, 1.0, v53
	v_add_f32_e32 v49, 1.0, v49
	v_add_f32_e32 v54, 1.0, v54
	v_add_f32_e32 v50, 1.0, v50
	v_add_f32_e32 v51, 1.0, v51
	v_add_f32_e32 v55, 1.0, v55
	v_rcp_f32_e32 v52, v52
	v_rcp_f32_e32 v48, v48
	v_rcp_f32_e32 v49, v49
	v_rcp_f32_e32 v54, v54
	v_rcp_f32_e32 v50, v50
	v_rcp_f32_e32 v51, v51
	v_rcp_f32_e32 v55, v55
	v_rcp_f32_e32 v53, v53
	s_cmp_eq_u32 s63, 0
	v_cvt_pk_f16_f32 v51, v50, v51
	v_cvt_pk_f16_f32 v50, v48, v49
	v_cvt_pk_f16_f32 v49, v54, v55
	v_cvt_pk_f16_f32 v48, v52, v53
	s_cselect_b32 s35, s43, s45
	s_cselect_b32 s34, s42, s44
	global_store_dwordx4 v136, v[48:51], s[34:35] offset:256 sc1
	v_add_u32_e32 v136, s28, v150
	s_and_b64 vcc, exec, s[4:5]
	s_mov_b64 s[34:35], -1
	s_cbranch_vccz .LBB0_1110

.LBB0_1165:
	v_mul_f32_e32 v44, 0xbfb8aa3b, v44
	v_mul_f32_e32 v40, 0xbfb8aa3b, v40
	v_mul_f32_e32 v45, 0xbfb8aa3b, v45
	v_mul_f32_e32 v41, 0xbfb8aa3b, v41
	v_mul_f32_e32 v46, 0xbfb8aa3b, v46
	v_mul_f32_e32 v42, 0xbfb8aa3b, v42
	v_mul_f32_e32 v43, 0xbfb8aa3b, v43
	v_mul_f32_e32 v47, 0xbfb8aa3b, v47
	v_exp_f32_e32 v44, v44
	v_exp_f32_e32 v40, v40
	v_exp_f32_e32 v45, v45
	v_exp_f32_e32 v41, v41
	v_exp_f32_e32 v46, v46
	v_exp_f32_e32 v42, v42
	v_exp_f32_e32 v43, v43
	v_exp_f32_e32 v47, v47
	v_add_f32_e32 v44, 1.0, v44
	v_add_f32_e32 v40, 1.0, v40
	v_add_f32_e32 v45, 1.0, v45
	v_add_f32_e32 v41, 1.0, v41
	v_add_f32_e32 v46, 1.0, v46
	v_add_f32_e32 v42, 1.0, v42
	v_add_f32_e32 v43, 1.0, v43
	v_add_f32_e32 v47, 1.0, v47
	v_rcp_f32_e32 v44, v44
	v_rcp_f32_e32 v40, v40
	v_rcp_f32_e32 v41, v41
	v_rcp_f32_e32 v46, v46
	v_rcp_f32_e32 v42, v42
	v_rcp_f32_e32 v43, v43
	v_rcp_f32_e32 v47, v47
	v_rcp_f32_e32 v45, v45
	s_cmp_eq_u32 s63, 0
	v_cvt_pk_f16_f32 v43, v42, v43
	v_cvt_pk_f16_f32 v42, v40, v41
	v_cvt_pk_f16_f32 v41, v46, v47
	v_cvt_pk_f16_f32 v40, v44, v45
	s_cselect_b32 s35, s43, s45
	s_cselect_b32 s34, s42, s44
	global_store_dwordx4 v136, v[40:43], s[34:35] sc1
	s_and_b64 vcc, exec, s[4:5]
	s_mov_b64 s[34:35], -1
	s_cbranch_vccz .LBB0_1116

.LBB0_1167:
	v_mul_f32_e32 v36, 0xbfb8aa3b, v36
	v_mul_f32_e32 v32, 0xbfb8aa3b, v32
	v_mul_f32_e32 v37, 0xbfb8aa3b, v37
	v_mul_f32_e32 v33, 0xbfb8aa3b, v33
	v_mul_f32_e32 v38, 0xbfb8aa3b, v38
	v_mul_f32_e32 v34, 0xbfb8aa3b, v34
	v_mul_f32_e32 v35, 0xbfb8aa3b, v35
	v_mul_f32_e32 v39, 0xbfb8aa3b, v39
	v_exp_f32_e32 v36, v36
	v_exp_f32_e32 v32, v32
	v_exp_f32_e32 v37, v37
	v_exp_f32_e32 v33, v33
	v_exp_f32_e32 v38, v38
	v_exp_f32_e32 v34, v34
	v_exp_f32_e32 v35, v35
	v_exp_f32_e32 v39, v39
	v_add_f32_e32 v36, 1.0, v36
	v_add_f32_e32 v32, 1.0, v32
	v_add_f32_e32 v37, 1.0, v37
	v_add_f32_e32 v33, 1.0, v33
	v_add_f32_e32 v38, 1.0, v38
	v_add_f32_e32 v34, 1.0, v34
	v_add_f32_e32 v35, 1.0, v35
	v_add_f32_e32 v39, 1.0, v39
	v_rcp_f32_e32 v36, v36
	v_rcp_f32_e32 v32, v32
	v_rcp_f32_e32 v33, v33
	v_rcp_f32_e32 v38, v38
	v_rcp_f32_e32 v34, v34
	v_rcp_f32_e32 v35, v35
	v_rcp_f32_e32 v39, v39
	v_rcp_f32_e32 v37, v37
	s_cmp_eq_u32 s63, 0
	v_cvt_pk_f16_f32 v35, v34, v35
	v_cvt_pk_f16_f32 v34, v32, v33
	v_cvt_pk_f16_f32 v33, v38, v39
	v_cvt_pk_f16_f32 v32, v36, v37
	s_cselect_b32 s35, s43, s45
	s_cselect_b32 s34, s42, s44
	global_store_dwordx4 v136, v[32:35], s[34:35] offset:256 sc1
	v_add_u32_e32 v136, s28, v151
	s_and_b64 vcc, exec, s[4:5]
	s_mov_b64 s[34:35], -1
	s_cbranch_vccz .LBB0_1122

.LBB0_1169:
	v_mul_f32_e32 v28, 0xbfb8aa3b, v28
	v_mul_f32_e32 v24, 0xbfb8aa3b, v24
	v_mul_f32_e32 v29, 0xbfb8aa3b, v29
	v_mul_f32_e32 v25, 0xbfb8aa3b, v25
	v_mul_f32_e32 v30, 0xbfb8aa3b, v30
	v_mul_f32_e32 v26, 0xbfb8aa3b, v26
	v_mul_f32_e32 v27, 0xbfb8aa3b, v27
	v_mul_f32_e32 v31, 0xbfb8aa3b, v31
	v_exp_f32_e32 v28, v28
	v_exp_f32_e32 v24, v24
	v_exp_f32_e32 v29, v29
	v_exp_f32_e32 v25, v25
	v_exp_f32_e32 v30, v30
	v_exp_f32_e32 v26, v26
	v_exp_f32_e32 v27, v27
	v_exp_f32_e32 v31, v31
	v_add_f32_e32 v28, 1.0, v28
	v_add_f32_e32 v24, 1.0, v24
	v_add_f32_e32 v29, 1.0, v29
	v_add_f32_e32 v25, 1.0, v25
	v_add_f32_e32 v30, 1.0, v30
	v_add_f32_e32 v26, 1.0, v26
	v_add_f32_e32 v27, 1.0, v27
	v_add_f32_e32 v31, 1.0, v31
	v_rcp_f32_e32 v28, v28
	v_rcp_f32_e32 v24, v24
	v_rcp_f32_e32 v25, v25
	v_rcp_f32_e32 v30, v30
	v_rcp_f32_e32 v26, v26
	v_rcp_f32_e32 v27, v27
	v_rcp_f32_e32 v31, v31
	v_rcp_f32_e32 v29, v29
	s_cmp_eq_u32 s63, 0
	v_cvt_pk_f16_f32 v27, v26, v27
	v_cvt_pk_f16_f32 v26, v24, v25
	v_cvt_pk_f16_f32 v25, v30, v31
	v_cvt_pk_f16_f32 v24, v28, v29
	s_cselect_b32 s35, s43, s45
	s_cselect_b32 s34, s42, s44
	global_store_dwordx4 v136, v[24:27], s[34:35] sc1
	s_and_b64 vcc, exec, s[4:5]
	s_mov_b64 s[34:35], -1
	s_cbranch_vccz .LBB0_1128

.LBB0_1171:
	v_mul_f32_e32 v20, 0xbfb8aa3b, v20
	v_mul_f32_e32 v16, 0xbfb8aa3b, v16
	v_mul_f32_e32 v21, 0xbfb8aa3b, v21
	v_mul_f32_e32 v17, 0xbfb8aa3b, v17
	v_mul_f32_e32 v22, 0xbfb8aa3b, v22
	v_mul_f32_e32 v18, 0xbfb8aa3b, v18
	v_mul_f32_e32 v19, 0xbfb8aa3b, v19
	v_mul_f32_e32 v23, 0xbfb8aa3b, v23
	v_exp_f32_e32 v20, v20
	v_exp_f32_e32 v16, v16
	v_exp_f32_e32 v21, v21
	v_exp_f32_e32 v17, v17
	v_exp_f32_e32 v22, v22
	v_exp_f32_e32 v18, v18
	v_exp_f32_e32 v19, v19
	v_exp_f32_e32 v23, v23
	v_add_f32_e32 v20, 1.0, v20
	v_add_f32_e32 v16, 1.0, v16
	v_add_f32_e32 v21, 1.0, v21
	v_add_f32_e32 v17, 1.0, v17
	v_add_f32_e32 v22, 1.0, v22
	v_add_f32_e32 v18, 1.0, v18
	v_add_f32_e32 v19, 1.0, v19
	v_add_f32_e32 v23, 1.0, v23
	v_rcp_f32_e32 v20, v20
	v_rcp_f32_e32 v16, v16
	v_rcp_f32_e32 v17, v17
	v_rcp_f32_e32 v22, v22
	v_rcp_f32_e32 v18, v18
	v_rcp_f32_e32 v19, v19
	v_rcp_f32_e32 v23, v23
	v_rcp_f32_e32 v21, v21
	s_cmp_eq_u32 s63, 0
	v_cvt_pk_f16_f32 v19, v18, v19
	v_cvt_pk_f16_f32 v18, v16, v17
	v_cvt_pk_f16_f32 v17, v22, v23
	v_cvt_pk_f16_f32 v16, v20, v21
	s_cselect_b32 s35, s43, s45
	s_cselect_b32 s34, s42, s44
	global_store_dwordx4 v136, v[16:19], s[34:35] offset:256 sc1
	v_add_u32_e32 v136, s28, v152
	s_and_b64 vcc, exec, s[4:5]
	s_mov_b64 s[34:35], -1
	s_cbranch_vccz .LBB0_1134

.LBB0_1173:
	v_mul_f32_e32 v12, 0xbfb8aa3b, v12
	v_mul_f32_e32 v8, 0xbfb8aa3b, v8
	v_mul_f32_e32 v13, 0xbfb8aa3b, v13
	v_mul_f32_e32 v9, 0xbfb8aa3b, v9
	v_mul_f32_e32 v14, 0xbfb8aa3b, v14
	v_mul_f32_e32 v10, 0xbfb8aa3b, v10
	v_mul_f32_e32 v11, 0xbfb8aa3b, v11
	v_mul_f32_e32 v15, 0xbfb8aa3b, v15
	v_exp_f32_e32 v12, v12
	v_exp_f32_e32 v8, v8
	v_exp_f32_e32 v13, v13
	v_exp_f32_e32 v9, v9
	v_exp_f32_e32 v14, v14
	v_exp_f32_e32 v10, v10
	v_exp_f32_e32 v11, v11
	v_exp_f32_e32 v15, v15
	v_add_f32_e32 v12, 1.0, v12
	v_add_f32_e32 v8, 1.0, v8
	v_add_f32_e32 v13, 1.0, v13
	v_add_f32_e32 v9, 1.0, v9
	v_add_f32_e32 v14, 1.0, v14
	v_add_f32_e32 v10, 1.0, v10
	v_add_f32_e32 v11, 1.0, v11
	v_add_f32_e32 v15, 1.0, v15
	v_rcp_f32_e32 v12, v12
	v_rcp_f32_e32 v8, v8
	v_rcp_f32_e32 v9, v9
	v_rcp_f32_e32 v14, v14
	v_rcp_f32_e32 v10, v10
	v_rcp_f32_e32 v11, v11
	v_rcp_f32_e32 v15, v15
	v_rcp_f32_e32 v13, v13
	s_cmp_eq_u32 s63, 0
	v_cvt_pk_f16_f32 v11, v10, v11
	v_cvt_pk_f16_f32 v10, v8, v9
	v_cvt_pk_f16_f32 v9, v14, v15
	v_cvt_pk_f16_f32 v8, v12, v13
	s_cselect_b32 s29, s43, s45
	s_cselect_b32 s28, s42, s44
	global_store_dwordx4 v136, v[8:11], s[28:29] sc1
	s_and_b64 vcc, exec, s[4:5]
	s_mov_b64 s[4:5], -1
	s_cbranch_vccz .LBB0_1140

.LBB0_1175:
	v_mul_f32_e32 v4, 0xbfb8aa3b, v4
	v_mul_f32_e32 v0, 0xbfb8aa3b, v0
	v_mul_f32_e32 v5, 0xbfb8aa3b, v5
	v_mul_f32_e32 v1, 0xbfb8aa3b, v1
	v_mul_f32_e32 v6, 0xbfb8aa3b, v6
	v_mul_f32_e32 v2, 0xbfb8aa3b, v2
	v_mul_f32_e32 v3, 0xbfb8aa3b, v3
	v_mul_f32_e32 v7, 0xbfb8aa3b, v7
	v_exp_f32_e32 v4, v4
	v_exp_f32_e32 v0, v0
	v_exp_f32_e32 v5, v5
	v_exp_f32_e32 v1, v1
	v_exp_f32_e32 v6, v6
	v_exp_f32_e32 v2, v2
	v_exp_f32_e32 v3, v3
	v_exp_f32_e32 v7, v7
	v_add_f32_e32 v4, 1.0, v4
	v_add_f32_e32 v0, 1.0, v0
	v_add_f32_e32 v5, 1.0, v5
	v_add_f32_e32 v1, 1.0, v1
	v_add_f32_e32 v6, 1.0, v6
	v_add_f32_e32 v2, 1.0, v2
	v_add_f32_e32 v3, 1.0, v3
	v_add_f32_e32 v7, 1.0, v7
	v_rcp_f32_e32 v4, v4
	v_rcp_f32_e32 v0, v0
	v_rcp_f32_e32 v1, v1
	v_rcp_f32_e32 v6, v6
	v_rcp_f32_e32 v2, v2
	v_rcp_f32_e32 v3, v3
	v_rcp_f32_e32 v7, v7
	v_rcp_f32_e32 v5, v5
	s_cmp_eq_u32 s63, 0
	v_cvt_pk_f16_f32 v3, v2, v3
	v_cvt_pk_f16_f32 v2, v0, v1
	v_cvt_pk_f16_f32 v1, v6, v7
	v_cvt_pk_f16_f32 v0, v4, v5
	s_cselect_b32 s5, s43, s45
	s_cselect_b32 s4, s42, s44
	global_store_dwordx4 v136, v[0:3], s[4:5] offset:256 sc1
	s_andn2_b64 vcc, exec, s[40:41]
	s_mov_b64 s[4:5], -1
	s_cbranch_vccnz .LBB0_1029

.Lsh_k01:
	s_cmp_eq_u32 s63, 0
	s_cselect_b32 s5, s43, s45
	s_cselect_b32 s4, s42, s44
	v_mov_b32_e32 v156, v136
	v_add_u32_e32 v157, 0x8000, v136
	v_add_u32_e32 v158, 0x10000, v136
	v_add_u32_e32 v159, 0x18000, v136
	v_add_u32_e32 v160, 0x40000, v136
	v_add_u32_e32 v161, 0x48000, v136
	v_add_u32_e32 v162, 0x50000, v136
	v_add_u32_e32 v163, 0x58000, v136
	v_mul_f32_e32 v124, 0xbfb8aa3b, v124
	v_mul_f32_e32 v120, 0xbfb8aa3b, v120
	v_mul_f32_e32 v125, 0xbfb8aa3b, v125
	v_mul_f32_e32 v121, 0xbfb8aa3b, v121
	v_mul_f32_e32 v126, 0xbfb8aa3b, v126
	v_mul_f32_e32 v122, 0xbfb8aa3b, v122
	v_mul_f32_e32 v123, 0xbfb8aa3b, v123
	v_mul_f32_e32 v127, 0xbfb8aa3b, v127
	v_exp_f32_e32 v124, v124
	v_exp_f32_e32 v120, v120
	v_exp_f32_e32 v125, v125
	v_exp_f32_e32 v121, v121
	v_exp_f32_e32 v126, v126
	v_exp_f32_e32 v122, v122
	v_exp_f32_e32 v123, v123
	v_exp_f32_e32 v127, v127
	v_add_f32_e32 v124, 1.0, v124
	v_add_f32_e32 v120, 1.0, v120
	v_add_f32_e32 v125, 1.0, v125
	v_add_f32_e32 v121, 1.0, v121
	v_add_f32_e32 v126, 1.0, v126
	v_add_f32_e32 v122, 1.0, v122
	v_add_f32_e32 v123, 1.0, v123
	v_add_f32_e32 v127, 1.0, v127
	v_rcp_f32_e32 v124, v124
	v_rcp_f32_e32 v120, v120
	v_rcp_f32_e32 v121, v121
	v_rcp_f32_e32 v126, v126
	v_rcp_f32_e32 v122, v122
	v_rcp_f32_e32 v123, v123
	v_rcp_f32_e32 v127, v127
	v_rcp_f32_e32 v125, v125
	s_nop 0
	v_cvt_pk_f16_f32 v123, v122, v123
	v_cvt_pk_f16_f32 v122, v120, v121
	v_cvt_pk_f16_f32 v121, v126, v127
	v_cvt_pk_f16_f32 v120, v124, v125
	global_store_dwordx4 v156, v[120:123], s[4:5] sc1
	v_mul_f32_e32 v116, 0xbfb8aa3b, v116
	v_mul_f32_e32 v112, 0xbfb8aa3b, v112
	v_mul_f32_e32 v117, 0xbfb8aa3b, v117
	v_mul_f32_e32 v113, 0xbfb8aa3b, v113
	v_mul_f32_e32 v118, 0xbfb8aa3b, v118
	v_mul_f32_e32 v114, 0xbfb8aa3b, v114
	v_mul_f32_e32 v115, 0xbfb8aa3b, v115
	v_mul_f32_e32 v119, 0xbfb8aa3b, v119
	v_exp_f32_e32 v116, v116
	v_exp_f32_e32 v112, v112
	v_exp_f32_e32 v117, v117
	v_exp_f32_e32 v113, v113
	v_exp_f32_e32 v118, v118
	v_exp_f32_e32 v114, v114
	v_exp_f32_e32 v115, v115
	v_exp_f32_e32 v119, v119
	v_add_f32_e32 v116, 1.0, v116
	v_add_f32_e32 v112, 1.0, v112
	v_add_f32_e32 v117, 1.0, v117
	v_add_f32_e32 v113, 1.0, v113
	v_add_f32_e32 v118, 1.0, v118
	v_add_f32_e32 v114, 1.0, v114
	v_add_f32_e32 v115, 1.0, v115
	v_add_f32_e32 v119, 1.0, v119
	v_rcp_f32_e32 v116, v116
	v_rcp_f32_e32 v112, v112
	v_rcp_f32_e32 v113, v113
	v_rcp_f32_e32 v118, v118
	v_rcp_f32_e32 v114, v114
	v_rcp_f32_e32 v115, v115
	v_rcp_f32_e32 v119, v119
	v_rcp_f32_e32 v117, v117
	s_nop 0
	v_cvt_pk_f16_f32 v115, v114, v115
	v_cvt_pk_f16_f32 v114, v112, v113
	v_cvt_pk_f16_f32 v113, v118, v119
	v_cvt_pk_f16_f32 v112, v116, v117
	global_store_dwordx4 v156, v[112:115], s[4:5] offset:256 sc1
	v_mul_f32_e32 v108, 0xbfb8aa3b, v108
	v_mul_f32_e32 v104, 0xbfb8aa3b, v104
	v_mul_f32_e32 v109, 0xbfb8aa3b, v109
	v_mul_f32_e32 v105, 0xbfb8aa3b, v105
	v_mul_f32_e32 v110, 0xbfb8aa3b, v110
	v_mul_f32_e32 v106, 0xbfb8aa3b, v106
	v_mul_f32_e32 v107, 0xbfb8aa3b, v107
	v_mul_f32_e32 v111, 0xbfb8aa3b, v111
	v_exp_f32_e32 v108, v108
	v_exp_f32_e32 v104, v104
	v_exp_f32_e32 v109, v109
	v_exp_f32_e32 v105, v105
	v_exp_f32_e32 v110, v110
	v_exp_f32_e32 v106, v106
	v_exp_f32_e32 v107, v107
	v_exp_f32_e32 v111, v111
	v_add_f32_e32 v108, 1.0, v108
	v_add_f32_e32 v104, 1.0, v104
	v_add_f32_e32 v109, 1.0, v109
	v_add_f32_e32 v105, 1.0, v105
	v_add_f32_e32 v110, 1.0, v110
	v_add_f32_e32 v106, 1.0, v106
	v_add_f32_e32 v107, 1.0, v107
	v_add_f32_e32 v111, 1.0, v111
	v_rcp_f32_e32 v108, v108
	v_rcp_f32_e32 v104, v104
	v_rcp_f32_e32 v105, v105
	v_rcp_f32_e32 v110, v110
	v_rcp_f32_e32 v106, v106
	v_rcp_f32_e32 v107, v107
	v_rcp_f32_e32 v111, v111
	v_rcp_f32_e32 v109, v109
	s_nop 0
	v_cvt_pk_f16_f32 v107, v106, v107
	v_cvt_pk_f16_f32 v106, v104, v105
	v_cvt_pk_f16_f32 v105, v110, v111
	v_cvt_pk_f16_f32 v104, v108, v109
	global_store_dwordx4 v157, v[104:107], s[4:5] sc1
	v_mul_f32_e32 v100, 0xbfb8aa3b, v100
	v_mul_f32_e32 v96, 0xbfb8aa3b, v96
	v_mul_f32_e32 v101, 0xbfb8aa3b, v101
	v_mul_f32_e32 v97, 0xbfb8aa3b, v97
	v_mul_f32_e32 v102, 0xbfb8aa3b, v102
	v_mul_f32_e32 v98, 0xbfb8aa3b, v98
	v_mul_f32_e32 v99, 0xbfb8aa3b, v99
	v_mul_f32_e32 v103, 0xbfb8aa3b, v103
	v_exp_f32_e32 v100, v100
	v_exp_f32_e32 v96, v96
	v_exp_f32_e32 v101, v101
	v_exp_f32_e32 v97, v97
	v_exp_f32_e32 v102, v102
	v_exp_f32_e32 v98, v98
	v_exp_f32_e32 v99, v99
	v_exp_f32_e32 v103, v103
	v_add_f32_e32 v100, 1.0, v100
	v_add_f32_e32 v96, 1.0, v96
	v_add_f32_e32 v101, 1.0, v101
	v_add_f32_e32 v97, 1.0, v97
	v_add_f32_e32 v102, 1.0, v102
	v_add_f32_e32 v98, 1.0, v98
	v_add_f32_e32 v99, 1.0, v99
	v_add_f32_e32 v103, 1.0, v103
	v_rcp_f32_e32 v100, v100
	v_rcp_f32_e32 v96, v96
	v_rcp_f32_e32 v97, v97
	v_rcp_f32_e32 v102, v102
	v_rcp_f32_e32 v98, v98
	v_rcp_f32_e32 v99, v99
	v_rcp_f32_e32 v103, v103
	v_rcp_f32_e32 v101, v101
	s_nop 0
	v_cvt_pk_f16_f32 v99, v98, v99
	v_cvt_pk_f16_f32 v98, v96, v97
	v_cvt_pk_f16_f32 v97, v102, v103
	v_cvt_pk_f16_f32 v96, v100, v101
	global_store_dwordx4 v157, v[96:99], s[4:5] offset:256 sc1
	v_mul_f32_e32 v92, 0xbfb8aa3b, v92
	v_mul_f32_e32 v88, 0xbfb8aa3b, v88
	v_mul_f32_e32 v93, 0xbfb8aa3b, v93
	v_mul_f32_e32 v89, 0xbfb8aa3b, v89
	v_mul_f32_e32 v94, 0xbfb8aa3b, v94
	v_mul_f32_e32 v90, 0xbfb8aa3b, v90
	v_mul_f32_e32 v91, 0xbfb8aa3b, v91
	v_mul_f32_e32 v95, 0xbfb8aa3b, v95
	v_exp_f32_e32 v92, v92
	v_exp_f32_e32 v88, v88
	v_exp_f32_e32 v93, v93
	v_exp_f32_e32 v89, v89
	v_exp_f32_e32 v94, v94
	v_exp_f32_e32 v90, v90
	v_exp_f32_e32 v91, v91
	v_exp_f32_e32 v95, v95
	v_add_f32_e32 v92, 1.0, v92
	v_add_f32_e32 v88, 1.0, v88
	v_add_f32_e32 v93, 1.0, v93
	v_add_f32_e32 v89, 1.0, v89
	v_add_f32_e32 v94, 1.0, v94
	v_add_f32_e32 v90, 1.0, v90
	v_add_f32_e32 v91, 1.0, v91
	v_add_f32_e32 v95, 1.0, v95
	v_rcp_f32_e32 v92, v92
	v_rcp_f32_e32 v88, v88
	v_rcp_f32_e32 v89, v89
	v_rcp_f32_e32 v94, v94
	v_rcp_f32_e32 v90, v90
	v_rcp_f32_e32 v91, v91
	v_rcp_f32_e32 v95, v95
	v_rcp_f32_e32 v93, v93
	s_nop 0
	v_cvt_pk_f16_f32 v91, v90, v91
	v_cvt_pk_f16_f32 v90, v88, v89
	v_cvt_pk_f16_f32 v89, v94, v95
	v_cvt_pk_f16_f32 v88, v92, v93
	global_store_dwordx4 v158, v[88:91], s[4:5] sc1
	v_mul_f32_e32 v84, 0xbfb8aa3b, v84
	v_mul_f32_e32 v80, 0xbfb8aa3b, v80
	v_mul_f32_e32 v85, 0xbfb8aa3b, v85
	v_mul_f32_e32 v81, 0xbfb8aa3b, v81
	v_mul_f32_e32 v86, 0xbfb8aa3b, v86
	v_mul_f32_e32 v82, 0xbfb8aa3b, v82
	v_mul_f32_e32 v83, 0xbfb8aa3b, v83
	v_mul_f32_e32 v87, 0xbfb8aa3b, v87
	v_exp_f32_e32 v84, v84
	v_exp_f32_e32 v80, v80
	v_exp_f32_e32 v85, v85
	v_exp_f32_e32 v81, v81
	v_exp_f32_e32 v86, v86
	v_exp_f32_e32 v82, v82
	v_exp_f32_e32 v83, v83
	v_exp_f32_e32 v87, v87
	v_add_f32_e32 v84, 1.0, v84
	v_add_f32_e32 v80, 1.0, v80
	v_add_f32_e32 v85, 1.0, v85
	v_add_f32_e32 v81, 1.0, v81
	v_add_f32_e32 v86, 1.0, v86
	v_add_f32_e32 v82, 1.0, v82
	v_add_f32_e32 v83, 1.0, v83
	v_add_f32_e32 v87, 1.0, v87
	v_rcp_f32_e32 v84, v84
	v_rcp_f32_e32 v80, v80
	v_rcp_f32_e32 v81, v81
	v_rcp_f32_e32 v86, v86
	v_rcp_f32_e32 v82, v82
	v_rcp_f32_e32 v83, v83
	v_rcp_f32_e32 v87, v87
	v_rcp_f32_e32 v85, v85
	s_nop 0
	v_cvt_pk_f16_f32 v83, v82, v83
	v_cvt_pk_f16_f32 v82, v80, v81
	v_cvt_pk_f16_f32 v81, v86, v87
	v_cvt_pk_f16_f32 v80, v84, v85
	global_store_dwordx4 v158, v[80:83], s[4:5] offset:256 sc1
	v_mul_f32_e32 v76, 0xbfb8aa3b, v76
	v_mul_f32_e32 v72, 0xbfb8aa3b, v72
	v_mul_f32_e32 v77, 0xbfb8aa3b, v77
	v_mul_f32_e32 v73, 0xbfb8aa3b, v73
	v_mul_f32_e32 v78, 0xbfb8aa3b, v78
	v_mul_f32_e32 v74, 0xbfb8aa3b, v74
	v_mul_f32_e32 v75, 0xbfb8aa3b, v75
	v_mul_f32_e32 v79, 0xbfb8aa3b, v79
	v_exp_f32_e32 v76, v76
	v_exp_f32_e32 v72, v72
	v_exp_f32_e32 v77, v77
	v_exp_f32_e32 v73, v73
	v_exp_f32_e32 v78, v78
	v_exp_f32_e32 v74, v74
	v_exp_f32_e32 v75, v75
	v_exp_f32_e32 v79, v79
	v_add_f32_e32 v76, 1.0, v76
	v_add_f32_e32 v72, 1.0, v72
	v_add_f32_e32 v77, 1.0, v77
	v_add_f32_e32 v73, 1.0, v73
	v_add_f32_e32 v78, 1.0, v78
	v_add_f32_e32 v74, 1.0, v74
	v_add_f32_e32 v75, 1.0, v75
	v_add_f32_e32 v79, 1.0, v79
	v_rcp_f32_e32 v76, v76
	v_rcp_f32_e32 v72, v72
	v_rcp_f32_e32 v73, v73
	v_rcp_f32_e32 v78, v78
	v_rcp_f32_e32 v74, v74
	v_rcp_f32_e32 v75, v75
	v_rcp_f32_e32 v79, v79
	v_rcp_f32_e32 v77, v77
	s_nop 0
	v_cvt_pk_f16_f32 v75, v74, v75
	v_cvt_pk_f16_f32 v74, v72, v73
	v_cvt_pk_f16_f32 v73, v78, v79
	v_cvt_pk_f16_f32 v72, v76, v77
	global_store_dwordx4 v159, v[72:75], s[4:5] sc1
	v_mul_f32_e32 v68, 0xbfb8aa3b, v68
	v_mul_f32_e32 v64, 0xbfb8aa3b, v64
	v_mul_f32_e32 v69, 0xbfb8aa3b, v69
	v_mul_f32_e32 v65, 0xbfb8aa3b, v65
	v_mul_f32_e32 v70, 0xbfb8aa3b, v70
	v_mul_f32_e32 v66, 0xbfb8aa3b, v66
	v_mul_f32_e32 v67, 0xbfb8aa3b, v67
	v_mul_f32_e32 v71, 0xbfb8aa3b, v71
	v_exp_f32_e32 v68, v68
	v_exp_f32_e32 v64, v64
	v_exp_f32_e32 v69, v69
	v_exp_f32_e32 v65, v65
	v_exp_f32_e32 v70, v70
	v_exp_f32_e32 v66, v66
	v_exp_f32_e32 v67, v67
	v_exp_f32_e32 v71, v71
	v_add_f32_e32 v68, 1.0, v68
	v_add_f32_e32 v64, 1.0, v64
	v_add_f32_e32 v69, 1.0, v69
	v_add_f32_e32 v65, 1.0, v65
	v_add_f32_e32 v70, 1.0, v70
	v_add_f32_e32 v66, 1.0, v66
	v_add_f32_e32 v67, 1.0, v67
	v_add_f32_e32 v71, 1.0, v71
	v_rcp_f32_e32 v68, v68
	v_rcp_f32_e32 v64, v64
	v_rcp_f32_e32 v65, v65
	v_rcp_f32_e32 v70, v70
	v_rcp_f32_e32 v66, v66
	v_rcp_f32_e32 v67, v67
	v_rcp_f32_e32 v71, v71
	v_rcp_f32_e32 v69, v69
	s_nop 0
	v_cvt_pk_f16_f32 v67, v66, v67
	v_cvt_pk_f16_f32 v66, v64, v65
	v_cvt_pk_f16_f32 v65, v70, v71
	v_cvt_pk_f16_f32 v64, v68, v69
	global_store_dwordx4 v159, v[64:67], s[4:5] offset:256 sc1
	v_mul_f32_e32 v60, 0xbfb8aa3b, v60
	v_mul_f32_e32 v56, 0xbfb8aa3b, v56
	v_mul_f32_e32 v61, 0xbfb8aa3b, v61
	v_mul_f32_e32 v57, 0xbfb8aa3b, v57
	v_mul_f32_e32 v62, 0xbfb8aa3b, v62
	v_mul_f32_e32 v58, 0xbfb8aa3b, v58
	v_mul_f32_e32 v59, 0xbfb8aa3b, v59
	v_mul_f32_e32 v63, 0xbfb8aa3b, v63
	v_exp_f32_e32 v60, v60
	v_exp_f32_e32 v56, v56
	v_exp_f32_e32 v61, v61
	v_exp_f32_e32 v57, v57
	v_exp_f32_e32 v62, v62
	v_exp_f32_e32 v58, v58
	v_exp_f32_e32 v59, v59
	v_exp_f32_e32 v63, v63
	v_add_f32_e32 v60, 1.0, v60
	v_add_f32_e32 v56, 1.0, v56
	v_add_f32_e32 v61, 1.0, v61
	v_add_f32_e32 v57, 1.0, v57
	v_add_f32_e32 v62, 1.0, v62
	v_add_f32_e32 v58, 1.0, v58
	v_add_f32_e32 v59, 1.0, v59
	v_add_f32_e32 v63, 1.0, v63
	v_rcp_f32_e32 v60, v60
	v_rcp_f32_e32 v56, v56
	v_rcp_f32_e32 v57, v57
	v_rcp_f32_e32 v62, v62
	v_rcp_f32_e32 v58, v58
	v_rcp_f32_e32 v59, v59
	v_rcp_f32_e32 v63, v63
	v_rcp_f32_e32 v61, v61
	s_nop 0
	v_cvt_pk_f16_f32 v59, v58, v59
	v_cvt_pk_f16_f32 v58, v56, v57
	v_cvt_pk_f16_f32 v57, v62, v63
	v_cvt_pk_f16_f32 v56, v60, v61
	global_store_dwordx4 v160, v[56:59], s[4:5] sc1
	v_mul_f32_e32 v52, 0xbfb8aa3b, v52
	v_mul_f32_e32 v48, 0xbfb8aa3b, v48
	v_mul_f32_e32 v53, 0xbfb8aa3b, v53
	v_mul_f32_e32 v49, 0xbfb8aa3b, v49
	v_mul_f32_e32 v54, 0xbfb8aa3b, v54
	v_mul_f32_e32 v50, 0xbfb8aa3b, v50
	v_mul_f32_e32 v51, 0xbfb8aa3b, v51
	v_mul_f32_e32 v55, 0xbfb8aa3b, v55
	v_exp_f32_e32 v52, v52
	v_exp_f32_e32 v48, v48
	v_exp_f32_e32 v53, v53
	v_exp_f32_e32 v49, v49
	v_exp_f32_e32 v54, v54
	v_exp_f32_e32 v50, v50
	v_exp_f32_e32 v51, v51
	v_exp_f32_e32 v55, v55
	v_add_f32_e32 v52, 1.0, v52
	v_add_f32_e32 v48, 1.0, v48
	v_add_f32_e32 v53, 1.0, v53
	v_add_f32_e32 v49, 1.0, v49
	v_add_f32_e32 v54, 1.0, v54
	v_add_f32_e32 v50, 1.0, v50
	v_add_f32_e32 v51, 1.0, v51
	v_add_f32_e32 v55, 1.0, v55
	v_rcp_f32_e32 v52, v52
	v_rcp_f32_e32 v48, v48
	v_rcp_f32_e32 v49, v49
	v_rcp_f32_e32 v54, v54
	v_rcp_f32_e32 v50, v50
	v_rcp_f32_e32 v51, v51
	v_rcp_f32_e32 v55, v55
	v_rcp_f32_e32 v53, v53
	s_nop 0
	v_cvt_pk_f16_f32 v51, v50, v51
	v_cvt_pk_f16_f32 v50, v48, v49
	v_cvt_pk_f16_f32 v49, v54, v55
	v_cvt_pk_f16_f32 v48, v52, v53
	global_store_dwordx4 v160, v[48:51], s[4:5] offset:256 sc1
	v_mul_f32_e32 v44, 0xbfb8aa3b, v44
	v_mul_f32_e32 v40, 0xbfb8aa3b, v40
	v_mul_f32_e32 v45, 0xbfb8aa3b, v45
	v_mul_f32_e32 v41, 0xbfb8aa3b, v41
	v_mul_f32_e32 v46, 0xbfb8aa3b, v46
	v_mul_f32_e32 v42, 0xbfb8aa3b, v42
	v_mul_f32_e32 v43, 0xbfb8aa3b, v43
	v_mul_f32_e32 v47, 0xbfb8aa3b, v47
	v_exp_f32_e32 v44, v44
	v_exp_f32_e32 v40, v40
	v_exp_f32_e32 v45, v45
	v_exp_f32_e32 v41, v41
	v_exp_f32_e32 v46, v46
	v_exp_f32_e32 v42, v42
	v_exp_f32_e32 v43, v43
	v_exp_f32_e32 v47, v47
	v_add_f32_e32 v44, 1.0, v44
	v_add_f32_e32 v40, 1.0, v40
	v_add_f32_e32 v45, 1.0, v45
	v_add_f32_e32 v41, 1.0, v41
	v_add_f32_e32 v46, 1.0, v46
	v_add_f32_e32 v42, 1.0, v42
	v_add_f32_e32 v43, 1.0, v43
	v_add_f32_e32 v47, 1.0, v47
	v_rcp_f32_e32 v44, v44
	v_rcp_f32_e32 v40, v40
	v_rcp_f32_e32 v41, v41
	v_rcp_f32_e32 v46, v46
	v_rcp_f32_e32 v42, v42
	v_rcp_f32_e32 v43, v43
	v_rcp_f32_e32 v47, v47
	v_rcp_f32_e32 v45, v45
	s_nop 0
	v_cvt_pk_f16_f32 v43, v42, v43
	v_cvt_pk_f16_f32 v42, v40, v41
	v_cvt_pk_f16_f32 v41, v46, v47
	v_cvt_pk_f16_f32 v40, v44, v45
	global_store_dwordx4 v161, v[40:43], s[4:5] sc1
	v_mul_f32_e32 v36, 0xbfb8aa3b, v36
	v_mul_f32_e32 v32, 0xbfb8aa3b, v32
	v_mul_f32_e32 v37, 0xbfb8aa3b, v37
	v_mul_f32_e32 v33, 0xbfb8aa3b, v33
	v_mul_f32_e32 v38, 0xbfb8aa3b, v38
	v_mul_f32_e32 v34, 0xbfb8aa3b, v34
	v_mul_f32_e32 v35, 0xbfb8aa3b, v35
	v_mul_f32_e32 v39, 0xbfb8aa3b, v39
	v_exp_f32_e32 v36, v36
	v_exp_f32_e32 v32, v32
	v_exp_f32_e32 v37, v37
	v_exp_f32_e32 v33, v33
	v_exp_f32_e32 v38, v38
	v_exp_f32_e32 v34, v34
	v_exp_f32_e32 v35, v35
	v_exp_f32_e32 v39, v39
	v_add_f32_e32 v36, 1.0, v36
	v_add_f32_e32 v32, 1.0, v32
	v_add_f32_e32 v37, 1.0, v37
	v_add_f32_e32 v33, 1.0, v33
	v_add_f32_e32 v38, 1.0, v38
	v_add_f32_e32 v34, 1.0, v34
	v_add_f32_e32 v35, 1.0, v35
	v_add_f32_e32 v39, 1.0, v39
	v_rcp_f32_e32 v36, v36
	v_rcp_f32_e32 v32, v32
	v_rcp_f32_e32 v33, v33
	v_rcp_f32_e32 v38, v38
	v_rcp_f32_e32 v34, v34
	v_rcp_f32_e32 v35, v35
	v_rcp_f32_e32 v39, v39
	v_rcp_f32_e32 v37, v37
	s_nop 0
	v_cvt_pk_f16_f32 v35, v34, v35
	v_cvt_pk_f16_f32 v34, v32, v33
	v_cvt_pk_f16_f32 v33, v38, v39
	v_cvt_pk_f16_f32 v32, v36, v37
	global_store_dwordx4 v161, v[32:35], s[4:5] offset:256 sc1
	v_mul_f32_e32 v28, 0xbfb8aa3b, v28
	v_mul_f32_e32 v24, 0xbfb8aa3b, v24
	v_mul_f32_e32 v29, 0xbfb8aa3b, v29
	v_mul_f32_e32 v25, 0xbfb8aa3b, v25
	v_mul_f32_e32 v30, 0xbfb8aa3b, v30
	v_mul_f32_e32 v26, 0xbfb8aa3b, v26
	v_mul_f32_e32 v27, 0xbfb8aa3b, v27
	v_mul_f32_e32 v31, 0xbfb8aa3b, v31
	v_exp_f32_e32 v28, v28
	v_exp_f32_e32 v24, v24
	v_exp_f32_e32 v29, v29
	v_exp_f32_e32 v25, v25
	v_exp_f32_e32 v30, v30
	v_exp_f32_e32 v26, v26
	v_exp_f32_e32 v27, v27
	v_exp_f32_e32 v31, v31
	v_add_f32_e32 v28, 1.0, v28
	v_add_f32_e32 v24, 1.0, v24
	v_add_f32_e32 v29, 1.0, v29
	v_add_f32_e32 v25, 1.0, v25
	v_add_f32_e32 v30, 1.0, v30
	v_add_f32_e32 v26, 1.0, v26
	v_add_f32_e32 v27, 1.0, v27
	v_add_f32_e32 v31, 1.0, v31
	v_rcp_f32_e32 v28, v28
	v_rcp_f32_e32 v24, v24
	v_rcp_f32_e32 v25, v25
	v_rcp_f32_e32 v30, v30
	v_rcp_f32_e32 v26, v26
	v_rcp_f32_e32 v27, v27
	v_rcp_f32_e32 v31, v31
	v_rcp_f32_e32 v29, v29
	s_nop 0
	v_cvt_pk_f16_f32 v27, v26, v27
	v_cvt_pk_f16_f32 v26, v24, v25
	v_cvt_pk_f16_f32 v25, v30, v31
	v_cvt_pk_f16_f32 v24, v28, v29
	global_store_dwordx4 v162, v[24:27], s[4:5] sc1
	v_mul_f32_e32 v20, 0xbfb8aa3b, v20
	v_mul_f32_e32 v16, 0xbfb8aa3b, v16
	v_mul_f32_e32 v21, 0xbfb8aa3b, v21
	v_mul_f32_e32 v17, 0xbfb8aa3b, v17
	v_mul_f32_e32 v22, 0xbfb8aa3b, v22
	v_mul_f32_e32 v18, 0xbfb8aa3b, v18
	v_mul_f32_e32 v19, 0xbfb8aa3b, v19
	v_mul_f32_e32 v23, 0xbfb8aa3b, v23
	v_exp_f32_e32 v20, v20
	v_exp_f32_e32 v16, v16
	v_exp_f32_e32 v21, v21
	v_exp_f32_e32 v17, v17
	v_exp_f32_e32 v22, v22
	v_exp_f32_e32 v18, v18
	v_exp_f32_e32 v19, v19
	v_exp_f32_e32 v23, v23
	v_add_f32_e32 v20, 1.0, v20
	v_add_f32_e32 v16, 1.0, v16
	v_add_f32_e32 v21, 1.0, v21
	v_add_f32_e32 v17, 1.0, v17
	v_add_f32_e32 v22, 1.0, v22
	v_add_f32_e32 v18, 1.0, v18
	v_add_f32_e32 v19, 1.0, v19
	v_add_f32_e32 v23, 1.0, v23
	v_rcp_f32_e32 v20, v20
	v_rcp_f32_e32 v16, v16
	v_rcp_f32_e32 v17, v17
	v_rcp_f32_e32 v22, v22
	v_rcp_f32_e32 v18, v18
	v_rcp_f32_e32 v19, v19
	v_rcp_f32_e32 v23, v23
	v_rcp_f32_e32 v21, v21
	s_nop 0
	v_cvt_pk_f16_f32 v19, v18, v19
	v_cvt_pk_f16_f32 v18, v16, v17
	v_cvt_pk_f16_f32 v17, v22, v23
	v_cvt_pk_f16_f32 v16, v20, v21
	global_store_dwordx4 v162, v[16:19], s[4:5] offset:256 sc1
	v_mul_f32_e32 v12, 0xbfb8aa3b, v12
	v_mul_f32_e32 v8, 0xbfb8aa3b, v8
	v_mul_f32_e32 v13, 0xbfb8aa3b, v13
	v_mul_f32_e32 v9, 0xbfb8aa3b, v9
	v_mul_f32_e32 v14, 0xbfb8aa3b, v14
	v_mul_f32_e32 v10, 0xbfb8aa3b, v10
	v_mul_f32_e32 v11, 0xbfb8aa3b, v11
	v_mul_f32_e32 v15, 0xbfb8aa3b, v15
	v_exp_f32_e32 v12, v12
	v_exp_f32_e32 v8, v8
	v_exp_f32_e32 v13, v13
	v_exp_f32_e32 v9, v9
	v_exp_f32_e32 v14, v14
	v_exp_f32_e32 v10, v10
	v_exp_f32_e32 v11, v11
	v_exp_f32_e32 v15, v15
	v_add_f32_e32 v12, 1.0, v12
	v_add_f32_e32 v8, 1.0, v8
	v_add_f32_e32 v13, 1.0, v13
	v_add_f32_e32 v9, 1.0, v9
	v_add_f32_e32 v14, 1.0, v14
	v_add_f32_e32 v10, 1.0, v10
	v_add_f32_e32 v11, 1.0, v11
	v_add_f32_e32 v15, 1.0, v15
	v_rcp_f32_e32 v12, v12
	v_rcp_f32_e32 v8, v8
	v_rcp_f32_e32 v9, v9
	v_rcp_f32_e32 v14, v14
	v_rcp_f32_e32 v10, v10
	v_rcp_f32_e32 v11, v11
	v_rcp_f32_e32 v15, v15
	v_rcp_f32_e32 v13, v13
	s_nop 0
	v_cvt_pk_f16_f32 v11, v10, v11
	v_cvt_pk_f16_f32 v10, v8, v9
	v_cvt_pk_f16_f32 v9, v14, v15
	v_cvt_pk_f16_f32 v8, v12, v13
	global_store_dwordx4 v163, v[8:11], s[4:5] sc1
	v_mul_f32_e32 v4, 0xbfb8aa3b, v4
	v_mul_f32_e32 v0, 0xbfb8aa3b, v0
	v_mul_f32_e32 v5, 0xbfb8aa3b, v5
	v_mul_f32_e32 v1, 0xbfb8aa3b, v1
	v_mul_f32_e32 v6, 0xbfb8aa3b, v6
	v_mul_f32_e32 v2, 0xbfb8aa3b, v2
	v_mul_f32_e32 v3, 0xbfb8aa3b, v3
	v_mul_f32_e32 v7, 0xbfb8aa3b, v7
	v_exp_f32_e32 v4, v4
	v_exp_f32_e32 v0, v0
	v_exp_f32_e32 v5, v5
	v_exp_f32_e32 v1, v1
	v_exp_f32_e32 v6, v6
	v_exp_f32_e32 v2, v2
	v_exp_f32_e32 v3, v3
	v_exp_f32_e32 v7, v7
	v_add_f32_e32 v4, 1.0, v4
	v_add_f32_e32 v0, 1.0, v0
	v_add_f32_e32 v5, 1.0, v5
	v_add_f32_e32 v1, 1.0, v1
	v_add_f32_e32 v6, 1.0, v6
	v_add_f32_e32 v2, 1.0, v2
	v_add_f32_e32 v3, 1.0, v3
	v_add_f32_e32 v7, 1.0, v7
	v_rcp_f32_e32 v4, v4
	v_rcp_f32_e32 v0, v0
	v_rcp_f32_e32 v1, v1
	v_rcp_f32_e32 v6, v6
	v_rcp_f32_e32 v2, v2
	v_rcp_f32_e32 v3, v3
	v_rcp_f32_e32 v7, v7
	v_rcp_f32_e32 v5, v5
	s_nop 0
	v_cvt_pk_f16_f32 v3, v2, v3
	v_cvt_pk_f16_f32 v2, v0, v1
	v_cvt_pk_f16_f32 v1, v6, v7
	v_cvt_pk_f16_f32 v0, v4, v5
	global_store_dwordx4 v163, v[0:3], s[4:5] offset:256 sc1
	s_branch .LBB0_1145
.Lsh_k3:
	v_mov_b32_e32 v156, v136
	v_add_u32_e32 v157, 0x8000, v136
	v_add_u32_e32 v158, 0x10000, v136
	v_add_u32_e32 v159, 0x18000, v136
	v_add_u32_e32 v160, 0x40000, v136
	v_add_u32_e32 v161, 0x48000, v136
	v_add_u32_e32 v162, 0x50000, v136
	v_add_u32_e32 v163, 0x58000, v136
	global_load_dwordx4 v[164:167], v156, s[44:45]
	global_load_dwordx4 v[168:171], v156, s[44:45] offset:256
	global_load_dwordx4 v[172:175], v157, s[44:45]
	global_load_dwordx4 v[176:179], v157, s[44:45] offset:256
	global_load_dwordx4 v[180:183], v158, s[44:45]
	global_load_dwordx4 v[184:187], v158, s[44:45] offset:256
	global_load_dwordx4 v[188:191], v159, s[44:45]
	global_load_dwordx4 v[192:195], v159, s[44:45] offset:256
	s_waitcnt vmcnt(7)
	v_cvt_f32_f16_e32 v196, v164
	v_cvt_f32_f16_sdwa v197, v164 dst_sel:DWORD dst_unused:UNUSED_PAD src0_sel:WORD_1
	v_cvt_f32_f16_e32 v198, v165
	v_cvt_f32_f16_sdwa v199, v165 dst_sel:DWORD dst_unused:UNUSED_PAD src0_sel:WORD_1
	v_cvt_f32_f16_e32 v200, v166
	v_cvt_f32_f16_sdwa v201, v166 dst_sel:DWORD dst_unused:UNUSED_PAD src0_sel:WORD_1
	v_cvt_f32_f16_e32 v202, v167
	v_cvt_f32_f16_sdwa v203, v167 dst_sel:DWORD dst_unused:UNUSED_PAD src0_sel:WORD_1
	v_pk_mul_f32 v[124:125], v[124:125], v[196:197]
	v_pk_mul_f32 v[126:127], v[126:127], v[198:199]
	v_pk_mul_f32 v[120:121], v[120:121], v[200:201]
	v_pk_mul_f32 v[122:123], v[122:123], v[202:203]
	v_cvt_pk_f16_f32 v164, v124, v125
	v_cvt_pk_f16_f32 v165, v126, v127
	v_cvt_pk_f16_f32 v166, v120, v121
	v_cvt_pk_f16_f32 v167, v122, v123
	global_store_dwordx4 v156, v[164:167], s[44:45] sc1
	s_nop 1
	global_load_dwordx4 v[164:167], v160, s[44:45]
	s_waitcnt vmcnt(8)
	v_cvt_f32_f16_e32 v196, v168
	v_cvt_f32_f16_sdwa v197, v168 dst_sel:DWORD dst_unused:UNUSED_PAD src0_sel:WORD_1
	v_cvt_f32_f16_e32 v198, v169
	v_cvt_f32_f16_sdwa v199, v169 dst_sel:DWORD dst_unused:UNUSED_PAD src0_sel:WORD_1
	v_cvt_f32_f16_e32 v200, v170
	v_cvt_f32_f16_sdwa v201, v170 dst_sel:DWORD dst_unused:UNUSED_PAD src0_sel:WORD_1
	v_cvt_f32_f16_e32 v202, v171
	v_cvt_f32_f16_sdwa v203, v171 dst_sel:DWORD dst_unused:UNUSED_PAD src0_sel:WORD_1
	v_pk_mul_f32 v[116:117], v[116:117], v[196:197]
	v_pk_mul_f32 v[118:119], v[118:119], v[198:199]
	v_pk_mul_f32 v[112:113], v[112:113], v[200:201]
	v_pk_mul_f32 v[114:115], v[114:115], v[202:203]
	v_cvt_pk_f16_f32 v168, v116, v117
	v_cvt_pk_f16_f32 v169, v118, v119
	v_cvt_pk_f16_f32 v170, v112, v113
	v_cvt_pk_f16_f32 v171, v114, v115
	global_store_dwordx4 v156, v[168:171], s[44:45] offset:256 sc1
	s_nop 1
	global_load_dwordx4 v[168:171], v160, s[44:45] offset:256
	s_waitcnt vmcnt(9)
	v_cvt_f32_f16_e32 v196, v172
	v_cvt_f32_f16_sdwa v197, v172 dst_sel:DWORD dst_unused:UNUSED_PAD src0_sel:WORD_1
	v_cvt_f32_f16_e32 v198, v173
	v_cvt_f32_f16_sdwa v199, v173 dst_sel:DWORD dst_unused:UNUSED_PAD src0_sel:WORD_1
	v_cvt_f32_f16_e32 v200, v174
	v_cvt_f32_f16_sdwa v201, v174 dst_sel:DWORD dst_unused:UNUSED_PAD src0_sel:WORD_1
	v_cvt_f32_f16_e32 v202, v175
	v_cvt_f32_f16_sdwa v203, v175 dst_sel:DWORD dst_unused:UNUSED_PAD src0_sel:WORD_1
	v_pk_mul_f32 v[108:109], v[108:109], v[196:197]
	v_pk_mul_f32 v[110:111], v[110:111], v[198:199]
	v_pk_mul_f32 v[104:105], v[104:105], v[200:201]
	v_pk_mul_f32 v[106:107], v[106:107], v[202:203]
	v_cvt_pk_f16_f32 v172, v108, v109
	v_cvt_pk_f16_f32 v173, v110, v111
	v_cvt_pk_f16_f32 v174, v104, v105
	v_cvt_pk_f16_f32 v175, v106, v107
	global_store_dwordx4 v157, v[172:175], s[44:45] sc1
	s_nop 1
	global_load_dwordx4 v[172:175], v161, s[44:45]
	s_waitcnt vmcnt(10)
	v_cvt_f32_f16_e32 v196, v176
	v_cvt_f32_f16_sdwa v197, v176 dst_sel:DWORD dst_unused:UNUSED_PAD src0_sel:WORD_1
	v_cvt_f32_f16_e32 v198, v177
	v_cvt_f32_f16_sdwa v199, v177 dst_sel:DWORD dst_unused:UNUSED_PAD src0_sel:WORD_1
	v_cvt_f32_f16_e32 v200, v178
	v_cvt_f32_f16_sdwa v201, v178 dst_sel:DWORD dst_unused:UNUSED_PAD src0_sel:WORD_1
	v_cvt_f32_f16_e32 v202, v179
	v_cvt_f32_f16_sdwa v203, v179 dst_sel:DWORD dst_unused:UNUSED_PAD src0_sel:WORD_1
	v_pk_mul_f32 v[100:101], v[100:101], v[196:197]
	v_pk_mul_f32 v[102:103], v[102:103], v[198:199]
	v_pk_mul_f32 v[96:97], v[96:97], v[200:201]
	v_pk_mul_f32 v[98:99], v[98:99], v[202:203]
	v_cvt_pk_f16_f32 v176, v100, v101
	v_cvt_pk_f16_f32 v177, v102, v103
	v_cvt_pk_f16_f32 v178, v96, v97
	v_cvt_pk_f16_f32 v179, v98, v99
	global_store_dwordx4 v157, v[176:179], s[44:45] offset:256 sc1
	s_nop 1
	global_load_dwordx4 v[176:179], v161, s[44:45] offset:256
	s_waitcnt vmcnt(11)
	v_cvt_f32_f16_e32 v196, v180
	v_cvt_f32_f16_sdwa v197, v180 dst_sel:DWORD dst_unused:UNUSED_PAD src0_sel:WORD_1
	v_cvt_f32_f16_e32 v198, v181
	v_cvt_f32_f16_sdwa v199, v181 dst_sel:DWORD dst_unused:UNUSED_PAD src0_sel:WORD_1
	v_cvt_f32_f16_e32 v200, v182
	v_cvt_f32_f16_sdwa v201, v182 dst_sel:DWORD dst_unused:UNUSED_PAD src0_sel:WORD_1
	v_cvt_f32_f16_e32 v202, v183
	v_cvt_f32_f16_sdwa v203, v183 dst_sel:DWORD dst_unused:UNUSED_PAD src0_sel:WORD_1
	v_pk_mul_f32 v[92:93], v[92:93], v[196:197]
	v_pk_mul_f32 v[94:95], v[94:95], v[198:199]
	v_pk_mul_f32 v[88:89], v[88:89], v[200:201]
	v_pk_mul_f32 v[90:91], v[90:91], v[202:203]
	v_cvt_pk_f16_f32 v180, v92, v93
	v_cvt_pk_f16_f32 v181, v94, v95
	v_cvt_pk_f16_f32 v182, v88, v89
	v_cvt_pk_f16_f32 v183, v90, v91
	global_store_dwordx4 v158, v[180:183], s[44:45] sc1
	s_nop 1
	global_load_dwordx4 v[180:183], v162, s[44:45]
	s_waitcnt vmcnt(12)
	v_cvt_f32_f16_e32 v196, v184
	v_cvt_f32_f16_sdwa v197, v184 dst_sel:DWORD dst_unused:UNUSED_PAD src0_sel:WORD_1
	v_cvt_f32_f16_e32 v198, v185
	v_cvt_f32_f16_sdwa v199, v185 dst_sel:DWORD dst_unused:UNUSED_PAD src0_sel:WORD_1
	v_cvt_f32_f16_e32 v200, v186
	v_cvt_f32_f16_sdwa v201, v186 dst_sel:DWORD dst_unused:UNUSED_PAD src0_sel:WORD_1
	v_cvt_f32_f16_e32 v202, v187
	v_cvt_f32_f16_sdwa v203, v187 dst_sel:DWORD dst_unused:UNUSED_PAD src0_sel:WORD_1
	v_pk_mul_f32 v[84:85], v[84:85], v[196:197]
	v_pk_mul_f32 v[86:87], v[86:87], v[198:199]
	v_pk_mul_f32 v[80:81], v[80:81], v[200:201]
	v_pk_mul_f32 v[82:83], v[82:83], v[202:203]
	v_cvt_pk_f16_f32 v184, v84, v85
	v_cvt_pk_f16_f32 v185, v86, v87
	v_cvt_pk_f16_f32 v186, v80, v81
	v_cvt_pk_f16_f32 v187, v82, v83
	global_store_dwordx4 v158, v[184:187], s[44:45] offset:256 sc1
	s_nop 1
	global_load_dwordx4 v[184:187], v162, s[44:45] offset:256
	s_waitcnt vmcnt(13)
	v_cvt_f32_f16_e32 v196, v188
	v_cvt_f32_f16_sdwa v197, v188 dst_sel:DWORD dst_unused:UNUSED_PAD src0_sel:WORD_1
	v_cvt_f32_f16_e32 v198, v189
	v_cvt_f32_f16_sdwa v199, v189 dst_sel:DWORD dst_unused:UNUSED_PAD src0_sel:WORD_1
	v_cvt_f32_f16_e32 v200, v190
	v_cvt_f32_f16_sdwa v201, v190 dst_sel:DWORD dst_unused:UNUSED_PAD src0_sel:WORD_1
	v_cvt_f32_f16_e32 v202, v191
	v_cvt_f32_f16_sdwa v203, v191 dst_sel:DWORD dst_unused:UNUSED_PAD src0_sel:WORD_1
	v_pk_mul_f32 v[76:77], v[76:77], v[196:197]
	v_pk_mul_f32 v[78:79], v[78:79], v[198:199]
	v_pk_mul_f32 v[72:73], v[72:73], v[200:201]
	v_pk_mul_f32 v[74:75], v[74:75], v[202:203]
	v_cvt_pk_f16_f32 v188, v76, v77
	v_cvt_pk_f16_f32 v189, v78, v79
	v_cvt_pk_f16_f32 v190, v72, v73
	v_cvt_pk_f16_f32 v191, v74, v75
	global_store_dwordx4 v159, v[188:191], s[44:45] sc1
	s_nop 1
	global_load_dwordx4 v[188:191], v163, s[44:45]
	s_waitcnt vmcnt(14)
	v_cvt_f32_f16_e32 v196, v192
	v_cvt_f32_f16_sdwa v197, v192 dst_sel:DWORD dst_unused:UNUSED_PAD src0_sel:WORD_1
	v_cvt_f32_f16_e32 v198, v193
	v_cvt_f32_f16_sdwa v199, v193 dst_sel:DWORD dst_unused:UNUSED_PAD src0_sel:WORD_1
	v_cvt_f32_f16_e32 v200, v194
	v_cvt_f32_f16_sdwa v201, v194 dst_sel:DWORD dst_unused:UNUSED_PAD src0_sel:WORD_1
	v_cvt_f32_f16_e32 v202, v195
	v_cvt_f32_f16_sdwa v203, v195 dst_sel:DWORD dst_unused:UNUSED_PAD src0_sel:WORD_1
	v_pk_mul_f32 v[68:69], v[68:69], v[196:197]
	v_pk_mul_f32 v[70:71], v[70:71], v[198:199]
	v_pk_mul_f32 v[64:65], v[64:65], v[200:201]
	v_pk_mul_f32 v[66:67], v[66:67], v[202:203]
	v_cvt_pk_f16_f32 v192, v68, v69
	v_cvt_pk_f16_f32 v193, v70, v71
	v_cvt_pk_f16_f32 v194, v64, v65
	v_cvt_pk_f16_f32 v195, v66, v67
	global_store_dwordx4 v159, v[192:195], s[44:45] offset:256 sc1
	s_nop 1
	global_load_dwordx4 v[192:195], v163, s[44:45] offset:256
	s_waitcnt vmcnt(14)
	v_cvt_f32_f16_e32 v196, v164
	v_cvt_f32_f16_sdwa v197, v164 dst_sel:DWORD dst_unused:UNUSED_PAD src0_sel:WORD_1
	v_cvt_f32_f16_e32 v198, v165
	v_cvt_f32_f16_sdwa v199, v165 dst_sel:DWORD dst_unused:UNUSED_PAD src0_sel:WORD_1
	v_cvt_f32_f16_e32 v200, v166
	v_cvt_f32_f16_sdwa v201, v166 dst_sel:DWORD dst_unused:UNUSED_PAD src0_sel:WORD_1
	v_cvt_f32_f16_e32 v202, v167
	v_cvt_f32_f16_sdwa v203, v167 dst_sel:DWORD dst_unused:UNUSED_PAD src0_sel:WORD_1
	v_pk_mul_f32 v[60:61], v[60:61], v[196:197]
	v_pk_mul_f32 v[62:63], v[62:63], v[198:199]
	v_pk_mul_f32 v[56:57], v[56:57], v[200:201]
	v_pk_mul_f32 v[58:59], v[58:59], v[202:203]
	v_cvt_pk_f16_f32 v164, v60, v61
	v_cvt_pk_f16_f32 v165, v62, v63
	v_cvt_pk_f16_f32 v166, v56, v57
	v_cvt_pk_f16_f32 v167, v58, v59
	global_store_dwordx4 v160, v[164:167], s[44:45] sc1
	s_nop 1
	s_waitcnt vmcnt(13)
	v_cvt_f32_f16_e32 v196, v168
	v_cvt_f32_f16_sdwa v197, v168 dst_sel:DWORD dst_unused:UNUSED_PAD src0_sel:WORD_1
	v_cvt_f32_f16_e32 v198, v169
	v_cvt_f32_f16_sdwa v199, v169 dst_sel:DWORD dst_unused:UNUSED_PAD src0_sel:WORD_1
	v_cvt_f32_f16_e32 v200, v170
	v_cvt_f32_f16_sdwa v201, v170 dst_sel:DWORD dst_unused:UNUSED_PAD src0_sel:WORD_1
	v_cvt_f32_f16_e32 v202, v171
	v_cvt_f32_f16_sdwa v203, v171 dst_sel:DWORD dst_unused:UNUSED_PAD src0_sel:WORD_1
	v_pk_mul_f32 v[52:53], v[52:53], v[196:197]
	v_pk_mul_f32 v[54:55], v[54:55], v[198:199]
	v_pk_mul_f32 v[48:49], v[48:49], v[200:201]
	v_pk_mul_f32 v[50:51], v[50:51], v[202:203]
	v_cvt_pk_f16_f32 v168, v52, v53
	v_cvt_pk_f16_f32 v169, v54, v55
	v_cvt_pk_f16_f32 v170, v48, v49
	v_cvt_pk_f16_f32 v171, v50, v51
	global_store_dwordx4 v160, v[168:171], s[44:45] offset:256 sc1
	s_nop 1
	s_waitcnt vmcnt(12)
	v_cvt_f32_f16_e32 v196, v172
	v_cvt_f32_f16_sdwa v197, v172 dst_sel:DWORD dst_unused:UNUSED_PAD src0_sel:WORD_1
	v_cvt_f32_f16_e32 v198, v173
	v_cvt_f32_f16_sdwa v199, v173 dst_sel:DWORD dst_unused:UNUSED_PAD src0_sel:WORD_1
	v_cvt_f32_f16_e32 v200, v174
	v_cvt_f32_f16_sdwa v201, v174 dst_sel:DWORD dst_unused:UNUSED_PAD src0_sel:WORD_1
	v_cvt_f32_f16_e32 v202, v175
	v_cvt_f32_f16_sdwa v203, v175 dst_sel:DWORD dst_unused:UNUSED_PAD src0_sel:WORD_1
	v_pk_mul_f32 v[44:45], v[44:45], v[196:197]
	v_pk_mul_f32 v[46:47], v[46:47], v[198:199]
	v_pk_mul_f32 v[40:41], v[40:41], v[200:201]
	v_pk_mul_f32 v[42:43], v[42:43], v[202:203]
	v_cvt_pk_f16_f32 v172, v44, v45
	v_cvt_pk_f16_f32 v173, v46, v47
	v_cvt_pk_f16_f32 v174, v40, v41
	v_cvt_pk_f16_f32 v175, v42, v43
	global_store_dwordx4 v161, v[172:175], s[44:45] sc1
	s_nop 1
	s_waitcnt vmcnt(11)
	v_cvt_f32_f16_e32 v196, v176
	v_cvt_f32_f16_sdwa v197, v176 dst_sel:DWORD dst_unused:UNUSED_PAD src0_sel:WORD_1
	v_cvt_f32_f16_e32 v198, v177
	v_cvt_f32_f16_sdwa v199, v177 dst_sel:DWORD dst_unused:UNUSED_PAD src0_sel:WORD_1
	v_cvt_f32_f16_e32 v200, v178
	v_cvt_f32_f16_sdwa v201, v178 dst_sel:DWORD dst_unused:UNUSED_PAD src0_sel:WORD_1
	v_cvt_f32_f16_e32 v202, v179
	v_cvt_f32_f16_sdwa v203, v179 dst_sel:DWORD dst_unused:UNUSED_PAD src0_sel:WORD_1
	v_pk_mul_f32 v[36:37], v[36:37], v[196:197]
	v_pk_mul_f32 v[38:39], v[38:39], v[198:199]
	v_pk_mul_f32 v[32:33], v[32:33], v[200:201]
	v_pk_mul_f32 v[34:35], v[34:35], v[202:203]
	v_cvt_pk_f16_f32 v176, v36, v37
	v_cvt_pk_f16_f32 v177, v38, v39
	v_cvt_pk_f16_f32 v178, v32, v33
	v_cvt_pk_f16_f32 v179, v34, v35
	global_store_dwordx4 v161, v[176:179], s[44:45] offset:256 sc1
	s_nop 1
	s_waitcnt vmcnt(10)
	v_cvt_f32_f16_e32 v196, v180
	v_cvt_f32_f16_sdwa v197, v180 dst_sel:DWORD dst_unused:UNUSED_PAD src0_sel:WORD_1
	v_cvt_f32_f16_e32 v198, v181
	v_cvt_f32_f16_sdwa v199, v181 dst_sel:DWORD dst_unused:UNUSED_PAD src0_sel:WORD_1
	v_cvt_f32_f16_e32 v200, v182
	v_cvt_f32_f16_sdwa v201, v182 dst_sel:DWORD dst_unused:UNUSED_PAD src0_sel:WORD_1
	v_cvt_f32_f16_e32 v202, v183
	v_cvt_f32_f16_sdwa v203, v183 dst_sel:DWORD dst_unused:UNUSED_PAD src0_sel:WORD_1
	v_pk_mul_f32 v[28:29], v[28:29], v[196:197]
	v_pk_mul_f32 v[30:31], v[30:31], v[198:199]
	v_pk_mul_f32 v[24:25], v[24:25], v[200:201]
	v_pk_mul_f32 v[26:27], v[26:27], v[202:203]
	v_cvt_pk_f16_f32 v180, v28, v29
	v_cvt_pk_f16_f32 v181, v30, v31
	v_cvt_pk_f16_f32 v182, v24, v25
	v_cvt_pk_f16_f32 v183, v26, v27
	global_store_dwordx4 v162, v[180:183], s[44:45] sc1
	s_nop 1
	s_waitcnt vmcnt(9)
	v_cvt_f32_f16_e32 v196, v184
	v_cvt_f32_f16_sdwa v197, v184 dst_sel:DWORD dst_unused:UNUSED_PAD src0_sel:WORD_1
	v_cvt_f32_f16_e32 v198, v185
	v_cvt_f32_f16_sdwa v199, v185 dst_sel:DWORD dst_unused:UNUSED_PAD src0_sel:WORD_1
	v_cvt_f32_f16_e32 v200, v186
	v_cvt_f32_f16_sdwa v201, v186 dst_sel:DWORD dst_unused:UNUSED_PAD src0_sel:WORD_1
	v_cvt_f32_f16_e32 v202, v187
	v_cvt_f32_f16_sdwa v203, v187 dst_sel:DWORD dst_unused:UNUSED_PAD src0_sel:WORD_1
	v_pk_mul_f32 v[20:21], v[20:21], v[196:197]
	v_pk_mul_f32 v[22:23], v[22:23], v[198:199]
	v_pk_mul_f32 v[16:17], v[16:17], v[200:201]
	v_pk_mul_f32 v[18:19], v[18:19], v[202:203]
	v_cvt_pk_f16_f32 v184, v20, v21
	v_cvt_pk_f16_f32 v185, v22, v23
	v_cvt_pk_f16_f32 v186, v16, v17
	v_cvt_pk_f16_f32 v187, v18, v19
	global_store_dwordx4 v162, v[184:187], s[44:45] offset:256 sc1
	s_nop 1
	s_waitcnt vmcnt(8)
	v_cvt_f32_f16_e32 v196, v188
	v_cvt_f32_f16_sdwa v197, v188 dst_sel:DWORD dst_unused:UNUSED_PAD src0_sel:WORD_1
	v_cvt_f32_f16_e32 v198, v189
	v_cvt_f32_f16_sdwa v199, v189 dst_sel:DWORD dst_unused:UNUSED_PAD src0_sel:WORD_1
	v_cvt_f32_f16_e32 v200, v190
	v_cvt_f32_f16_sdwa v201, v190 dst_sel:DWORD dst_unused:UNUSED_PAD src0_sel:WORD_1
	v_cvt_f32_f16_e32 v202, v191
	v_cvt_f32_f16_sdwa v203, v191 dst_sel:DWORD dst_unused:UNUSED_PAD src0_sel:WORD_1
	v_pk_mul_f32 v[12:13], v[12:13], v[196:197]
	v_pk_mul_f32 v[14:15], v[14:15], v[198:199]
	v_pk_mul_f32 v[8:9], v[8:9], v[200:201]
	v_pk_mul_f32 v[10:11], v[10:11], v[202:203]
	v_cvt_pk_f16_f32 v188, v12, v13
	v_cvt_pk_f16_f32 v189, v14, v15
	v_cvt_pk_f16_f32 v190, v8, v9
	v_cvt_pk_f16_f32 v191, v10, v11
	global_store_dwordx4 v163, v[188:191], s[44:45] sc1
	s_nop 1
	s_waitcnt vmcnt(7)
	v_cvt_f32_f16_e32 v196, v192
	v_cvt_f32_f16_sdwa v197, v192 dst_sel:DWORD dst_unused:UNUSED_PAD src0_sel:WORD_1
	v_cvt_f32_f16_e32 v198, v193
	v_cvt_f32_f16_sdwa v199, v193 dst_sel:DWORD dst_unused:UNUSED_PAD src0_sel:WORD_1
	v_cvt_f32_f16_e32 v200, v194
	v_cvt_f32_f16_sdwa v201, v194 dst_sel:DWORD dst_unused:UNUSED_PAD src0_sel:WORD_1
	v_cvt_f32_f16_e32 v202, v195
	v_cvt_f32_f16_sdwa v203, v195 dst_sel:DWORD dst_unused:UNUSED_PAD src0_sel:WORD_1
	v_pk_mul_f32 v[4:5], v[4:5], v[196:197]
	v_pk_mul_f32 v[6:7], v[6:7], v[198:199]
	v_pk_mul_f32 v[0:1], v[0:1], v[200:201]
	v_pk_mul_f32 v[2:3], v[2:3], v[202:203]
	v_cvt_pk_f16_f32 v192, v4, v5
	v_cvt_pk_f16_f32 v193, v6, v7
	v_cvt_pk_f16_f32 v194, v0, v1
	v_cvt_pk_f16_f32 v195, v2, v3
	global_store_dwordx4 v163, v[192:195], s[44:45] offset:256 sc1
	s_nop 1
	s_branch .LBB0_1145

.LBB0_1432:
	s_lshl_b32 s15, s20, 8
	v_add_u32_e32 v158, s15, v146
	v_min_i32_e32 v160, 0x807f, v158
	v_ashrrev_i32_e32 v161, 31, v160
	v_lshlrev_b64 v[160:161], 6, v[160:161]
	v_lshl_add_u64 v[160:161], v[136:137], 0, v[160:161]
	global_load_dwordx4 v[162:165], v[160:161], off
	v_add_u32_e32 v174, s15, v148
	v_min_i32_e32 v160, 0x807f, v174
	v_ashrrev_i32_e32 v161, 31, v160
	v_lshlrev_b64 v[160:161], 6, v[160:161]
	v_lshl_add_u64 v[160:161], v[136:137], 0, v[160:161]
	global_load_dwordx4 v[166:169], v[160:161], off
	v_and_b32_e32 v160, 64, v156
	v_xor_b32_e32 v159, 16, v156
	v_add_u32_e32 v160, 64, v160
	v_xor_b32_e32 v161, 32, v156
	v_cmp_lt_i32_e32 vcc, v159, v160
	s_lshl_b32 s13, s50, 9
	v_add_u32_e32 v175, s15, v149
	v_cndmask_b32_e32 v159, v156, v159, vcc
	v_cmp_lt_i32_e32 vcc, v161, v160
	v_lshlrev_b32_e32 v160, 2, v159
	v_lshl_add_u32 v171, v158, 11, s13
	v_cndmask_b32_e32 v161, v156, v161, vcc
	v_lshlrev_b32_e32 v159, 2, v161
	v_min_i32_e32 v170, 0x807f, v175
	s_andn2_b64 vcc, exec, s[4:5]
	s_mov_b64 s[4:5], -1
	s_waitcnt vmcnt(0)
	v_mov_b32_e32 v172, v163
	v_mov_b32_e32 v173, v164
	v_mov_b32_e32 v163, v165
	v_pk_add_f32 v[162:163], v[172:173], v[162:163]
	v_or_b32_e32 v165, v171, v147
	v_add_f32_e32 v161, v162, v163
	ds_bpermute_b32 v164, v160, v161
	v_mov_b32_e32 v162, v167
	v_mov_b32_e32 v163, v168
	v_mov_b32_e32 v167, v169
	v_pk_add_f32 v[162:163], v[162:163], v[166:167]
	s_waitcnt lgkmcnt(0)
	v_add_f32_e32 v161, v161, v164
	ds_bpermute_b32 v164, v159, v161
	v_add_f32_e32 v166, v162, v163
	ds_bpermute_b32 v167, v160, v166
	v_ashrrev_i32_e32 v171, 31, v170
	v_lshlrev_b64 v[162:163], 6, v[170:171]
	s_waitcnt lgkmcnt(1)
	v_add_f32_e32 v161, v161, v164
	v_fmamk_f32 v161, v161, 0x3a800000, v157
	v_rsq_f32_e32 v161, v161
	s_waitcnt lgkmcnt(0)
	v_add_f32_e32 v164, v166, v167
	ds_bpermute_b32 v166, v159, v164
	v_mul_f32_e32 v161, 0xbfb8aa3b, v161
	v_mul_f32_e32 v124, v124, v161
	v_mul_f32_e32 v120, v120, v161
	v_mul_f32_e32 v125, v125, v161
	v_mul_f32_e32 v121, v121, v161
	v_mul_f32_e32 v126, v126, v161
	v_mul_f32_e32 v122, v122, v161
	v_mul_f32_e32 v127, v127, v161
	v_mul_f32_e32 v123, v123, v161
	v_exp_f32_e32 v124, v124
	v_exp_f32_e32 v120, v120
	v_exp_f32_e32 v125, v125
	v_exp_f32_e32 v121, v121
	v_exp_f32_e32 v126, v126
	v_exp_f32_e32 v122, v122
	v_exp_f32_e32 v127, v127
	v_exp_f32_e32 v123, v123
	v_mul_f32_e32 v112, v112, v161
	v_mul_f32_e32 v117, v117, v161
	v_mul_f32_e32 v113, v113, v161
	v_mul_f32_e32 v118, v118, v161
	v_mul_f32_e32 v114, v114, v161
	v_mul_f32_e32 v119, v119, v161
	v_mul_f32_e32 v115, v115, v161
	v_exp_f32_e32 v112, v112
	v_exp_f32_e32 v117, v117
	v_exp_f32_e32 v113, v113
	v_exp_f32_e32 v118, v118
	v_exp_f32_e32 v114, v114
	v_exp_f32_e32 v119, v119
	v_exp_f32_e32 v115, v115
	v_add_f32_e32 v124, 1.0, v124
	v_add_f32_e32 v120, 1.0, v120
	v_add_f32_e32 v125, 1.0, v125
	v_add_f32_e32 v121, 1.0, v121
	v_add_f32_e32 v126, 1.0, v126
	v_add_f32_e32 v122, 1.0, v122
	v_add_f32_e32 v127, 1.0, v127
	v_add_f32_e32 v123, 1.0, v123
	v_rcp_f32_e32 v124, v124
	v_rcp_f32_e32 v120, v120
	v_rcp_f32_e32 v125, v125
	v_rcp_f32_e32 v121, v121
	v_rcp_f32_e32 v126, v126
	v_rcp_f32_e32 v122, v122
	v_rcp_f32_e32 v127, v127
	v_rcp_f32_e32 v123, v123
	v_add_f32_e32 v112, 1.0, v112
	v_add_f32_e32 v117, 1.0, v117
	v_add_f32_e32 v113, 1.0, v113
	v_add_f32_e32 v118, 1.0, v118
	v_add_f32_e32 v114, 1.0, v114
	v_add_f32_e32 v119, 1.0, v119
	v_add_f32_e32 v115, 1.0, v115
	v_mul_f32_e32 v116, v116, v161
	v_rcp_f32_e32 v161, v112
	v_rcp_f32_e32 v167, v117
	v_rcp_f32_e32 v117, v113
	v_rcp_f32_e32 v168, v118
	v_rcp_f32_e32 v118, v114
	v_rcp_f32_e32 v169, v119
	v_rcp_f32_e32 v119, v115
	v_cvt_pk_f16_f32 v115, v122, v123
	v_cvt_pk_f16_f32 v114, v120, v121
	v_cvt_pk_f16_f32 v113, v126, v127
	v_cvt_pk_f16_f32 v112, v124, v125
	global_store_dwordx4 v165, v[112:115], s[28:29] sc1
	s_waitcnt lgkmcnt(0)
	v_add_f32_e32 v120, v164, v166
	v_fmamk_f32 v120, v120, 0x3a800000, v157
	v_lshl_add_u64 v[112:113], v[136:137], 0, v[162:163]
	global_load_dwordx4 v[112:115], v[112:113], off
	v_rsq_f32_e32 v120, v120
	v_exp_f32_e32 v116, v116
	v_cvt_pk_f16_f32 v119, v118, v119
	v_cvt_pk_f16_f32 v118, v161, v117
	v_mul_f32_e32 v120, 0xbfb8aa3b, v120
	v_mul_f32_e32 v108, v108, v120
	v_mul_f32_e32 v104, v104, v120
	v_mul_f32_e32 v109, v109, v120
	v_mul_f32_e32 v105, v105, v120
	v_mul_f32_e32 v106, v106, v120
	v_mul_f32_e32 v107, v107, v120
	v_exp_f32_e32 v108, v108
	v_exp_f32_e32 v104, v104
	v_exp_f32_e32 v109, v109
	v_exp_f32_e32 v105, v105
	v_exp_f32_e32 v106, v106
	v_exp_f32_e32 v107, v107
	v_mul_f32_e32 v96, v96, v120
	v_add_f32_e32 v108, 1.0, v108
	v_add_f32_e32 v104, 1.0, v104
	v_add_f32_e32 v109, 1.0, v109
	v_add_f32_e32 v105, 1.0, v105
	v_add_f32_e32 v106, 1.0, v106
	v_add_f32_e32 v107, 1.0, v107
	v_exp_f32_e32 v96, v96
	v_mul_f32_e32 v101, v101, v120
	v_rcp_f32_e32 v108, v108
	v_rcp_f32_e32 v104, v104
	v_rcp_f32_e32 v105, v105
	v_rcp_f32_e32 v106, v106
	v_rcp_f32_e32 v107, v107
	v_rcp_f32_e32 v109, v109
	v_exp_f32_e32 v101, v101
	v_mul_f32_e32 v97, v97, v120
	v_mul_f32_e32 v110, v110, v120
	v_mul_f32_e32 v111, v111, v120
	v_exp_f32_e32 v97, v97
	v_exp_f32_e32 v110, v110
	v_exp_f32_e32 v111, v111
	v_add_f32_e32 v96, 1.0, v96
	v_cvt_pk_f16_f32 v107, v106, v107
	v_cvt_pk_f16_f32 v106, v104, v105
	v_cvt_pk_f16_f32 v104, v108, v109
	v_rcp_f32_e32 v109, v96
	v_add_f32_e32 v96, 1.0, v101
	v_rcp_f32_e32 v101, v96
	v_add_f32_e32 v96, 1.0, v97
	v_mul_f32_e32 v97, v102, v120
	v_add_f32_e32 v110, 1.0, v110
	v_add_f32_e32 v111, 1.0, v111
	v_exp_f32_e32 v97, v97
	v_mul_f32_e32 v98, v98, v120
	v_rcp_f32_e32 v110, v110
	v_rcp_f32_e32 v111, v111
	v_exp_f32_e32 v98, v98
	v_add_f32_e32 v116, 1.0, v116
	v_rcp_f32_e32 v102, v96
	v_add_f32_e32 v96, 1.0, v97
	v_rcp_f32_e32 v116, v116
	v_cvt_pk_f16_f32 v105, v110, v111
	v_rcp_f32_e32 v110, v96
	v_add_f32_e32 v96, 1.0, v98
	v_add_u32_e32 v111, s15, v150
	v_rcp_f32_e32 v98, v96
	v_min_i32_e32 v96, 0x807f, v111
	v_ashrrev_i32_e32 v97, 31, v96
	v_lshl_add_u32 v108, v174, 11, s13
	v_lshlrev_b64 v[96:97], 6, v[96:97]
	v_cvt_pk_f16_f32 v117, v168, v169
	v_cvt_pk_f16_f32 v116, v116, v167
	v_or_b32_e32 v121, 0x100, v165
	v_or_b32_e32 v108, v108, v147
	v_lshl_add_u64 v[96:97], v[136:137], 0, v[96:97]
	global_store_dwordx4 v121, v[116:119], s[28:29] sc1
	global_store_dwordx4 v108, v[104:107], s[28:29] sc1
	global_load_dwordx4 v[104:107], v[96:97], off
	v_mul_f32_e32 v99, v99, v120
	v_exp_f32_e32 v99, v99
	v_mul_f32_e32 v100, v100, v120
	s_waitcnt vmcnt(3)
	v_mov_b32_e32 v96, v113
	v_mov_b32_e32 v97, v114
	v_mov_b32_e32 v113, v115
	v_pk_add_f32 v[96:97], v[96:97], v[112:113]
	v_add_f32_e32 v99, 1.0, v99
	v_add_f32_e32 v96, v96, v97
	ds_bpermute_b32 v97, v160, v96
	v_rcp_f32_e32 v99, v99
	v_mul_f32_e32 v103, v103, v120
	v_exp_f32_e32 v100, v100
	v_exp_f32_e32 v103, v103
	s_waitcnt lgkmcnt(0)
	v_add_f32_e32 v96, v96, v97
	ds_bpermute_b32 v97, v159, v96
	v_cvt_pk_f16_f32 v99, v98, v99
	v_cvt_pk_f16_f32 v98, v109, v102
	v_add_f32_e32 v100, 1.0, v100
	v_add_f32_e32 v103, 1.0, v103
	s_waitcnt lgkmcnt(0)
	v_add_f32_e32 v96, v96, v97
	v_fmamk_f32 v96, v96, 0x3a800000, v157
	v_rsq_f32_e32 v96, v96
	v_rcp_f32_e32 v100, v100
	v_rcp_f32_e32 v103, v103
	v_mul_f32_e32 v102, 0xbfb8aa3b, v96
	v_mul_f32_e32 v92, v92, v102
	v_mul_f32_e32 v88, v88, v102
	v_mul_f32_e32 v93, v93, v102
	v_mul_f32_e32 v89, v89, v102
	v_mul_f32_e32 v90, v90, v102
	v_mul_f32_e32 v91, v91, v102
	v_exp_f32_e32 v92, v92
	v_exp_f32_e32 v88, v88
	v_exp_f32_e32 v93, v93
	v_exp_f32_e32 v89, v89
	v_mul_f32_e32 v94, v94, v102
	v_exp_f32_e32 v90, v90
	v_exp_f32_e32 v91, v91
	v_mul_f32_e32 v95, v95, v102
	v_exp_f32_e32 v94, v94
	v_exp_f32_e32 v95, v95
	v_add_f32_e32 v92, 1.0, v92
	v_add_f32_e32 v88, 1.0, v88
	v_add_f32_e32 v93, 1.0, v93
	v_add_f32_e32 v89, 1.0, v89
	v_add_f32_e32 v90, 1.0, v90
	v_add_f32_e32 v91, 1.0, v91
	v_rcp_f32_e32 v92, v92
	v_rcp_f32_e32 v88, v88
	v_rcp_f32_e32 v89, v89
	v_add_f32_e32 v94, 1.0, v94
	v_rcp_f32_e32 v90, v90
	v_rcp_f32_e32 v91, v91
	v_add_f32_e32 v95, 1.0, v95
	v_rcp_f32_e32 v93, v93
	v_mul_f32_e32 v80, v80, v102
	v_rcp_f32_e32 v94, v94
	v_rcp_f32_e32 v95, v95
	v_exp_f32_e32 v80, v80
	v_mul_f32_e32 v85, v85, v102
	v_exp_f32_e32 v85, v85
	v_mul_f32_e32 v81, v81, v102
	v_exp_f32_e32 v81, v81
	v_cvt_pk_f16_f32 v91, v90, v91
	v_cvt_pk_f16_f32 v90, v88, v89
	v_cvt_pk_f16_f32 v88, v92, v93
	v_lshl_add_u32 v92, v175, 11, s13
	v_cvt_pk_f16_f32 v97, v110, v103
	v_cvt_pk_f16_f32 v96, v100, v101
	v_or_b32_e32 v100, 0x100, v108
	v_cvt_pk_f16_f32 v89, v94, v95
	v_or_b32_e32 v92, v92, v147
	v_add_f32_e32 v80, 1.0, v80
	global_store_dwordx4 v100, v[96:99], s[28:29] sc1
	global_store_dwordx4 v92, v[88:91], s[28:29] sc1
	v_mul_f32_e32 v82, v82, v102
	v_exp_f32_e32 v82, v82
	v_rcp_f32_e32 v88, v80
	v_add_f32_e32 v80, 1.0, v85
	v_rcp_f32_e32 v89, v80
	v_add_f32_e32 v80, 1.0, v81
	v_mul_f32_e32 v81, v86, v102
	v_exp_f32_e32 v81, v81
	v_rcp_f32_e32 v85, v80
	v_add_u32_e32 v95, 0x80, v158
	v_mul_f32_e32 v84, v84, v102
	v_add_f32_e32 v80, 1.0, v81
	v_rcp_f32_e32 v90, v80
	v_add_f32_e32 v80, 1.0, v82
	v_rcp_f32_e32 v86, v80
	v_mul_f32_e32 v80, v87, v102
	v_exp_f32_e32 v82, v80
	v_mul_f32_e32 v80, v83, v102
	v_exp_f32_e32 v83, v80
	s_waitcnt vmcnt(2)
	v_mov_b32_e32 v80, v105
	v_mov_b32_e32 v81, v106
	v_mov_b32_e32 v105, v107
	v_pk_add_f32 v[80:81], v[80:81], v[104:105]
	v_add_f32_e32 v82, 1.0, v82
	v_add_f32_e32 v80, v80, v81
	ds_bpermute_b32 v81, v160, v80
	v_rcp_f32_e32 v91, v82
	v_add_f32_e32 v82, 1.0, v83
	v_rcp_f32_e32 v87, v82
	v_exp_f32_e32 v84, v84
	s_waitcnt lgkmcnt(0)
	v_add_f32_e32 v93, v80, v81
	v_min_i32_e32 v80, 0x807f, v95
	v_ashrrev_i32_e32 v81, 31, v80
	v_lshlrev_b64 v[80:81], 6, v[80:81]
	v_lshl_add_u64 v[80:81], v[136:137], 0, v[80:81]
	global_load_dwordx4 v[80:83], v[80:81], off
	ds_bpermute_b32 v94, v159, v93
	v_cvt_pk_f16_f32 v87, v86, v87
	v_cvt_pk_f16_f32 v86, v88, v85
	v_add_f32_e32 v84, 1.0, v84
	v_rcp_f32_e32 v84, v84
	s_waitcnt lgkmcnt(0)
	v_add_f32_e32 v93, v93, v94
	v_fmamk_f32 v93, v93, 0x3a800000, v157
	v_rsq_f32_e32 v93, v93
	v_cvt_pk_f16_f32 v85, v90, v91
	v_cvt_pk_f16_f32 v84, v84, v89
	v_or_b32_e32 v89, 0x100, v92
	v_mul_f32_e32 v88, 0xbfb8aa3b, v93
	v_mul_f32_e32 v76, v76, v88
	v_mul_f32_e32 v72, v72, v88
	v_mul_f32_e32 v77, v77, v88
	v_mul_f32_e32 v73, v73, v88
	v_mul_f32_e32 v74, v74, v88
	v_mul_f32_e32 v75, v75, v88
	v_exp_f32_e32 v76, v76
	v_exp_f32_e32 v72, v72
	v_exp_f32_e32 v77, v77
	v_exp_f32_e32 v73, v73
	v_exp_f32_e32 v74, v74
	v_exp_f32_e32 v75, v75
	v_mul_f32_e32 v64, v64, v88
	v_add_f32_e32 v76, 1.0, v76
	v_add_f32_e32 v72, 1.0, v72
	v_add_f32_e32 v77, 1.0, v77
	v_add_f32_e32 v73, 1.0, v73
	v_add_f32_e32 v74, 1.0, v74
	v_add_f32_e32 v75, 1.0, v75
	v_exp_f32_e32 v64, v64
	v_mul_f32_e32 v69, v69, v88
	v_rcp_f32_e32 v76, v76
	v_rcp_f32_e32 v72, v72
	v_rcp_f32_e32 v73, v73
	v_rcp_f32_e32 v74, v74
	v_rcp_f32_e32 v75, v75
	v_rcp_f32_e32 v77, v77
	v_exp_f32_e32 v69, v69
	v_mul_f32_e32 v65, v65, v88
	v_mul_f32_e32 v78, v78, v88
	v_mul_f32_e32 v79, v79, v88
	v_exp_f32_e32 v65, v65
	v_exp_f32_e32 v78, v78
	v_exp_f32_e32 v79, v79
	v_add_f32_e32 v64, 1.0, v64
	v_cvt_pk_f16_f32 v75, v74, v75
	v_cvt_pk_f16_f32 v74, v72, v73
	v_cvt_pk_f16_f32 v72, v76, v77
	v_rcp_f32_e32 v77, v64
	v_add_f32_e32 v64, 1.0, v69
	v_rcp_f32_e32 v69, v64
	v_add_f32_e32 v64, 1.0, v65
	v_mul_f32_e32 v65, v70, v88
	v_add_f32_e32 v78, 1.0, v78
	v_add_f32_e32 v79, 1.0, v79
	v_exp_f32_e32 v65, v65
	v_mul_f32_e32 v66, v66, v88
	v_rcp_f32_e32 v78, v78
	v_rcp_f32_e32 v79, v79
	v_exp_f32_e32 v66, v66
	v_rcp_f32_e32 v70, v64
	v_add_f32_e32 v64, 1.0, v65
	v_cvt_pk_f16_f32 v73, v78, v79
	v_rcp_f32_e32 v78, v64
	v_add_f32_e32 v64, 1.0, v66
	v_add_u32_e32 v79, 0x90, v158
	v_rcp_f32_e32 v66, v64
	v_min_i32_e32 v64, 0x807f, v79
	v_ashrrev_i32_e32 v65, 31, v64
	v_lshl_add_u32 v76, v111, 11, s13
	v_lshlrev_b64 v[64:65], 6, v[64:65]
	v_or_b32_e32 v76, v76, v147
	v_lshl_add_u64 v[64:65], v[136:137], 0, v[64:65]
	global_store_dwordx4 v89, v[84:87], s[28:29] sc1
	global_store_dwordx4 v76, v[72:75], s[28:29] sc1
	global_load_dwordx4 v[72:75], v[64:65], off
	v_mul_f32_e32 v67, v67, v88
	s_waitcnt vmcnt(3)
	v_mov_b32_e32 v64, v81
	v_mov_b32_e32 v65, v82
	v_mov_b32_e32 v81, v83
	v_pk_add_f32 v[64:65], v[64:65], v[80:81]
	v_exp_f32_e32 v67, v67
	v_add_f32_e32 v64, v64, v65
	ds_bpermute_b32 v65, v160, v64
	v_mul_f32_e32 v68, v68, v88
	v_add_f32_e32 v67, 1.0, v67
	v_rcp_f32_e32 v67, v67
	v_mul_f32_e32 v71, v71, v88
	s_waitcnt lgkmcnt(0)
	v_add_f32_e32 v64, v64, v65
	ds_bpermute_b32 v65, v159, v64
	v_cvt_pk_f16_f32 v67, v66, v67
	v_cvt_pk_f16_f32 v66, v77, v70
	v_exp_f32_e32 v68, v68
	v_exp_f32_e32 v71, v71
	s_waitcnt lgkmcnt(0)
	v_add_f32_e32 v64, v64, v65
	v_fmamk_f32 v64, v64, 0x3a800000, v157
	v_rsq_f32_e32 v64, v64
	v_add_f32_e32 v68, 1.0, v68
	v_add_f32_e32 v71, 1.0, v71
	v_rcp_f32_e32 v68, v68
	v_mul_f32_e32 v70, 0xbfb8aa3b, v64
	v_mul_f32_e32 v60, v60, v70
	v_mul_f32_e32 v56, v56, v70
	v_mul_f32_e32 v61, v61, v70
	v_mul_f32_e32 v57, v57, v70
	v_mul_f32_e32 v58, v58, v70
	v_mul_f32_e32 v59, v59, v70
	v_exp_f32_e32 v60, v60
	v_exp_f32_e32 v56, v56
	v_exp_f32_e32 v61, v61
	v_exp_f32_e32 v57, v57
	v_mul_f32_e32 v62, v62, v70
	v_exp_f32_e32 v58, v58
	v_exp_f32_e32 v59, v59
	v_mul_f32_e32 v63, v63, v70
	v_exp_f32_e32 v62, v62
	v_exp_f32_e32 v63, v63
	v_add_f32_e32 v60, 1.0, v60
	v_add_f32_e32 v56, 1.0, v56
	v_add_f32_e32 v61, 1.0, v61
	v_add_f32_e32 v57, 1.0, v57
	v_add_f32_e32 v58, 1.0, v58
	v_add_f32_e32 v59, 1.0, v59
	v_rcp_f32_e32 v60, v60
	v_rcp_f32_e32 v56, v56
	v_rcp_f32_e32 v57, v57
	v_add_f32_e32 v62, 1.0, v62
	v_rcp_f32_e32 v58, v58
	v_rcp_f32_e32 v59, v59
	v_add_f32_e32 v63, 1.0, v63
	v_rcp_f32_e32 v61, v61
	v_mul_f32_e32 v48, v48, v70
	v_rcp_f32_e32 v71, v71
	v_rcp_f32_e32 v62, v62
	v_rcp_f32_e32 v63, v63
	v_exp_f32_e32 v48, v48
	v_mul_f32_e32 v53, v53, v70
	v_exp_f32_e32 v53, v53
	v_mul_f32_e32 v49, v49, v70
	v_exp_f32_e32 v49, v49
	v_cvt_pk_f16_f32 v59, v58, v59
	v_cvt_pk_f16_f32 v58, v56, v57
	v_cvt_pk_f16_f32 v56, v60, v61
	v_lshl_add_u32 v60, v95, 11, s13
	v_cvt_pk_f16_f32 v65, v78, v71
	v_cvt_pk_f16_f32 v64, v68, v69
	v_or_b32_e32 v68, 0x100, v76
	v_cvt_pk_f16_f32 v57, v62, v63
	v_or_b32_e32 v60, v60, v147
	v_add_f32_e32 v48, 1.0, v48
	global_store_dwordx4 v68, v[64:67], s[28:29] sc1
	global_store_dwordx4 v60, v[56:59], s[28:29] sc1
	v_mul_f32_e32 v50, v50, v70
	v_exp_f32_e32 v50, v50
	v_rcp_f32_e32 v56, v48
	v_add_f32_e32 v48, 1.0, v53
	v_rcp_f32_e32 v57, v48
	v_add_f32_e32 v48, 1.0, v49
	v_mul_f32_e32 v49, v54, v70
	v_exp_f32_e32 v49, v49
	v_rcp_f32_e32 v53, v48
	v_add_u32_e32 v63, 0xa0, v158
	v_mul_f32_e32 v52, v52, v70
	v_add_f32_e32 v48, 1.0, v49
	v_rcp_f32_e32 v58, v48
	v_add_f32_e32 v48, 1.0, v50
	v_rcp_f32_e32 v54, v48
	v_mul_f32_e32 v48, v55, v70
	v_exp_f32_e32 v50, v48
	v_mul_f32_e32 v48, v51, v70
	v_exp_f32_e32 v51, v48
	s_waitcnt vmcnt(2)
	v_mov_b32_e32 v48, v73
	v_mov_b32_e32 v49, v74
	v_mov_b32_e32 v73, v75
	v_pk_add_f32 v[48:49], v[48:49], v[72:73]
	v_add_f32_e32 v50, 1.0, v50
	v_add_f32_e32 v48, v48, v49
	ds_bpermute_b32 v49, v160, v48
	v_rcp_f32_e32 v59, v50
	v_add_f32_e32 v50, 1.0, v51
	v_rcp_f32_e32 v55, v50
	v_exp_f32_e32 v52, v52
	s_waitcnt lgkmcnt(0)
	v_add_f32_e32 v61, v48, v49
	v_min_i32_e32 v48, 0x807f, v63
	v_ashrrev_i32_e32 v49, 31, v48
	v_lshlrev_b64 v[48:49], 6, v[48:49]
	v_lshl_add_u64 v[48:49], v[136:137], 0, v[48:49]
	global_load_dwordx4 v[48:51], v[48:49], off
	ds_bpermute_b32 v62, v159, v61
	v_cvt_pk_f16_f32 v55, v54, v55
	v_cvt_pk_f16_f32 v54, v56, v53
	v_add_f32_e32 v52, 1.0, v52
	v_rcp_f32_e32 v52, v52
	s_waitcnt lgkmcnt(0)
	v_add_f32_e32 v61, v61, v62
	v_fmamk_f32 v61, v61, 0x3a800000, v157
	v_rsq_f32_e32 v61, v61
	v_cvt_pk_f16_f32 v53, v58, v59
	v_cvt_pk_f16_f32 v52, v52, v57
	v_or_b32_e32 v57, 0x100, v60
	v_mul_f32_e32 v56, 0xbfb8aa3b, v61
	v_mul_f32_e32 v44, v44, v56
	v_mul_f32_e32 v40, v40, v56
	v_mul_f32_e32 v45, v45, v56
	v_mul_f32_e32 v41, v41, v56
	v_mul_f32_e32 v42, v42, v56
	v_mul_f32_e32 v43, v43, v56
	v_exp_f32_e32 v44, v44
	v_exp_f32_e32 v40, v40
	v_exp_f32_e32 v45, v45
	v_exp_f32_e32 v41, v41
	v_exp_f32_e32 v42, v42
	v_exp_f32_e32 v43, v43
	v_mul_f32_e32 v32, v32, v56
	v_add_f32_e32 v44, 1.0, v44
	v_add_f32_e32 v40, 1.0, v40
	v_add_f32_e32 v45, 1.0, v45
	v_add_f32_e32 v41, 1.0, v41
	v_add_f32_e32 v42, 1.0, v42
	v_add_f32_e32 v43, 1.0, v43
	v_exp_f32_e32 v32, v32
	v_mul_f32_e32 v37, v37, v56
	v_rcp_f32_e32 v44, v44
	v_rcp_f32_e32 v40, v40
	v_rcp_f32_e32 v41, v41
	v_rcp_f32_e32 v42, v42
	v_rcp_f32_e32 v43, v43
	v_rcp_f32_e32 v45, v45
	v_exp_f32_e32 v37, v37
	v_mul_f32_e32 v33, v33, v56
	v_mul_f32_e32 v46, v46, v56
	v_mul_f32_e32 v47, v47, v56
	v_exp_f32_e32 v33, v33
	v_exp_f32_e32 v46, v46
	v_exp_f32_e32 v47, v47
	v_add_f32_e32 v32, 1.0, v32
	v_cvt_pk_f16_f32 v43, v42, v43
	v_cvt_pk_f16_f32 v42, v40, v41
	v_cvt_pk_f16_f32 v40, v44, v45
	v_rcp_f32_e32 v45, v32
	v_add_f32_e32 v32, 1.0, v37
	v_rcp_f32_e32 v37, v32
	v_add_f32_e32 v32, 1.0, v33
	v_mul_f32_e32 v33, v38, v56
	v_add_f32_e32 v46, 1.0, v46
	v_add_f32_e32 v47, 1.0, v47
	v_exp_f32_e32 v33, v33
	v_mul_f32_e32 v34, v34, v56
	v_rcp_f32_e32 v46, v46
	v_rcp_f32_e32 v47, v47
	v_exp_f32_e32 v34, v34
	v_rcp_f32_e32 v38, v32
	v_add_f32_e32 v32, 1.0, v33
	v_cvt_pk_f16_f32 v41, v46, v47
	v_rcp_f32_e32 v46, v32
	v_add_f32_e32 v32, 1.0, v34
	v_add_u32_e32 v47, 0xb0, v158
	v_rcp_f32_e32 v34, v32
	v_min_i32_e32 v32, 0x807f, v47
	v_ashrrev_i32_e32 v33, 31, v32
	v_lshl_add_u32 v44, v79, 11, s13
	v_lshlrev_b64 v[32:33], 6, v[32:33]
	v_or_b32_e32 v44, v44, v147
	v_lshl_add_u64 v[32:33], v[136:137], 0, v[32:33]
	global_store_dwordx4 v57, v[52:55], s[28:29] sc1
	global_store_dwordx4 v44, v[40:43], s[28:29] sc1
	global_load_dwordx4 v[40:43], v[32:33], off
	v_mul_f32_e32 v35, v35, v56
	s_waitcnt vmcnt(3)
	v_mov_b32_e32 v32, v49
	v_mov_b32_e32 v33, v50
	v_mov_b32_e32 v49, v51
	v_pk_add_f32 v[32:33], v[32:33], v[48:49]
	v_exp_f32_e32 v35, v35
	v_add_f32_e32 v32, v32, v33
	ds_bpermute_b32 v33, v160, v32
	v_mul_f32_e32 v36, v36, v56
	v_add_f32_e32 v35, 1.0, v35
	v_rcp_f32_e32 v35, v35
	v_mul_f32_e32 v39, v39, v56
	s_waitcnt lgkmcnt(0)
	v_add_f32_e32 v32, v32, v33
	ds_bpermute_b32 v33, v159, v32
	v_cvt_pk_f16_f32 v35, v34, v35
	v_cvt_pk_f16_f32 v34, v45, v38
	v_exp_f32_e32 v36, v36
	v_exp_f32_e32 v39, v39
	s_waitcnt lgkmcnt(0)
	v_add_f32_e32 v32, v32, v33
	v_fmamk_f32 v32, v32, 0x3a800000, v157
	v_rsq_f32_e32 v32, v32
	v_add_f32_e32 v36, 1.0, v36
	v_add_f32_e32 v39, 1.0, v39
	v_rcp_f32_e32 v36, v36
	v_mul_f32_e32 v38, 0xbfb8aa3b, v32
	v_mul_f32_e32 v28, v28, v38
	v_mul_f32_e32 v24, v24, v38
	v_mul_f32_e32 v29, v29, v38
	v_mul_f32_e32 v25, v25, v38
	v_mul_f32_e32 v26, v26, v38
	v_mul_f32_e32 v27, v27, v38
	v_exp_f32_e32 v28, v28
	v_exp_f32_e32 v24, v24
	v_exp_f32_e32 v29, v29
	v_exp_f32_e32 v25, v25
	v_mul_f32_e32 v30, v30, v38
	v_exp_f32_e32 v26, v26
	v_exp_f32_e32 v27, v27
	v_mul_f32_e32 v31, v31, v38
	v_exp_f32_e32 v30, v30
	v_exp_f32_e32 v31, v31
	v_add_f32_e32 v28, 1.0, v28
	v_add_f32_e32 v24, 1.0, v24
	v_add_f32_e32 v29, 1.0, v29
	v_add_f32_e32 v25, 1.0, v25
	v_add_f32_e32 v26, 1.0, v26
	v_add_f32_e32 v27, 1.0, v27
	v_rcp_f32_e32 v28, v28
	v_rcp_f32_e32 v24, v24
	v_rcp_f32_e32 v25, v25
	v_add_f32_e32 v30, 1.0, v30
	v_rcp_f32_e32 v26, v26
	v_rcp_f32_e32 v27, v27
	v_add_f32_e32 v31, 1.0, v31
	v_rcp_f32_e32 v29, v29
	v_mul_f32_e32 v16, v16, v38
	v_rcp_f32_e32 v39, v39
	v_rcp_f32_e32 v30, v30
	v_rcp_f32_e32 v31, v31
	v_exp_f32_e32 v16, v16
	v_mul_f32_e32 v21, v21, v38
	v_exp_f32_e32 v21, v21
	v_mul_f32_e32 v17, v17, v38
	v_exp_f32_e32 v17, v17
	v_cvt_pk_f16_f32 v27, v26, v27
	v_cvt_pk_f16_f32 v26, v24, v25
	v_cvt_pk_f16_f32 v24, v28, v29
	v_lshl_add_u32 v28, v63, 11, s13
	v_cvt_pk_f16_f32 v33, v46, v39
	v_cvt_pk_f16_f32 v32, v36, v37
	v_or_b32_e32 v36, 0x100, v44
	v_cvt_pk_f16_f32 v25, v30, v31
	v_or_b32_e32 v28, v28, v147
	v_add_f32_e32 v16, 1.0, v16
	global_store_dwordx4 v36, v[32:35], s[28:29] sc1
	global_store_dwordx4 v28, v[24:27], s[28:29] sc1
	v_mul_f32_e32 v18, v18, v38
	v_exp_f32_e32 v18, v18
	v_rcp_f32_e32 v24, v16
	v_add_f32_e32 v16, 1.0, v21
	v_rcp_f32_e32 v21, v16
	v_add_f32_e32 v16, 1.0, v17
	v_mul_f32_e32 v17, v22, v38
	v_exp_f32_e32 v17, v17
	v_rcp_f32_e32 v22, v16
	v_mul_f32_e32 v19, v19, v38
	v_exp_f32_e32 v19, v19
	v_add_f32_e32 v16, 1.0, v17
	v_rcp_f32_e32 v25, v16
	v_add_f32_e32 v16, 1.0, v18
	v_rcp_f32_e32 v18, v16
	s_waitcnt vmcnt(2)
	v_mov_b32_e32 v16, v41
	v_mov_b32_e32 v17, v42
	v_mov_b32_e32 v41, v43
	v_pk_add_f32 v[16:17], v[16:17], v[40:41]
	v_add_f32_e32 v19, 1.0, v19
	v_add_f32_e32 v16, v16, v17
	ds_bpermute_b32 v17, v160, v16
	v_rcp_f32_e32 v19, v19
	v_mul_f32_e32 v20, v20, v38
	v_mul_f32_e32 v23, v23, v38
	v_exp_f32_e32 v20, v20
	s_waitcnt lgkmcnt(0)
	v_add_f32_e32 v16, v16, v17
	ds_bpermute_b32 v17, v159, v16
	v_cvt_pk_f16_f32 v19, v18, v19
	v_cvt_pk_f16_f32 v18, v24, v22
	v_exp_f32_e32 v23, v23
	v_add_f32_e32 v20, 1.0, v20
	s_waitcnt lgkmcnt(0)
	v_add_f32_e32 v16, v16, v17
	v_fmamk_f32 v16, v16, 0x3a800000, v157
	v_rsq_f32_e32 v16, v16
	v_add_f32_e32 v23, 1.0, v23
	v_rcp_f32_e32 v20, v20
	v_rcp_f32_e32 v23, v23
	v_mul_f32_e32 v22, 0xbfb8aa3b, v16
	v_mul_f32_e32 v12, v12, v22
	v_mul_f32_e32 v8, v8, v22
	v_mul_f32_e32 v13, v13, v22
	v_mul_f32_e32 v9, v9, v22
	v_mul_f32_e32 v10, v10, v22
	v_mul_f32_e32 v11, v11, v22
	v_exp_f32_e32 v12, v12
	v_exp_f32_e32 v8, v8
	v_exp_f32_e32 v13, v13
	v_exp_f32_e32 v9, v9
	v_exp_f32_e32 v10, v10
	v_exp_f32_e32 v11, v11
	v_mul_f32_e32 v14, v14, v22
	v_mul_f32_e32 v15, v15, v22
	v_mul_f32_e32 v4, v4, v22
	v_mul_f32_e32 v0, v0, v22
	v_mul_f32_e32 v5, v5, v22
	v_mul_f32_e32 v1, v1, v22
	v_mul_f32_e32 v6, v6, v22
	v_mul_f32_e32 v2, v2, v22
	v_mul_f32_e32 v3, v3, v22
	v_mul_f32_e32 v7, v7, v22
	v_exp_f32_e32 v14, v14
	v_exp_f32_e32 v15, v15
	v_exp_f32_e32 v4, v4
	v_exp_f32_e32 v0, v0
	v_exp_f32_e32 v5, v5
	v_exp_f32_e32 v1, v1
	v_exp_f32_e32 v6, v6
	v_exp_f32_e32 v2, v2
	v_exp_f32_e32 v3, v3
	v_exp_f32_e32 v7, v7
	v_add_f32_e32 v12, 1.0, v12
	v_add_f32_e32 v8, 1.0, v8
	v_add_f32_e32 v13, 1.0, v13
	v_add_f32_e32 v9, 1.0, v9
	v_add_f32_e32 v10, 1.0, v10
	v_add_f32_e32 v11, 1.0, v11
	v_rcp_f32_e32 v12, v12
	v_rcp_f32_e32 v8, v8
	v_rcp_f32_e32 v9, v9
	v_rcp_f32_e32 v10, v10
	v_rcp_f32_e32 v11, v11
	v_rcp_f32_e32 v13, v13
	v_add_f32_e32 v14, 1.0, v14
	v_add_f32_e32 v15, 1.0, v15
	v_add_f32_e32 v4, 1.0, v4
	v_add_f32_e32 v0, 1.0, v0
	v_add_f32_e32 v5, 1.0, v5
	v_add_f32_e32 v1, 1.0, v1
	v_add_f32_e32 v6, 1.0, v6
	v_add_f32_e32 v2, 1.0, v2
	v_add_f32_e32 v3, 1.0, v3
	v_add_f32_e32 v7, 1.0, v7
	v_rcp_f32_e32 v14, v14
	v_rcp_f32_e32 v15, v15
	v_rcp_f32_e32 v4, v4
	v_rcp_f32_e32 v0, v0
	v_rcp_f32_e32 v1, v1
	v_rcp_f32_e32 v6, v6
	v_rcp_f32_e32 v2, v2
	v_rcp_f32_e32 v3, v3
	v_rcp_f32_e32 v7, v7
	v_rcp_f32_e32 v5, v5
	v_cvt_pk_f16_f32 v11, v10, v11
	v_cvt_pk_f16_f32 v10, v8, v9
	v_cvt_pk_f16_f32 v8, v12, v13
	v_lshl_add_u32 v12, v47, 11, s13
	v_or_b32_e32 v12, v12, v147
	v_cvt_pk_f16_f32 v17, v25, v23
	v_cvt_pk_f16_f32 v16, v20, v21
	v_or_b32_e32 v20, 0x100, v28
	v_cvt_pk_f16_f32 v9, v14, v15
	v_cvt_pk_f16_f32 v3, v2, v3
	v_cvt_pk_f16_f32 v2, v0, v1
	v_cvt_pk_f16_f32 v1, v6, v7
	v_cvt_pk_f16_f32 v0, v4, v5
	v_or_b32_e32 v4, 0x100, v12
	global_store_dwordx4 v20, v[16:19], s[28:29] sc1
	global_store_dwordx4 v12, v[8:11], s[28:29] sc1
	global_store_dwordx4 v4, v[0:3], s[28:29] sc1
	s_cbranch_vccnz .LBB0_1421
	s_and_b64 vcc, exec, s[0:1]
	s_cbranch_vccnz .LBB0_1420
	s_barrier
	s_branch .LBB0_1420

.LBB0_1536:
	s_or_b64 exec, exec, s[50:51]
	s_waitcnt vmcnt(0) lgkmcnt(0)
	s_barrier
	v_lshl_add_u32 v136, v155, 2, s79
	v_lshl_add_u32 v142, v154, 3, s70
	v_readlane_b32 s88, v255, 0
	v_readlane_b32 s89, v255, 1
	v_readlane_b32 s90, v255, 2
	v_readlane_b32 s91, v255, 3
	v_readlane_b32 s92, v255, 4
	v_readlane_b32 s93, v255, 5
	v_readlane_b32 s94, v255, 6
	v_readlane_b32 s95, v255, 7
	ds_read_b32 v190, v136
	ds_read_b32 v192, v136 offset:64
	ds_read_b32 v194, v136 offset:128
	ds_read_b32 v196, v136 offset:192
	ds_read_b32 v198, v136 offset:512
	ds_read_b32 v200, v136 offset:576
	ds_read_b32 v202, v136 offset:640
	ds_read_b32 v204, v136 offset:704
	v_lshl_add_u32 v154, s30, 8, v142
	s_waitcnt lgkmcnt(7)
	s_and_saveexec_b64 s[22:23], s[6:7]
	v_pk_mul_f32 v[126:127], v[126:127], v[190:191] op_sel_hi:[1,0]
	v_pk_mul_f32 v[124:125], v[124:125], v[190:191] op_sel_hi:[1,0]
	v_pk_mul_f32 v[118:119], v[118:119], v[190:191] op_sel_hi:[1,0]
	v_pk_mul_f32 v[116:117], v[116:117], v[190:191] op_sel_hi:[1,0]
	v_pk_mul_f32 v[122:123], v[122:123], v[190:191] op_sel_hi:[1,0]
	v_pk_mul_f32 v[120:121], v[120:121], v[190:191] op_sel_hi:[1,0]
	v_pk_mul_f32 v[114:115], v[114:115], v[190:191] op_sel_hi:[1,0]
	v_pk_mul_f32 v[112:113], v[112:113], v[190:191] op_sel_hi:[1,0]
	v_lshlrev_b32_e32 v143, 12, v153
	v_lshl_add_u32 v152, v154, 2, v143
	v_pk_mul_f32 v[124:125], v[174:175], v[124:125]
	v_pk_mul_f32 v[126:127], v[176:177], v[126:127]
	v_pk_mul_f32 v[116:117], v[178:179], v[116:117]
	v_pk_mul_f32 v[118:119], v[180:181], v[118:119]
	v_pk_mul_f32 v[120:121], v[182:183], v[120:121]
	v_pk_mul_f32 v[122:123], v[184:185], v[122:123]
	v_pk_mul_f32 v[112:113], v[186:187], v[112:113]
	v_pk_mul_f32 v[114:115], v[188:189], v[114:115]
	global_store_dwordx4 v152, v[124:127], s[94:95] sc1
	global_store_dwordx4 v152, v[116:119], s[94:95] offset:16 sc1
	global_store_dwordx4 v152, v[120:123], s[94:95] offset:512 sc1
	global_store_dwordx4 v152, v[112:115], s[94:95] offset:528 sc1
	s_mov_b64 exec, s[22:23]
	s_waitcnt lgkmcnt(6)
	s_and_saveexec_b64 s[22:23], s[8:9]
	v_pk_mul_f32 v[110:111], v[110:111], v[192:193] op_sel_hi:[1,0]
	v_pk_mul_f32 v[108:109], v[108:109], v[192:193] op_sel_hi:[1,0]
	v_pk_mul_f32 v[102:103], v[102:103], v[192:193] op_sel_hi:[1,0]
	v_pk_mul_f32 v[100:101], v[100:101], v[192:193] op_sel_hi:[1,0]
	v_pk_mul_f32 v[106:107], v[106:107], v[192:193] op_sel_hi:[1,0]
	v_pk_mul_f32 v[104:105], v[104:105], v[192:193] op_sel_hi:[1,0]
	v_pk_mul_f32 v[98:99], v[98:99], v[192:193] op_sel_hi:[1,0]
	v_pk_mul_f32 v[96:97], v[96:97], v[192:193] op_sel_hi:[1,0]
	v_lshlrev_b32_e32 v143, 12, v156
	v_lshl_add_u32 v152, v154, 2, v143
	v_pk_mul_f32 v[108:109], v[174:175], v[108:109]
	v_pk_mul_f32 v[110:111], v[176:177], v[110:111]
	v_pk_mul_f32 v[100:101], v[178:179], v[100:101]
	v_pk_mul_f32 v[102:103], v[180:181], v[102:103]
	v_pk_mul_f32 v[104:105], v[182:183], v[104:105]
	v_pk_mul_f32 v[106:107], v[184:185], v[106:107]
	v_pk_mul_f32 v[96:97], v[186:187], v[96:97]
	v_pk_mul_f32 v[98:99], v[188:189], v[98:99]
	global_store_dwordx4 v152, v[108:111], s[94:95] sc1
	global_store_dwordx4 v152, v[100:103], s[94:95] offset:16 sc1
	global_store_dwordx4 v152, v[104:107], s[94:95] offset:512 sc1
	global_store_dwordx4 v152, v[96:99], s[94:95] offset:528 sc1
	s_mov_b64 exec, s[22:23]
	s_waitcnt lgkmcnt(5)
	s_and_saveexec_b64 s[22:23], s[10:11]
	v_pk_mul_f32 v[94:95], v[94:95], v[194:195] op_sel_hi:[1,0]
	v_pk_mul_f32 v[92:93], v[92:93], v[194:195] op_sel_hi:[1,0]
	v_pk_mul_f32 v[86:87], v[86:87], v[194:195] op_sel_hi:[1,0]
	v_pk_mul_f32 v[84:85], v[84:85], v[194:195] op_sel_hi:[1,0]
	v_pk_mul_f32 v[90:91], v[90:91], v[194:195] op_sel_hi:[1,0]
	v_pk_mul_f32 v[88:89], v[88:89], v[194:195] op_sel_hi:[1,0]
	v_pk_mul_f32 v[82:83], v[82:83], v[194:195] op_sel_hi:[1,0]
	v_pk_mul_f32 v[80:81], v[80:81], v[194:195] op_sel_hi:[1,0]
	v_lshlrev_b32_e32 v143, 12, v157
	v_lshl_add_u32 v152, v154, 2, v143
	v_pk_mul_f32 v[92:93], v[174:175], v[92:93]
	v_pk_mul_f32 v[94:95], v[176:177], v[94:95]
	v_pk_mul_f32 v[84:85], v[178:179], v[84:85]
	v_pk_mul_f32 v[86:87], v[180:181], v[86:87]
	v_pk_mul_f32 v[88:89], v[182:183], v[88:89]
	v_pk_mul_f32 v[90:91], v[184:185], v[90:91]
	v_pk_mul_f32 v[80:81], v[186:187], v[80:81]
	v_pk_mul_f32 v[82:83], v[188:189], v[82:83]
	global_store_dwordx4 v152, v[92:95], s[94:95] sc1
	global_store_dwordx4 v152, v[84:87], s[94:95] offset:16 sc1
	global_store_dwordx4 v152, v[88:91], s[94:95] offset:512 sc1
	global_store_dwordx4 v152, v[80:83], s[94:95] offset:528 sc1
	s_mov_b64 exec, s[22:23]
	s_waitcnt lgkmcnt(4)
	s_and_saveexec_b64 s[22:23], s[12:13]
	v_pk_mul_f32 v[78:79], v[78:79], v[196:197] op_sel_hi:[1,0]
	v_pk_mul_f32 v[76:77], v[76:77], v[196:197] op_sel_hi:[1,0]
	v_pk_mul_f32 v[70:71], v[70:71], v[196:197] op_sel_hi:[1,0]
	v_pk_mul_f32 v[68:69], v[68:69], v[196:197] op_sel_hi:[1,0]
	v_pk_mul_f32 v[74:75], v[74:75], v[196:197] op_sel_hi:[1,0]
	v_pk_mul_f32 v[72:73], v[72:73], v[196:197] op_sel_hi:[1,0]
	v_pk_mul_f32 v[66:67], v[66:67], v[196:197] op_sel_hi:[1,0]
	v_pk_mul_f32 v[64:65], v[64:65], v[196:197] op_sel_hi:[1,0]
	v_lshlrev_b32_e32 v143, 12, v158
	v_lshl_add_u32 v152, v154, 2, v143
	v_pk_mul_f32 v[76:77], v[174:175], v[76:77]
	v_pk_mul_f32 v[78:79], v[176:177], v[78:79]
	v_pk_mul_f32 v[68:69], v[178:179], v[68:69]
	v_pk_mul_f32 v[70:71], v[180:181], v[70:71]
	v_pk_mul_f32 v[72:73], v[182:183], v[72:73]
	v_pk_mul_f32 v[74:75], v[184:185], v[74:75]
	v_pk_mul_f32 v[64:65], v[186:187], v[64:65]
	v_pk_mul_f32 v[66:67], v[188:189], v[66:67]
	global_store_dwordx4 v152, v[76:79], s[94:95] sc1
	global_store_dwordx4 v152, v[68:71], s[94:95] offset:16 sc1
	global_store_dwordx4 v152, v[72:75], s[94:95] offset:512 sc1
	global_store_dwordx4 v152, v[64:67], s[94:95] offset:528 sc1
	s_mov_b64 exec, s[22:23]
	s_waitcnt lgkmcnt(3)
	s_and_saveexec_b64 s[22:23], s[14:15]
	v_pk_mul_f32 v[62:63], v[62:63], v[198:199] op_sel_hi:[1,0]
	v_pk_mul_f32 v[60:61], v[60:61], v[198:199] op_sel_hi:[1,0]
	v_pk_mul_f32 v[54:55], v[54:55], v[198:199] op_sel_hi:[1,0]
	v_pk_mul_f32 v[52:53], v[52:53], v[198:199] op_sel_hi:[1,0]
	v_pk_mul_f32 v[58:59], v[58:59], v[198:199] op_sel_hi:[1,0]
	v_pk_mul_f32 v[56:57], v[56:57], v[198:199] op_sel_hi:[1,0]
	v_pk_mul_f32 v[50:51], v[50:51], v[198:199] op_sel_hi:[1,0]
	v_pk_mul_f32 v[48:49], v[48:49], v[198:199] op_sel_hi:[1,0]
	v_lshlrev_b32_e32 v143, 12, v159
	v_lshl_add_u32 v152, v154, 2, v143
	v_pk_mul_f32 v[60:61], v[174:175], v[60:61]
	v_pk_mul_f32 v[62:63], v[176:177], v[62:63]
	v_pk_mul_f32 v[52:53], v[178:179], v[52:53]
	v_pk_mul_f32 v[54:55], v[180:181], v[54:55]
	v_pk_mul_f32 v[56:57], v[182:183], v[56:57]
	v_pk_mul_f32 v[58:59], v[184:185], v[58:59]
	v_pk_mul_f32 v[48:49], v[186:187], v[48:49]
	v_pk_mul_f32 v[50:51], v[188:189], v[50:51]
	global_store_dwordx4 v152, v[60:63], s[94:95] sc1
	global_store_dwordx4 v152, v[52:55], s[94:95] offset:16 sc1
	global_store_dwordx4 v152, v[56:59], s[94:95] offset:512 sc1
	global_store_dwordx4 v152, v[48:51], s[94:95] offset:528 sc1
	s_mov_b64 exec, s[22:23]
	s_waitcnt lgkmcnt(2)
	s_and_saveexec_b64 s[22:23], s[16:17]
	v_pk_mul_f32 v[46:47], v[46:47], v[200:201] op_sel_hi:[1,0]
	v_pk_mul_f32 v[44:45], v[44:45], v[200:201] op_sel_hi:[1,0]
	v_pk_mul_f32 v[38:39], v[38:39], v[200:201] op_sel_hi:[1,0]
	v_pk_mul_f32 v[36:37], v[36:37], v[200:201] op_sel_hi:[1,0]
	v_pk_mul_f32 v[42:43], v[42:43], v[200:201] op_sel_hi:[1,0]
	v_pk_mul_f32 v[40:41], v[40:41], v[200:201] op_sel_hi:[1,0]
	v_pk_mul_f32 v[34:35], v[34:35], v[200:201] op_sel_hi:[1,0]
	v_pk_mul_f32 v[32:33], v[32:33], v[200:201] op_sel_hi:[1,0]
	v_lshlrev_b32_e32 v143, 12, v162
	v_lshl_add_u32 v152, v154, 2, v143
	v_pk_mul_f32 v[44:45], v[174:175], v[44:45]
	v_pk_mul_f32 v[46:47], v[176:177], v[46:47]
	v_pk_mul_f32 v[36:37], v[178:179], v[36:37]
	v_pk_mul_f32 v[38:39], v[180:181], v[38:39]
	v_pk_mul_f32 v[40:41], v[182:183], v[40:41]
	v_pk_mul_f32 v[42:43], v[184:185], v[42:43]
	v_pk_mul_f32 v[32:33], v[186:187], v[32:33]
	v_pk_mul_f32 v[34:35], v[188:189], v[34:35]
	global_store_dwordx4 v152, v[44:47], s[94:95] sc1
	global_store_dwordx4 v152, v[36:39], s[94:95] offset:16 sc1
	global_store_dwordx4 v152, v[40:43], s[94:95] offset:512 sc1
	global_store_dwordx4 v152, v[32:35], s[94:95] offset:528 sc1
	s_mov_b64 exec, s[22:23]
	s_waitcnt lgkmcnt(1)
	s_and_saveexec_b64 s[22:23], s[18:19]
	v_pk_mul_f32 v[30:31], v[30:31], v[202:203] op_sel_hi:[1,0]
	v_pk_mul_f32 v[28:29], v[28:29], v[202:203] op_sel_hi:[1,0]
	v_pk_mul_f32 v[22:23], v[22:23], v[202:203] op_sel_hi:[1,0]
	v_pk_mul_f32 v[20:21], v[20:21], v[202:203] op_sel_hi:[1,0]
	v_pk_mul_f32 v[26:27], v[26:27], v[202:203] op_sel_hi:[1,0]
	v_pk_mul_f32 v[24:25], v[24:25], v[202:203] op_sel_hi:[1,0]
	v_pk_mul_f32 v[18:19], v[18:19], v[202:203] op_sel_hi:[1,0]
	v_pk_mul_f32 v[16:17], v[16:17], v[202:203] op_sel_hi:[1,0]
	v_lshlrev_b32_e32 v143, 12, v163
	v_lshl_add_u32 v152, v154, 2, v143
	v_pk_mul_f32 v[28:29], v[174:175], v[28:29]
	v_pk_mul_f32 v[30:31], v[176:177], v[30:31]
	v_pk_mul_f32 v[20:21], v[178:179], v[20:21]
	v_pk_mul_f32 v[22:23], v[180:181], v[22:23]
	v_pk_mul_f32 v[24:25], v[182:183], v[24:25]
	v_pk_mul_f32 v[26:27], v[184:185], v[26:27]
	v_pk_mul_f32 v[16:17], v[186:187], v[16:17]
	v_pk_mul_f32 v[18:19], v[188:189], v[18:19]
	global_store_dwordx4 v152, v[28:31], s[94:95] sc1
	global_store_dwordx4 v152, v[20:23], s[94:95] offset:16 sc1
	global_store_dwordx4 v152, v[24:27], s[94:95] offset:512 sc1
	global_store_dwordx4 v152, v[16:19], s[94:95] offset:528 sc1
	s_mov_b64 exec, s[22:23]
	s_waitcnt lgkmcnt(0)
	s_and_saveexec_b64 s[22:23], s[20:21]
	v_pk_mul_f32 v[14:15], v[14:15], v[204:205] op_sel_hi:[1,0]
	v_pk_mul_f32 v[12:13], v[12:13], v[204:205] op_sel_hi:[1,0]
	v_pk_mul_f32 v[6:7], v[6:7], v[204:205] op_sel_hi:[1,0]
	v_pk_mul_f32 v[4:5], v[4:5], v[204:205] op_sel_hi:[1,0]
	v_pk_mul_f32 v[10:11], v[10:11], v[204:205] op_sel_hi:[1,0]
	v_pk_mul_f32 v[8:9], v[8:9], v[204:205] op_sel_hi:[1,0]
	v_pk_mul_f32 v[2:3], v[2:3], v[204:205] op_sel_hi:[1,0]
	v_pk_mul_f32 v[0:1], v[0:1], v[204:205] op_sel_hi:[1,0]
	v_lshlrev_b32_e32 v143, 12, v164
	v_lshl_add_u32 v152, v154, 2, v143
	v_pk_mul_f32 v[12:13], v[174:175], v[12:13]
	v_pk_mul_f32 v[14:15], v[176:177], v[14:15]
	v_pk_mul_f32 v[4:5], v[178:179], v[4:5]
	v_pk_mul_f32 v[6:7], v[180:181], v[6:7]
	v_pk_mul_f32 v[8:9], v[182:183], v[8:9]
	v_pk_mul_f32 v[10:11], v[184:185], v[10:11]
	v_pk_mul_f32 v[0:1], v[186:187], v[0:1]
	v_pk_mul_f32 v[2:3], v[188:189], v[2:3]
	global_store_dwordx4 v152, v[12:15], s[94:95] sc1
	global_store_dwordx4 v152, v[4:7], s[94:95] offset:16 sc1
	global_store_dwordx4 v152, v[8:11], s[94:95] offset:512 sc1
	global_store_dwordx4 v152, v[0:3], s[94:95] offset:528 sc1
	s_mov_b64 exec, s[22:23]
	s_waitcnt lgkmcnt(0)
	s_barrier
	s_andn2_b64 vcc, exec, s[4:5]
	s_mov_b64 s[4:5], -1
	s_cbranch_vccnz .LBB0_1462
	s_and_b64 vcc, exec, s[0:1]
	s_cbranch_vccnz .LBB0_1461
	s_barrier
	s_branch .LBB0_1461
